# hand-written dense attention loop: scale folded into q, no running max, 1 barrier per tile
# speedup vs baseline: 1.0378x; 1.0378x over previous
;     ...
;   const bf16* Qw = Qb + (long)(wid * QBLK + r32) * ldq + hi * 8;
; #pragma unroll
;   for (int d0 = 0; d0 < 8; ++d0) qr[d0] = *reinterpret_cast<const bf16x8*>(Qw + d0 * 16);
;   if constexpr (QPREP) {
;     float x[8][8]; float ssq = 0.f;
; #pragma unroll
;     for (int d0 = 0; d0 < 8; ++d0)
; #pragma unroll
;       for (int j = 0; j < 8; ++j) { x[d0][j] = __builtin_bit_cast(float, (unsigned)(unsigned short)qr[d0][j] << 16); ssq += x[d0][j] * x[d0][j]; }
;     { auto rr = __builtin_amdgcn_permlane32_swap(__float_as_uint(ssq), __float_as_uint(ssq), false, false); ssq = __uint_as_float(rr[0]) + __uint_as_float(rr[1]); }
;     const float rstd = 1.0f / sqrtf(ssq * (1.0f / 128.0f) + 1e-6f);
;     const int sq = qs0 + wid * QBLK + r32;
; #pragma unroll
;     for (int aa = 0; aa < 2; ++aa) { const float pos = (float)(aa == 0 ? (sq >> 6) : (sq & 63));
; #pragma unroll
;       for (int dd = 0; dd < 2; ++dd) { const int d0 = aa * 4 + dd;
; #pragma unroll
;         for (int j = 0; j < 8; ++j) { const int i = 16 * dd + 8 * hi + j; const int e1 = aa * 64 + i;
;           const float rev = pos * exp2f(-(float)i * 0.41524101186092029f) * 0.15915494309189535f;
;           const float sn = __builtin_amdgcn_sinf(rev), cs = __builtin_amdgcn_cosf(rev);
; __global__ void __launch_bounds__(NWAVES * 64, 2) mk_fwd(Args args) {
;     ...
;                 const int u = u0 + k * ustep;
;                 if (k < nA && u < uend) {
;                     const int combo = u >> 8, b = combo >> 1, kvh = combo & 1, hq = kvh * 4 + ((u >> 6) & 3), qb = u & 63;
;                     const size_t rowq = (size_t)b * SEQ + (size_t)qb * 256;
;                     att::attn_unit<0, true>(P + rowq * INW + O_QA + hq * 128, INW, P + (size_t)b * SEQ * INW + O_KA + kvh * 128, P + (size_t)b * SEQ * INW + O_VA + kvh * 128, INW,
.LBB0_484:
	s_mul_i32 s0, s19, s51
	s_add_i32 s0, s35, s0
	s_cmp_lt_i32 s51, s60
	s_cselect_b64 s[2:3], -1, 0
	s_cmp_lt_i32 s0, s31
	s_cselect_b64 s[4:5], -1, 0
	s_and_b64 s[2:3], s[2:3], s[4:5]
	s_andn2_b64 vcc, exec, s[2:3]
	s_cbranch_vccnz .LBB0_478
	s_ashr_i32 s2, s0, 9
	s_ashr_i32 s3, s2, 31
	s_lshl_b64 s[20:21], s[2:3], 14
	s_lshl_b32 s3, s0, 8
	s_and_b32 s39, s3, 0x3f00
	s_or_b32 s20, s20, s39
	s_bfe_u32 s1, s0, 0x10008
	s_mul_i32 s3, s21, 0x5400
	s_mul_hi_u32 s5, s20, 0x5400
	s_lshl_b32 s4, s1, 8
	s_add_i32 s5, s5, s3
	s_mul_i32 s3, s20, 0x5400
	s_add_u32 s3, s64, s3
	s_addc_u32 s5, s65, s5
	s_lshl_b32 s0, s0, 1
	s_lshl_b32 s1, s1, 9
	s_and_b32 s0, s0, 0x180
	s_or_b32 s14, s1, s0
	s_lshl_b32 s0, s14, 1
	s_add_u32 s0, s3, s0
	s_addc_u32 s1, s5, 0
	s_mul_i32 s28, s2, 0x15000000
	s_mul_hi_i32 s5, s2, 0x15000000
	s_add_u32 s2, s64, s28
	s_addc_u32 s3, s65, s5
	v_mov_b32_e32 v230, v218
	s_add_u32 s2, s2, s4
	s_addc_u32 s3, s3, 0
	v_readfirstlane_b32 s29, v230
	s_ashr_i32 s42, s29, 1
	v_mov_b32_e32 v0, s42
	v_bfe_u32 v229, v230, 5, 1
	v_bfi_b32 v2, s72, v0, v230
	v_mov_b64_e32 v[0:1], s[0:1]
	s_movk_i32 s0, 0x5400
	v_mad_i64_i32 v[0:1], s[0:1], v2, s0, v[0:1]
	v_lshlrev_b32_e32 v164, 4, v229
	v_and_b32_e32 v228, 31, v230
	v_lshl_add_u64 v[0:1], v[0:1], 0, v[164:165]
	s_and_b32 s38, s42, 0xffffffe0
	global_load_dwordx4 v[56:59], v[0:1], off
	global_load_dwordx4 v[72:75], v[0:1], off offset:32
	global_load_dwordx4 v[60:63], v[0:1], off offset:64
	global_load_dwordx4 v[76:79], v[0:1], off offset:96
	global_load_dwordx4 v[80:83], v[0:1], off offset:128
	global_load_dwordx4 v[88:91], v[0:1], off offset:160
	global_load_dwordx4 v[84:87], v[0:1], off offset:192
	global_load_dwordx4 v[92:95], v[0:1], off offset:224
	v_or_b32_e32 v0, s39, v228
	v_lshlrev_b32_e32 v20, 3, v229
	v_add_u32_e32 v0, s38, v0
	v_ashrrev_i32_e32 v1, 6, v0
	v_and_b32_e32 v40, 63, v0
	v_cvt_f32_ubyte0_e32 v0, v20
	v_or_b32_e32 v4, 1, v20
	v_mul_f32_e32 v2, 0xbed49a78, v0
	v_cvt_f32_ubyte0_e32 v4, v4
	v_cmp_gt_f32_e32 vcc, s74, v2
	v_mul_f32_e32 v5, 0xbed49a78, v4
	v_cvt_f32_i32_e32 v41, v1
	v_cndmask_b32_e32 v2, 0, v225, vcc
	v_cndmask_b32_e32 v1, 0, v226, vcc
	v_cmp_gt_f32_e32 vcc, s74, v5
	v_or_b32_e32 v16, 16, v20
	v_cvt_f32_ubyte0_e32 v16, v16
	v_cndmask_b32_e32 v5, 0, v225, vcc
	v_fmac_f32_e32 v5, 0xbed49a78, v4
	v_exp_f32_e32 v17, v5
	v_cndmask_b32_e32 v18, 0, v226, vcc
	v_or_b32_e32 v21, 17, v20
	v_cvt_f32_ubyte0_e32 v21, v21
	v_ldexp_f32 v118, v17, v18
	v_or_b32_e32 v18, 2, v20
	v_cvt_f32_ubyte0_e32 v18, v18
	v_mul_f32_e32 v19, 0xbed49a78, v18
	v_cmp_gt_f32_e32 vcc, s74, v19
	v_mul_f32_e32 v17, v118, v41
	v_mul_f32_e32 v17, 0.15915494, v17
	v_cndmask_b32_e32 v19, 0, v225, vcc
	v_fmac_f32_e32 v19, 0xbed49a78, v18
	v_exp_f32_e32 v18, v19
	v_sin_f32_e32 v99, v17
	v_cos_f32_e32 v98, v17
	v_cndmask_b32_e32 v17, 0, v226, vcc
	v_ldexp_f32 v119, v18, v17
	v_or_b32_e32 v18, 3, v20
	v_cvt_f32_ubyte0_e32 v18, v18
	v_mul_f32_e32 v19, 0xbed49a78, v18
	v_cmp_gt_f32_e32 vcc, s74, v19
	v_mul_f32_e32 v17, v119, v41
	v_mul_f32_e32 v17, 0.15915494, v17
	v_cndmask_b32_e32 v19, 0, v225, vcc
	v_fmac_f32_e32 v19, 0xbed49a78, v18
	v_exp_f32_e32 v18, v19
	v_sin_f32_e32 v100, v17
	v_cos_f32_e32 v101, v17
	v_cndmask_b32_e32 v17, 0, v226, vcc
	v_ldexp_f32 v120, v18, v17
	v_or_b32_e32 v18, 4, v20
	v_cvt_f32_ubyte0_e32 v18, v18
	v_mul_f32_e32 v19, 0xbed49a78, v18
	v_cmp_gt_f32_e32 vcc, s74, v19
	v_mul_f32_e32 v17, v120, v41
	v_mul_f32_e32 v17, 0.15915494, v17
	v_cndmask_b32_e32 v19, 0, v225, vcc
	v_fmac_f32_e32 v19, 0xbed49a78, v18
	v_exp_f32_e32 v18, v19
	v_sin_f32_e32 v103, v17
	v_cos_f32_e32 v102, v17
	v_cndmask_b32_e32 v17, 0, v226, vcc
	v_ldexp_f32 v121, v18, v17
	v_or_b32_e32 v18, 5, v20
	v_cvt_f32_ubyte0_e32 v18, v18
	v_mul_f32_e32 v19, 0xbed49a78, v18
	v_cmp_gt_f32_e32 vcc, s74, v19
	v_mul_f32_e32 v17, v121, v41
	v_mul_f32_e32 v17, 0.15915494, v17
	v_cndmask_b32_e32 v19, 0, v225, vcc
	v_fmac_f32_e32 v19, 0xbed49a78, v18
	v_exp_f32_e32 v18, v19
	v_sin_f32_e32 v104, v17
	v_cos_f32_e32 v105, v17
	v_cndmask_b32_e32 v17, 0, v226, vcc
	v_ldexp_f32 v124, v18, v17
	v_or_b32_e32 v18, 6, v20
	v_cvt_f32_ubyte0_e32 v18, v18
	v_mul_f32_e32 v19, 0xbed49a78, v18
	v_cmp_gt_f32_e32 vcc, s74, v19
	v_mul_f32_e32 v17, v124, v41
	v_mul_f32_e32 v17, 0.15915494, v17
	v_cndmask_b32_e32 v19, 0, v225, vcc
	v_fmac_f32_e32 v19, 0xbed49a78, v18
	v_exp_f32_e32 v18, v19
	v_sin_f32_e32 v107, v17
	v_cos_f32_e32 v106, v17
	v_cndmask_b32_e32 v17, 0, v226, vcc
	v_ldexp_f32 v125, v18, v17
	v_or_b32_e32 v18, 7, v20
	v_cvt_f32_ubyte0_e32 v18, v18
	v_mul_f32_e32 v19, 0xbed49a78, v18
	v_cmp_gt_f32_e32 vcc, s74, v19
	v_mul_f32_e32 v17, v125, v41
	v_mul_f32_e32 v17, 0.15915494, v17
	v_cndmask_b32_e32 v19, 0, v225, vcc
	v_fmac_f32_e32 v19, 0xbed49a78, v18
	v_exp_f32_e32 v18, v19
	v_sin_f32_e32 v108, v17
	v_cos_f32_e32 v109, v17
	v_cndmask_b32_e32 v17, 0, v226, vcc
	v_ldexp_f32 v128, v18, v17
	v_mul_f32_e32 v17, v128, v41
	v_mul_f32_e32 v18, 0xbed49a78, v16
	v_mul_f32_e32 v17, 0.15915494, v17
	v_cmp_gt_f32_e32 vcc, s74, v18
	v_mul_f32_e32 v22, 0xbed49a78, v21
	v_sin_f32_e32 v113, v17
	v_cndmask_b32_e32 v18, 0, v225, vcc
	v_cos_f32_e32 v112, v17
	v_cndmask_b32_e32 v17, 0, v226, vcc
	v_cmp_gt_f32_e32 vcc, s74, v22
	v_fmac_f32_e32 v2, 0xbed49a78, v0
	v_fmac_f32_e32 v18, 0xbed49a78, v16
	v_cndmask_b32_e32 v22, 0, v225, vcc
	v_fmac_f32_e32 v22, 0xbed49a78, v21
	v_exp_f32_e32 v21, v22
	v_cndmask_b32_e32 v22, 0, v226, vcc
	v_exp_f32_e32 v0, v2
	v_exp_f32_e32 v16, v18
	v_ldexp_f32 v130, v21, v22
	v_or_b32_e32 v22, 18, v20
	v_cvt_f32_ubyte0_e32 v22, v22
	v_mul_f32_e32 v23, 0xbed49a78, v22
	v_cmp_gt_f32_e32 vcc, s74, v23
;     ...
;     const int sq = qs0 + wid * QBLK + r32;
; #pragma unroll
;     for (int aa = 0; aa < 2; ++aa) { const float pos = (float)(aa == 0 ? (sq >> 6) : (sq & 63));
; #pragma unroll
;       for (int dd = 0; dd < 2; ++dd) { const int d0 = aa * 4 + dd;
; #pragma unroll
;         for (int j = 0; j < 8; ++j) { const int i = 16 * dd + 8 * hi + j; const int e1 = aa * 64 + i;
;           const float rev = pos * exp2f(-(float)i * 0.41524101186092029f) * 0.15915494309189535f;
;           const float sn = __builtin_amdgcn_sinf(rev), cs = __builtin_amdgcn_cosf(rev);
;           const float y1 = x[d0][j] * rstd * qgain[e1], y2 = x[d0 + 2][j] * rstd * qgain[e1 + 32];
	v_mul_f32_e32 v21, v130, v41
	v_mul_f32_e32 v21, 0.15915494, v21
	v_cndmask_b32_e32 v23, 0, v225, vcc
	v_fmac_f32_e32 v23, 0xbed49a78, v22
	v_exp_f32_e32 v22, v23
	v_sin_f32_e32 v115, v21
	v_cos_f32_e32 v114, v21
	v_cndmask_b32_e32 v21, 0, v226, vcc
	v_ldexp_f32 v131, v22, v21
	v_or_b32_e32 v22, 19, v20
	v_cvt_f32_ubyte0_e32 v22, v22
	v_mul_f32_e32 v23, 0xbed49a78, v22
	v_cmp_gt_f32_e32 vcc, s74, v23
	v_mul_f32_e32 v21, v131, v41
	v_mul_f32_e32 v21, 0.15915494, v21
	v_cndmask_b32_e32 v23, 0, v225, vcc
	v_fmac_f32_e32 v23, 0xbed49a78, v22
	v_exp_f32_e32 v22, v23
	v_sin_f32_e32 v116, v21
	v_cos_f32_e32 v117, v21
	v_cndmask_b32_e32 v21, 0, v226, vcc
	v_ldexp_f32 v132, v22, v21
	v_or_b32_e32 v22, 20, v20
	v_cvt_f32_ubyte0_e32 v22, v22
	v_mul_f32_e32 v23, 0xbed49a78, v22
	v_cmp_gt_f32_e32 vcc, s74, v23
	v_mul_f32_e32 v21, v132, v41
	v_mul_f32_e32 v21, 0.15915494, v21
	v_cndmask_b32_e32 v23, 0, v225, vcc
	v_fmac_f32_e32 v23, 0xbed49a78, v22
	v_exp_f32_e32 v22, v23
	v_sin_f32_e32 v123, v21
	v_cos_f32_e32 v122, v21
	v_cndmask_b32_e32 v21, 0, v226, vcc
	v_ldexp_f32 v133, v22, v21
	v_or_b32_e32 v22, 21, v20
	v_cvt_f32_ubyte0_e32 v22, v22
	v_mul_f32_e32 v23, 0xbed49a78, v22
	v_cmp_gt_f32_e32 vcc, s74, v23
	v_mul_f32_e32 v21, v133, v41
	v_mul_f32_e32 v21, 0.15915494, v21
	v_cndmask_b32_e32 v23, 0, v225, vcc
	v_fmac_f32_e32 v23, 0xbed49a78, v22
	v_exp_f32_e32 v22, v23
	v_sin_f32_e32 v126, v21
	v_cos_f32_e32 v127, v21
	v_cndmask_b32_e32 v21, 0, v226, vcc
	v_ldexp_f32 v134, v22, v21
	v_or_b32_e32 v22, 22, v20
	v_cvt_f32_ubyte0_e32 v22, v22
	v_mul_f32_e32 v23, 0xbed49a78, v22
	v_cmp_gt_f32_e32 vcc, s74, v23
	v_mul_f32_e32 v21, v134, v41
	v_mul_f32_e32 v21, 0.15915494, v21
	v_cndmask_b32_e32 v23, 0, v225, vcc
	v_fmac_f32_e32 v23, 0xbed49a78, v22
	v_exp_f32_e32 v22, v23
	v_sin_f32_e32 v137, v21
	v_cos_f32_e32 v136, v21
	v_cndmask_b32_e32 v21, 0, v226, vcc
	v_ldexp_f32 v135, v22, v21
	v_or_b32_e32 v20, 23, v20
	v_mul_f32_e32 v21, v135, v41
	v_cvt_f32_ubyte0_e32 v20, v20
	v_ldexp_f32 v42, v0, v1
	v_ldexp_f32 v129, v16, v17
	v_mul_f32_e32 v43, 0.15915494, v21
	v_mul_f32_e32 v21, 0xbed49a78, v20
	v_mul_f32_e32 v0, v42, v41
	v_mul_f32_e32 v16, v129, v41
	v_cmp_gt_f32_e32 vcc, s74, v21
	v_mul_f32_e32 v0, 0.15915494, v0
	v_and_b32_e32 v68, 32, v230
	v_mul_f32_e32 v16, 0.15915494, v16
	v_cndmask_b32_e32 v44, 0, v225, vcc
	v_sin_f32_e32 v96, v0
	v_cos_f32_e32 v97, v0
	global_load_dwordx4 v[0:3], v68, s[36:37] offset:16
	global_load_dwordx4 v[8:11], v68, s[36:37]
	global_load_dwordx4 v[4:7], v68, s[36:37] offset:144
	global_load_dwordx4 v[12:15], v68, s[36:37] offset:128
	v_sin_f32_e32 v110, v16
	v_cos_f32_e32 v111, v16
	global_load_dwordx4 v[16:19], v68, s[36:37] offset:80
	global_load_dwordx4 v[32:35], v68, s[36:37] offset:64
	global_load_dwordx4 v[28:31], v68, s[36:37] offset:208
	global_load_dwordx4 v[36:39], v68, s[36:37] offset:192
	v_fmac_f32_e32 v44, 0xbed49a78, v20
	global_load_dwordx4 v[20:23], v68, s[36:37] offset:336
	global_load_dwordx4 v[24:27], v68, s[36:37] offset:464
	v_cvt_f32_ubyte0_e32 v151, v40
	v_mul_f32_e32 v118, v118, v151
	v_mul_f32_e32 v118, 0.15915494, v118
	v_sin_f32_e32 v163, v118
	v_cos_f32_e32 v162, v118
	v_mul_f32_e32 v118, v119, v151
	v_mul_f32_e32 v118, 0.15915494, v118
	v_sin_f32_e32 v160, v118
	v_cos_f32_e32 v161, v118
	v_mul_f32_e32 v118, v120, v151
	v_mul_f32_e32 v118, 0.15915494, v118
	v_sin_f32_e32 v159, v118
	v_cos_f32_e32 v158, v118
	v_mul_f32_e32 v118, v121, v151
	v_mul_f32_e32 v118, 0.15915494, v118
	v_sin_f32_e32 v156, v118
	v_cos_f32_e32 v157, v118
	v_mul_f32_e32 v118, v124, v151
	v_mul_f32_e32 v118, 0.15915494, v118
	v_sin_f32_e32 v153, v118
	v_cos_f32_e32 v152, v118
	v_mul_f32_e32 v118, v125, v151
	v_mul_f32_e32 v118, 0.15915494, v118
	v_sin_f32_e32 v148, v118
	v_cos_f32_e32 v149, v118
	v_mul_f32_e32 v118, v128, v151
	v_mul_f32_e32 v118, 0.15915494, v118
	v_sin_f32_e32 v147, v118
	v_cos_f32_e32 v146, v118
	v_mul_f32_e32 v118, v129, v151
	v_mul_f32_e32 v118, 0.15915494, v118
	v_sin_f32_e32 v144, v118
	v_cos_f32_e32 v145, v118
	v_mul_f32_e32 v118, v130, v151
	v_mul_f32_e32 v118, 0.15915494, v118
	v_sin_f32_e32 v143, v118
	v_cos_f32_e32 v142, v118
	v_mul_f32_e32 v118, v131, v151
	v_mul_f32_e32 v118, 0.15915494, v118
	v_sin_f32_e32 v140, v118
	v_cos_f32_e32 v141, v118
	v_mul_f32_e32 v118, v132, v151
	v_exp_f32_e32 v44, v44
	v_mul_f32_e32 v118, 0.15915494, v118
	v_sin_f32_e32 v139, v118
	v_cos_f32_e32 v138, v118
	v_mul_f32_e32 v118, v133, v151
	v_mul_f32_e32 v118, 0.15915494, v118
	v_sin_f32_e32 v174, v43
	v_cos_f32_e32 v175, v43
	v_cndmask_b32_e32 v43, 0, v226, vcc
	v_sin_f32_e32 v132, v118
	v_cos_f32_e32 v133, v118
	v_mul_f32_e32 v118, v134, v151
	v_ldexp_f32 v150, v44, v43
	v_mul_f32_e32 v118, 0.15915494, v118
	v_mul_f32_e32 v40, v42, v151
	v_sin_f32_e32 v125, v118
	v_cos_f32_e32 v124, v118
	v_mul_f32_e32 v118, v135, v151
	s_waitcnt vmcnt(0)
;     ...
;     float x[8][8]; float ssq = 0.f;
; #pragma unroll
;     for (int d0 = 0; d0 < 8; ++d0)
; #pragma unroll
;       for (int j = 0; j < 8; ++j) { x[d0][j] = __builtin_bit_cast(float, (unsigned)(unsigned short)qr[d0][j] << 16); ssq += x[d0][j] * x[d0][j]; }
;     { auto rr = __builtin_amdgcn_permlane32_swap(__float_as_uint(ssq), __float_as_uint(ssq), false, false); ssq = __uint_as_float(rr[0]) + __uint_as_float(rr[1]); }
	v_lshlrev_b32_e32 v128, 16, v91
	v_and_b32_e32 v134, 0xffff0000, v91
	v_and_b32_e32 v91, 0xffff0000, v94
	v_lshlrev_b32_e32 v170, 16, v89
	v_lshlrev_b32_e32 v177, 16, v92
	v_lshlrev_b32_e32 v180, 16, v83
	v_lshlrev_b32_e32 v185, 16, v86
	v_lshlrev_b32_e32 v188, 16, v81
	v_lshlrev_b32_e32 v193, 16, v84
	v_lshlrev_b32_e32 v196, 16, v75
	v_lshlrev_b32_e32 v201, 16, v78
	v_lshlrev_b32_e32 v204, 16, v73
	v_lshlrev_b32_e32 v209, 16, v76
	v_lshlrev_b32_e32 v214, 16, v59
	v_lshlrev_b32_e32 v233, 16, v62
	v_and_b32_e32 v234, 0xffff0000, v57
	v_lshlrev_b32_e32 v236, 16, v56
	v_and_b32_e32 v56, 0xffff0000, v56
	v_mov_b32_e32 v130, v22
	v_mul_f32_e32 v22, v150, v151
	v_lshlrev_b32_e32 v151, 16, v94
	v_and_b32_e32 v94, 0xffff0000, v89
	v_and_b32_e32 v89, 0xffff0000, v92
	v_and_b32_e32 v92, 0xffff0000, v83
	v_and_b32_e32 v83, 0xffff0000, v86
	v_and_b32_e32 v86, 0xffff0000, v81
	v_and_b32_e32 v81, 0xffff0000, v84
	v_and_b32_e32 v84, 0xffff0000, v75
	v_and_b32_e32 v75, 0xffff0000, v78
	v_and_b32_e32 v78, 0xffff0000, v73
	v_and_b32_e32 v73, 0xffff0000, v76
	v_and_b32_e32 v76, 0xffff0000, v59
	v_and_b32_e32 v59, 0xffff0000, v62
	v_lshlrev_b32_e32 v62, 16, v57
	v_and_b32_e32 v57, 0xffff0000, v60
	v_lshlrev_b32_e32 v129, 16, v95
	v_and_b32_e32 v135, 0xffff0000, v95
	v_lshlrev_b32_e32 v171, 16, v93
	v_and_b32_e32 v95, 0xffff0000, v93
	v_lshlrev_b32_e32 v181, 16, v87
	v_and_b32_e32 v93, 0xffff0000, v87
	v_lshlrev_b32_e32 v189, 16, v85
	v_and_b32_e32 v87, 0xffff0000, v85
	v_lshlrev_b32_e32 v197, 16, v79
	v_and_b32_e32 v85, 0xffff0000, v79
	v_lshlrev_b32_e32 v205, 16, v77
	v_and_b32_e32 v79, 0xffff0000, v77
	v_lshlrev_b32_e32 v215, 16, v63
	v_and_b32_e32 v77, 0xffff0000, v63
	v_lshlrev_b32_e32 v63, 16, v61
	v_and_b32_e32 v235, 0xffff0000, v61
	v_lshlrev_b32_e32 v237, 16, v60
	v_pk_mul_f32 v[60:61], v[56:57], v[56:57]
	v_lshlrev_b32_e32 v232, 16, v58
	v_pk_fma_f32 v[238:239], v[236:237], v[236:237], v[60:61]
	v_and_b32_e32 v58, 0xffff0000, v58
	v_pk_fma_f32 v[238:239], v[62:63], v[62:63], v[238:239]
	v_lshlrev_b32_e32 v208, 16, v72
	v_pk_fma_f32 v[238:239], v[234:235], v[234:235], v[238:239]
	v_and_b32_e32 v72, 0xffff0000, v72
	v_pk_fma_f32 v[238:239], v[232:233], v[232:233], v[238:239]
	v_lshlrev_b32_e32 v200, 16, v74
	v_pk_fma_f32 v[238:239], v[58:59], v[58:59], v[238:239]
	v_and_b32_e32 v74, 0xffff0000, v74
	v_pk_fma_f32 v[238:239], v[214:215], v[214:215], v[238:239]
	v_mov_b32_e32 v216, v2
	v_pk_fma_f32 v[238:239], v[76:77], v[76:77], v[238:239]
	v_mul_f32_e32 v2, v237, v237
	v_pk_fma_f32 v[238:239], v[208:209], v[208:209], v[238:239]
	v_lshlrev_b32_e32 v192, 16, v80
	v_pk_fma_f32 v[238:239], v[72:73], v[72:73], v[238:239]
	v_and_b32_e32 v80, 0xffff0000, v80
	v_pk_fma_f32 v[238:239], v[204:205], v[204:205], v[238:239]
	v_lshlrev_b32_e32 v184, 16, v82
	v_pk_fma_f32 v[238:239], v[78:79], v[78:79], v[238:239]
	v_and_b32_e32 v82, 0xffff0000, v82
	v_pk_fma_f32 v[238:239], v[200:201], v[200:201], v[238:239]
	v_lshlrev_b32_e32 v176, 16, v88
	v_pk_fma_f32 v[238:239], v[74:75], v[74:75], v[238:239]
	v_and_b32_e32 v88, 0xffff0000, v88
	v_pk_fma_f32 v[238:239], v[196:197], v[196:197], v[238:239]
	v_mul_f32_e32 v41, v150, v41
	v_pk_fma_f32 v[238:239], v[84:85], v[84:85], v[238:239]
	v_lshlrev_b32_e32 v150, 16, v90
	v_pk_add_f32 v[238:239], v[2:3], v[238:239] op_sel_hi:[0,1]
	v_pk_add_f32 v[60:61], v[60:61], v[238:239] op_sel:[1,0] op_sel_hi:[0,1]
	v_mul_f32_e32 v2, v63, v63
	v_pk_add_f32 v[60:61], v[2:3], v[60:61] op_sel_hi:[0,1]
	v_mul_f32_e32 v2, v235, v235
	v_pk_add_f32 v[60:61], v[2:3], v[60:61] op_sel_hi:[0,1]
	v_mul_f32_e32 v2, v233, v233
	v_pk_add_f32 v[60:61], v[2:3], v[60:61] op_sel_hi:[0,1]
	v_mul_f32_e32 v2, v59, v59
	v_pk_add_f32 v[60:61], v[2:3], v[60:61] op_sel_hi:[0,1]
	v_mul_f32_e32 v2, v215, v215
	v_pk_add_f32 v[60:61], v[2:3], v[60:61] op_sel_hi:[0,1]
	v_mul_f32_e32 v2, v77, v77
	v_pk_add_f32 v[60:61], v[2:3], v[60:61] op_sel_hi:[0,1]
	v_mul_f32_e32 v2, v209, v209
	v_pk_add_f32 v[60:61], v[2:3], v[60:61] op_sel_hi:[0,1]
	v_mul_f32_e32 v2, v73, v73
	v_pk_add_f32 v[60:61], v[2:3], v[60:61] op_sel_hi:[0,1]
	v_mul_f32_e32 v2, v205, v205
	v_pk_add_f32 v[60:61], v[2:3], v[60:61] op_sel_hi:[0,1]
	v_mul_f32_e32 v2, v79, v79
	v_pk_add_f32 v[60:61], v[2:3], v[60:61] op_sel_hi:[0,1]
	v_mul_f32_e32 v2, v201, v201
	v_pk_add_f32 v[60:61], v[2:3], v[60:61] op_sel_hi:[0,1]
	v_mul_f32_e32 v2, v75, v75
	v_pk_add_f32 v[60:61], v[2:3], v[60:61] op_sel_hi:[0,1]
	v_mul_f32_e32 v2, v197, v197
	v_pk_add_f32 v[60:61], v[2:3], v[60:61] op_sel_hi:[0,1]
	v_mul_f32_e32 v2, v85, v85
	v_pk_add_f32 v[60:61], v[2:3], v[60:61] op_sel_hi:[0,1]
	v_pk_fma_f32 v[60:61], v[192:193], v[192:193], v[60:61]
	v_and_b32_e32 v90, 0xffff0000, v90
	v_pk_fma_f32 v[60:61], v[80:81], v[80:81], v[60:61]
	v_mul_f32_e32 v2, v193, v193
	v_pk_fma_f32 v[60:61], v[188:189], v[188:189], v[60:61]
	v_mul_f32_e32 v41, 0.15915494, v41
	v_pk_fma_f32 v[60:61], v[86:87], v[86:87], v[60:61]
	v_mul_f32_e32 v40, 0.15915494, v40
	v_pk_fma_f32 v[60:61], v[184:185], v[184:185], v[60:61]
	v_sin_f32_e32 v169, v41
	v_pk_fma_f32 v[60:61], v[82:83], v[82:83], v[60:61]
	v_cos_f32_e32 v168, v41
	v_pk_fma_f32 v[60:61], v[180:181], v[180:181], v[60:61]
	v_sin_f32_e32 v166, v40
	v_pk_fma_f32 v[60:61], v[92:93], v[92:93], v[60:61]
	v_cos_f32_e32 v167, v40
	v_pk_fma_f32 v[60:61], v[176:177], v[176:177], v[60:61]
	global_load_dwordx4 v[48:51], v68, s[36:37] offset:272
	global_load_dwordx4 v[64:67], v68, s[36:37] offset:256
	global_load_dwordx4 v[44:47], v68, s[36:37] offset:320
	global_load_dwordx4 v[40:43], v68, s[36:37] offset:448
	global_load_dwordx4 v[52:55], v68, s[36:37] offset:400
	s_nop 0
	global_load_dwordx4 v[68:71], v68, s[36:37] offset:384
;     ...
;     { auto rr = __builtin_amdgcn_permlane32_swap(__float_as_uint(ssq), __float_as_uint(ssq), false, false); ssq = __uint_as_float(rr[0]) + __uint_as_float(rr[1]); }
;     const float rstd = 1.0f / sqrtf(ssq * (1.0f / 128.0f) + 1e-6f);
;     const int sq = qs0 + wid * QBLK + r32;
; #pragma unroll
;     for (int aa = 0; aa < 2; ++aa) { const float pos = (float)(aa == 0 ? (sq >> 6) : (sq & 63));
; #pragma unroll
;       for (int dd = 0; dd < 2; ++dd) { const int d0 = aa * 4 + dd;
; #pragma unroll
;         for (int j = 0; j < 8; ++j) { const int i = 16 * dd + 8 * hi + j; const int e1 = aa * 64 + i;
;           const float rev = pos * exp2f(-(float)i * 0.41524101186092029f) * 0.15915494309189535f;
;           const float sn = __builtin_amdgcn_sinf(rev), cs = __builtin_amdgcn_cosf(rev);
;           const float y1 = x[d0][j] * rstd * qgain[e1], y2 = x[d0 + 2][j] * rstd * qgain[e1 + 32];
;           x[d0][j] = y1 * cs - y2 * sn; x[d0 + 2][j] = y2 * cs + y1 * sn; } } }
	v_pk_fma_f32 v[60:61], v[88:89], v[88:89], v[60:61]
	v_mov_b32_e32 v212, v135
	v_pk_fma_f32 v[60:61], v[170:171], v[170:171], v[60:61]
	v_mov_b32_e32 v213, v129
	v_pk_fma_f32 v[60:61], v[94:95], v[94:95], v[60:61]
	v_mov_b32_e32 v217, v6
	v_pk_fma_f32 v[60:61], v[150:151], v[150:151], v[60:61]
	v_mov_b32_e32 v6, 0x358637bd
	v_pk_fma_f32 v[60:61], v[90:91], v[90:91], v[60:61]
	s_mov_b32 s0, 0xf800000
	v_pk_fma_f32 v[60:61], v[128:129], v[128:129], v[60:61]
	v_mov_b32_e32 v238, v8
	v_pk_fma_f32 v[60:61], v[134:135], v[134:135], v[60:61]
	v_mov_b32_e32 v239, v12
	v_pk_add_f32 v[60:61], v[2:3], v[60:61] op_sel_hi:[0,1]
	v_mul_f32_e32 v2, v81, v81
	v_pk_add_f32 v[60:61], v[2:3], v[60:61] op_sel_hi:[0,1]
	v_mul_f32_e32 v2, v189, v189
	v_pk_add_f32 v[60:61], v[2:3], v[60:61] op_sel_hi:[0,1]
	v_mul_f32_e32 v2, v87, v87
	v_pk_add_f32 v[60:61], v[2:3], v[60:61] op_sel_hi:[0,1]
	v_mul_f32_e32 v2, v185, v185
	v_pk_add_f32 v[60:61], v[2:3], v[60:61] op_sel_hi:[0,1]
	v_mul_f32_e32 v2, v83, v83
	v_pk_add_f32 v[60:61], v[2:3], v[60:61] op_sel_hi:[0,1]
	v_mul_f32_e32 v2, v181, v181
	v_pk_add_f32 v[60:61], v[2:3], v[60:61] op_sel_hi:[0,1]
	v_mul_f32_e32 v2, v93, v93
	v_pk_add_f32 v[60:61], v[2:3], v[60:61] op_sel_hi:[0,1]
	v_mul_f32_e32 v2, v177, v177
	v_pk_add_f32 v[60:61], v[2:3], v[60:61] op_sel_hi:[0,1]
	v_mul_f32_e32 v2, v89, v89
	v_pk_add_f32 v[60:61], v[2:3], v[60:61] op_sel_hi:[0,1]
	v_mul_f32_e32 v2, v171, v171
	v_pk_add_f32 v[60:61], v[2:3], v[60:61] op_sel_hi:[0,1]
	v_mul_f32_e32 v2, v95, v95
	v_pk_add_f32 v[60:61], v[2:3], v[60:61] op_sel_hi:[0,1]
	v_mul_f32_e32 v2, v151, v151
	v_pk_add_f32 v[60:61], v[2:3], v[60:61] op_sel_hi:[0,1]
	v_mul_f32_e32 v2, v91, v91
	v_pk_add_f32 v[60:61], v[2:3], v[60:61] op_sel_hi:[0,1]
	v_mul_f32_e32 v2, v129, v129
	v_pk_add_f32 v[60:61], v[2:3], v[60:61] op_sel_hi:[0,1]
	v_pk_fma_f32 v[60:61], v[212:213], v[212:213], v[60:61]
	v_mov_b32_e32 v212, v10
	v_mov_b32_e32 v2, v60
	s_nop 1
	v_permlane32_swap_b32_e32 v60, v2
	v_add_f32_e32 v2, v60, v2
	v_fmamk_f32 v2, v2, 0x3c000000, v6
	v_mul_f32_e32 v6, 0x4f800000, v2
	v_cmp_gt_f32_e32 vcc, s0, v2
	v_mov_b32_e32 v60, v0
	v_mov_b32_e32 v61, v4
	v_cndmask_b32_e32 v2, v2, v6, vcc
	v_sqrt_f32_e32 v6, v2
	v_mov_b32_e32 v12, v9
	v_mov_b32_e32 v154, v20
	v_mul_f32_e32 v22, 0.15915494, v22
	v_add_u32_e32 v0, -1, v6
	v_fma_f32 v4, -v0, v6, v2
	v_cmp_ge_f32_e64 s[0:1], 0, v4
	v_add_u32_e32 v4, 1, v6
	v_sin_f32_e32 v121, v22
	v_cndmask_b32_e64 v0, v6, v0, s[0:1]
	v_fma_f32 v6, -v4, v6, v2
	v_cmp_lt_f32_e64 s[0:1], 0, v6
	v_cos_f32_e32 v120, v22
	v_mov_b32_e32 v213, v14
	v_cndmask_b32_e64 v0, v0, v4, s[0:1]
	v_mul_f32_e32 v4, 0x37800000, v0
	v_cndmask_b32_e32 v0, v0, v4, vcc
	v_cmp_class_f32_e32 vcc, v2, v223
	v_mov_b32_e32 v14, v11
	v_mov_b32_e32 v210, v32
	v_cndmask_b32_e32 v0, v0, v2, vcc
	v_div_scale_f32 v2, s[0:1], v0, v0, 1.0
	v_rcp_f32_e32 v4, v2
	v_mov_b32_e32 v206, v34
	v_mov_b32_e32 v211, v36
	s_waitcnt vmcnt(3)
	v_mov_b32_e32 v172, v46
	v_fma_f32 v6, -v2, v4, 1.0
	v_fmac_f32_e32 v4, v6, v4
	v_div_scale_f32 v6, vcc, 1.0, v0, 1.0
	v_mul_f32_e32 v8, v6, v4
	v_fma_f32 v10, -v2, v8, v6
	v_fmac_f32_e32 v8, v10, v4
	v_fma_f32 v2, -v2, v8, v6
	v_div_fmas_f32 v2, v2, v4, v8
	v_div_fixup_f32 v0, v2, v0, 1.0
	v_mul_f32_e32 v0, 0x3e0293ee, v0
	v_pk_mul_f32 v[56:57], v[0:1], v[56:57] op_sel_hi:[0,1]
	v_pk_mul_f32 v[8:9], v[12:13], v[56:57]
	v_mov_b32_e32 v4, v1
	v_pk_mul_f32 v[12:13], v[98:99], v[8:9]
	v_mov_b32_e32 v6, v3
	v_sub_f32_e32 v20, v12, v13
	v_mov_b32_e32 v12, v99
	v_mov_b32_e32 v13, v98
	v_pk_mul_f32 v[8:9], v[12:13], v[8:9]
	v_mov_b32_e32 v12, v101
	v_add_f32_e32 v22, v8, v9
	v_pk_mul_f32 v[8:9], v[0:1], v[62:63] op_sel_hi:[0,1]
	v_pk_mul_f32 v[8:9], v[212:213], v[8:9]
	v_mov_b32_e32 v13, v100
	v_pk_mul_f32 v[12:13], v[12:13], v[8:9]
	v_pk_mul_f32 v[8:9], v[100:101], v[8:9]
	v_sub_f32_e32 v12, v12, v13
	v_add_f32_e32 v13, v8, v9
	v_pk_mul_f32 v[8:9], v[0:1], v[234:235] op_sel_hi:[0,1]
	v_pk_mul_f32 v[8:9], v[14:15], v[8:9]
	v_mov_b32_e32 v36, v33
	v_pk_mul_f32 v[10:11], v[102:103], v[8:9]
	v_mov_b32_e32 v178, v44
	v_sub_f32_e32 v14, v10, v11
	v_mov_b32_e32 v10, v103
	v_mov_b32_e32 v11, v102
	v_pk_mul_f32 v[8:9], v[10:11], v[8:9]
	v_mov_b32_e32 v10, v105
	v_add_f32_e32 v15, v8, v9
	v_pk_mul_f32 v[8:9], v[0:1], v[232:233] op_sel_hi:[0,1]
	v_pk_mul_f32 v[8:9], v[8:9], v[60:61]
	v_mov_b32_e32 v11, v104
	v_pk_mul_f32 v[10:11], v[10:11], v[8:9]
	v_pk_mul_f32 v[8:9], v[104:105], v[8:9]
	v_sub_f32_e32 v10, v10, v11
	v_add_f32_e32 v11, v8, v9
	v_pk_mul_f32 v[8:9], v[0:1], v[58:59] op_sel_hi:[0,1]
	v_pk_mul_f32 v[4:5], v[8:9], v[4:5]
	v_mov_b32_e32 v207, v38
	v_pk_mul_f32 v[8:9], v[106:107], v[4:5]
	v_mov_b32_e32 v186, v48
	v_sub_f32_e32 v32, v8, v9
	v_mov_b32_e32 v8, v107
	v_mov_b32_e32 v9, v106
	v_pk_mul_f32 v[4:5], v[8:9], v[4:5]
	v_mov_b32_e32 v8, v109
	v_add_f32_e32 v34, v4, v5
	v_pk_mul_f32 v[4:5], v[0:1], v[214:215] op_sel_hi:[0,1]
	v_pk_mul_f32 v[4:5], v[4:5], v[216:217]
	v_mov_b32_e32 v9, v108
	v_pk_mul_f32 v[8:9], v[8:9], v[4:5]
	v_pk_mul_f32 v[4:5], v[108:109], v[4:5]
	v_sub_f32_e32 v8, v8, v9
	v_add_f32_e32 v9, v4, v5
	v_pk_mul_f32 v[4:5], v[0:1], v[76:77] op_sel_hi:[0,1]
	v_pk_mul_f32 v[2:3], v[4:5], v[6:7]
	v_mov_b32_e32 v38, v35
	v_pk_mul_f32 v[4:5], v[112:113], v[2:3]
	v_mov_b32_e32 v202, v16
	v_sub_f32_e32 v6, v4, v5
	v_mov_b32_e32 v4, v113
	v_mov_b32_e32 v5, v112
	v_pk_mul_f32 v[2:3], v[4:5], v[2:3]
	v_mov_b32_e32 v4, v111
	v_add_f32_e32 v7, v2, v3
	v_pk_mul_f32 v[2:3], v[0:1], v[208:209] op_sel_hi:[0,1]
	v_pk_mul_f32 v[2:3], v[2:3], v[210:211]
	v_mov_b32_e32 v5, v110
	v_pk_mul_f32 v[4:5], v[4:5], v[2:3]
	v_pk_mul_f32 v[2:3], v[110:111], v[2:3]
;     ...
;       for (int dd = 0; dd < 2; ++dd) { const int d0 = aa * 4 + dd;
; #pragma unroll
;         for (int j = 0; j < 8; ++j) { const int i = 16 * dd + 8 * hi + j; const int e1 = aa * 64 + i;
;           const float rev = pos * exp2f(-(float)i * 0.41524101186092029f) * 0.15915494309189535f;
;           const float sn = __builtin_amdgcn_sinf(rev), cs = __builtin_amdgcn_cosf(rev);
;           const float y1 = x[d0][j] * rstd * qgain[e1], y2 = x[d0 + 2][j] * rstd * qgain[e1 + 32];
;           x[d0][j] = y1 * cs - y2 * sn; x[d0 + 2][j] = y2 * cs + y1 * sn; } } }
	v_sub_f32_e32 v44, v4, v5
	v_add_f32_e32 v46, v2, v3
	v_pk_mul_f32 v[2:3], v[0:1], v[72:73] op_sel_hi:[0,1]
	v_pk_mul_f32 v[2:3], v[2:3], v[36:37]
	v_mov_b32_e32 v203, v28
	v_pk_mul_f32 v[4:5], v[114:115], v[2:3]
	v_mov_b32_e32 v182, v50
	v_sub_f32_e32 v33, v4, v5
	v_mov_b32_e32 v4, v115
	v_mov_b32_e32 v5, v114
	v_pk_mul_f32 v[2:3], v[4:5], v[2:3]
	v_mov_b32_e32 v4, v117
	v_add_f32_e32 v36, v2, v3
	v_pk_mul_f32 v[2:3], v[0:1], v[204:205] op_sel_hi:[0,1]
	v_pk_mul_f32 v[2:3], v[2:3], v[206:207]
	v_mov_b32_e32 v5, v116
	v_pk_mul_f32 v[4:5], v[4:5], v[2:3]
	v_pk_mul_f32 v[2:3], v[116:117], v[2:3]
	v_sub_f32_e32 v37, v4, v5
	v_add_f32_e32 v48, v2, v3
	v_pk_mul_f32 v[2:3], v[0:1], v[78:79] op_sel_hi:[0,1]
	v_pk_mul_f32 v[2:3], v[2:3], v[38:39]
	v_mov_b32_e32 v28, v17
	v_pk_mul_f32 v[4:5], v[122:123], v[2:3]
	v_mov_b32_e32 v198, v18
	v_sub_f32_e32 v35, v4, v5
	v_mov_b32_e32 v4, v123
	v_mov_b32_e32 v5, v122
	v_pk_mul_f32 v[2:3], v[4:5], v[2:3]
	v_mov_b32_e32 v4, v127
	v_add_f32_e32 v38, v2, v3
	v_pk_mul_f32 v[2:3], v[0:1], v[200:201] op_sel_hi:[0,1]
	v_pk_mul_f32 v[2:3], v[2:3], v[202:203]
	v_mov_b32_e32 v5, v126
	v_pk_mul_f32 v[4:5], v[4:5], v[2:3]
	v_pk_mul_f32 v[2:3], v[126:127], v[2:3]
	v_sub_f32_e32 v39, v4, v5
	v_add_f32_e32 v50, v2, v3
	v_pk_mul_f32 v[2:3], v[0:1], v[74:75] op_sel_hi:[0,1]
	v_pk_mul_f32 v[2:3], v[2:3], v[28:29]
	v_mov_b32_e32 v199, v30
	v_pk_mul_f32 v[4:5], v[136:137], v[2:3]
	v_mov_b32_e32 v30, v19
	v_sub_f32_e32 v17, v4, v5
	v_mov_b32_e32 v4, v137
	v_mov_b32_e32 v5, v136
	v_pk_mul_f32 v[2:3], v[4:5], v[2:3]
	v_mov_b32_e32 v4, v175
	v_add_f32_e32 v28, v2, v3
	v_pk_mul_f32 v[2:3], v[0:1], v[196:197] op_sel_hi:[0,1]
	v_pk_mul_f32 v[2:3], v[2:3], v[198:199]
	v_mov_b32_e32 v5, v174
	v_pk_mul_f32 v[4:5], v[4:5], v[2:3]
	v_pk_mul_f32 v[2:3], v[174:175], v[2:3]
	v_sub_f32_e32 v29, v4, v5
	v_add_f32_e32 v56, v2, v3
	v_pk_mul_f32 v[2:3], v[0:1], v[84:85] op_sel_hi:[0,1]
	v_pk_mul_f32 v[2:3], v[2:3], v[30:31]
	v_mov_b32_e32 v194, v64
	v_pk_mul_f32 v[4:5], v[168:169], v[2:3]
	s_waitcnt vmcnt(0)
	v_mov_b32_e32 v195, v68
	v_sub_f32_e32 v19, v4, v5
	v_mov_b32_e32 v4, v169
	v_mov_b32_e32 v5, v168
	v_pk_mul_f32 v[2:3], v[4:5], v[2:3]
	v_mov_b32_e32 v4, v167
	v_add_f32_e32 v30, v2, v3
	v_pk_mul_f32 v[2:3], v[0:1], v[192:193] op_sel_hi:[0,1]
	v_pk_mul_f32 v[2:3], v[2:3], v[194:195]
	v_mov_b32_e32 v5, v166
	v_pk_mul_f32 v[4:5], v[4:5], v[2:3]
	v_pk_mul_f32 v[2:3], v[166:167], v[2:3]
	v_mov_b32_e32 v68, v65
	v_add_f32_e32 v57, v2, v3
	v_pk_mul_f32 v[2:3], v[0:1], v[80:81] op_sel_hi:[0,1]
	v_pk_mul_f32 v[2:3], v[2:3], v[68:69]
	v_sub_f32_e32 v31, v4, v5
	v_pk_mul_f32 v[4:5], v[162:163], v[2:3]
	v_mov_b32_e32 v190, v66
	v_sub_f32_e32 v58, v4, v5
	v_mov_b32_e32 v4, v163
	v_mov_b32_e32 v5, v162
	v_pk_mul_f32 v[2:3], v[4:5], v[2:3]
	v_mov_b32_e32 v191, v70
	v_add_f32_e32 v59, v2, v3
	v_pk_mul_f32 v[2:3], v[0:1], v[188:189] op_sel_hi:[0,1]
	v_pk_mul_f32 v[2:3], v[2:3], v[190:191]
	v_mov_b32_e32 v4, v161
	v_mov_b32_e32 v5, v160
	v_pk_mul_f32 v[4:5], v[4:5], v[2:3]
	v_pk_mul_f32 v[2:3], v[160:161], v[2:3]
	v_mov_b32_e32 v70, v67
	v_add_f32_e32 v61, v2, v3
	v_pk_mul_f32 v[2:3], v[0:1], v[86:87] op_sel_hi:[0,1]
	v_pk_mul_f32 v[2:3], v[2:3], v[70:71]
	v_sub_f32_e32 v60, v4, v5
	v_pk_mul_f32 v[4:5], v[158:159], v[2:3]
	v_mov_b32_e32 v187, v52
	v_sub_f32_e32 v62, v4, v5
	v_mov_b32_e32 v4, v159
	v_mov_b32_e32 v5, v158
	v_pk_mul_f32 v[2:3], v[4:5], v[2:3]
	v_mov_b32_e32 v4, v157
	v_add_f32_e32 v63, v2, v3
	v_pk_mul_f32 v[2:3], v[0:1], v[184:185] op_sel_hi:[0,1]
	v_pk_mul_f32 v[2:3], v[2:3], v[186:187]
	v_mov_b32_e32 v5, v156
	v_pk_mul_f32 v[4:5], v[4:5], v[2:3]
	v_pk_mul_f32 v[2:3], v[156:157], v[2:3]
	v_mov_b32_e32 v52, v49
	v_add_f32_e32 v65, v2, v3
	v_pk_mul_f32 v[2:3], v[0:1], v[82:83] op_sel_hi:[0,1]
	v_pk_mul_f32 v[2:3], v[2:3], v[52:53]
	v_sub_f32_e32 v64, v4, v5
	v_pk_mul_f32 v[4:5], v[152:153], v[2:3]
	v_mov_b32_e32 v183, v54
	v_sub_f32_e32 v49, v4, v5
	v_mov_b32_e32 v4, v153
	v_mov_b32_e32 v5, v152
	v_pk_mul_f32 v[2:3], v[4:5], v[2:3]
	v_mov_b32_e32 v4, v149
	v_add_f32_e32 v52, v2, v3
	v_pk_mul_f32 v[2:3], v[0:1], v[180:181] op_sel_hi:[0,1]
	v_pk_mul_f32 v[2:3], v[2:3], v[182:183]
	v_mov_b32_e32 v5, v148
	v_pk_mul_f32 v[4:5], v[4:5], v[2:3]
	v_pk_mul_f32 v[2:3], v[148:149], v[2:3]
	v_mov_b32_e32 v54, v51
	v_add_f32_e32 v66, v2, v3
	v_pk_mul_f32 v[2:3], v[0:1], v[92:93] op_sel_hi:[0,1]
	v_pk_mul_f32 v[2:3], v[2:3], v[54:55]
	v_sub_f32_e32 v53, v4, v5
	v_pk_mul_f32 v[4:5], v[146:147], v[2:3]
	v_mov_b32_e32 v179, v40
	v_sub_f32_e32 v51, v4, v5
	v_mov_b32_e32 v4, v147
	v_mov_b32_e32 v5, v146
	v_pk_mul_f32 v[2:3], v[4:5], v[2:3]
	v_mov_b32_e32 v4, v145
	v_add_f32_e32 v54, v2, v3
	v_pk_mul_f32 v[2:3], v[0:1], v[176:177] op_sel_hi:[0,1]
	v_pk_mul_f32 v[2:3], v[2:3], v[178:179]
	v_mov_b32_e32 v5, v144
	v_pk_mul_f32 v[4:5], v[4:5], v[2:3]
	v_pk_mul_f32 v[2:3], v[144:145], v[2:3]
	v_mov_b32_e32 v40, v45
	v_add_f32_e32 v67, v2, v3
	v_pk_mul_f32 v[2:3], v[0:1], v[88:89] op_sel_hi:[0,1]
	v_pk_mul_f32 v[2:3], v[2:3], v[40:41]
	v_sub_f32_e32 v55, v4, v5
	v_pk_mul_f32 v[4:5], v[142:143], v[2:3]
	v_mov_b32_e32 v173, v42
	v_sub_f32_e32 v40, v4, v5
	v_mov_b32_e32 v4, v143
	v_mov_b32_e32 v5, v142
	v_pk_mul_f32 v[2:3], v[4:5], v[2:3]
	v_mov_b32_e32 v4, v141
	v_add_f32_e32 v41, v2, v3
	v_pk_mul_f32 v[2:3], v[0:1], v[170:171] op_sel_hi:[0,1]
	v_pk_mul_f32 v[2:3], v[2:3], v[172:173]
	v_mov_b32_e32 v5, v140
	v_pk_mul_f32 v[4:5], v[4:5], v[2:3]
	v_pk_mul_f32 v[2:3], v[140:141], v[2:3]
	v_mov_b32_e32 v42, v47
	v_add_f32_e32 v68, v2, v3
	v_pk_mul_f32 v[2:3], v[0:1], v[94:95] op_sel_hi:[0,1]
	v_pk_mul_f32 v[2:3], v[2:3], v[42:43]
	v_sub_f32_e32 v45, v4, v5
; __device__ __forceinline__ unsigned cvtpk(float lo, float hi) { unsigned r; asm volatile("v_cvt_pk_bf16_f32 %0, %1, %2" : "=v"(r) : "v"(lo), "v"(hi)); return r; }
; __device__ __forceinline__ int v_st(int k, int c) { const int kk = (k & ~0xC) | ((k & 4) << 1) | ((k & 8) >> 1); return ((kk >> 3) * 4 + (c >> 5)) * 512 + ((kk & 7) * 32 + (c & 31)) * 2; }
; __device__ __forceinline__ int v_rd_base(int lane) { return ((lane & 3) << 3) | (((lane >> 2) & 3) << 6) | (((lane >> 4) & 1) << 5) | (((lane >> 5) & 1) << 8); }
;     ...
;           x[d0][j] = y1 * cs - y2 * sn; x[d0 + 2][j] = y2 * cs + y1 * sn; } } }
; #pragma unroll
;     for (int d0 = 0; d0 < 8; ++d0) { u32x4 w = {cvtpk(x[d0][0], x[d0][1]), cvtpk(x[d0][2], x[d0][3]), cvtpk(x[d0][4], x[d0][5]), cvtpk(x[d0][6], x[d0][7])}; qr[d0] = *reinterpret_cast<bf16x8*>(&w); }
;   }
;   const int sr = tid >> 4, sc = (tid & 15) * 8, vst0 = v_st(sr, sc), vst1 = vst0 + 8192;
;   const int vb0 = (int)(uintptr_t)V_lds + v_rd_base(lane);
;   const int qrel = wid * QBLK + r32;
;   constexpr int SD = (MODE == 0) ? ATT_SD0 : 2;
;   struct { bf16x8 vs0, vs1, ks0, ks1; } sr_[SD];
;   const unsigned soff0 = (unsigned)(sr * (int)ldk + sc) * 2u, soff1 = soff0 + (unsigned)(32 * (int)ldk) * 2u;
;     ...
;   PLOAD(0); asm volatile("s_waitcnt vmcnt(0)" ::: "memory"); PWRITE(0); __syncthreads();
	v_pk_mul_f32 v[4:5], v[138:139], v[2:3]
	v_mov_b32_e32 v155, v24
	v_sub_f32_e32 v42, v4, v5
	v_mov_b32_e32 v4, v139
	v_mov_b32_e32 v5, v138
	v_pk_mul_f32 v[2:3], v[4:5], v[2:3]
	v_mov_b32_e32 v4, v133
	v_add_f32_e32 v43, v2, v3
	v_pk_mul_f32 v[2:3], v[0:1], v[150:151] op_sel_hi:[0,1]
	v_pk_mul_f32 v[2:3], v[2:3], v[154:155]
	v_mov_b32_e32 v5, v132
	v_pk_mul_f32 v[4:5], v[4:5], v[2:3]
	v_pk_mul_f32 v[2:3], v[132:133], v[2:3]
	v_mov_b32_e32 v24, v21
	v_add_f32_e32 v69, v2, v3
	v_pk_mul_f32 v[2:3], v[0:1], v[90:91] op_sel_hi:[0,1]
	v_mul_f32_e32 v119, 0.15915494, v118
	v_pk_mul_f32 v[2:3], v[2:3], v[24:25]
	v_sin_f32_e32 v118, v119
	v_cos_f32_e32 v119, v119
	v_sub_f32_e32 v47, v4, v5
	v_pk_mul_f32 v[4:5], v[124:125], v[2:3]
	v_mov_b32_e32 v131, v26
	v_sub_f32_e32 v21, v4, v5
	v_mov_b32_e32 v4, v125
	v_mov_b32_e32 v5, v124
	v_pk_mul_f32 v[2:3], v[4:5], v[2:3]
	v_pk_mul_f32 v[236:237], v[0:1], v[236:237] op_sel_hi:[0,1]
	v_add_f32_e32 v24, v2, v3
	v_pk_mul_f32 v[2:3], v[0:1], v[128:129] op_sel_hi:[0,1]
	v_pk_mul_f32 v[2:3], v[2:3], v[130:131]
	v_mov_b32_e32 v4, v119
	v_mov_b32_e32 v5, v118
	v_pk_mul_f32 v[0:1], v[0:1], v[134:135] op_sel_hi:[0,1]
	v_mov_b32_e32 v26, v23
	v_pk_mul_f32 v[4:5], v[4:5], v[2:3]
	v_pk_mul_f32 v[2:3], v[118:119], v[2:3]
	v_pk_mul_f32 v[0:1], v[0:1], v[26:27]
	v_sub_f32_e32 v4, v4, v5
	v_add_f32_e32 v5, v2, v3
	v_pk_mul_f32 v[2:3], v[120:121], v[0:1]
	v_pk_mul_f32 v[236:237], v[238:239], v[236:237]
	v_mov_b32_e32 v238, v97
	v_mov_b32_e32 v239, v96
	v_sub_f32_e32 v23, v2, v3
	v_mov_b32_e32 v2, v121
	v_mov_b32_e32 v3, v120
	v_pk_mul_f32 v[238:239], v[238:239], v[236:237]
	v_pk_mul_f32 v[0:1], v[2:3], v[0:1]
	v_sub_f32_e32 v16, v238, v239
	v_pk_mul_f32 v[96:97], v[96:97], v[236:237]
	v_add_f32_e32 v0, v0, v1
	v_cvt_pk_bf16_f32 v124, v16, v20
	v_cvt_pk_bf16_f32 v125, v12, v14
	v_cvt_pk_bf16_f32 v126, v10, v32
	v_cvt_pk_bf16_f32 v127, v8, v6
	v_cvt_pk_bf16_f32 v120, v44, v33
	v_ashrrev_i32_e32 v32, 4, v230
	v_lshlrev_b32_e32 v33, 3, v230
	s_movk_i32 s0, 0x2a00
	v_add_f32_e32 v18, v96, v97
	v_cvt_pk_bf16_f32 v121, v37, v35
	v_cvt_pk_bf16_f32 v122, v39, v17
	v_cvt_pk_bf16_f32 v123, v29, v19
	v_cvt_pk_bf16_f32 v116, v18, v22
	v_cvt_pk_bf16_f32 v117, v13, v15
	v_cvt_pk_bf16_f32 v118, v11, v34
	v_cvt_pk_bf16_f32 v119, v9, v7
	v_cvt_pk_bf16_f32 v112, v46, v36
	v_cvt_pk_bf16_f32 v113, v48, v38
	v_cvt_pk_bf16_f32 v114, v50, v28
	v_cvt_pk_bf16_f32 v115, v56, v30
	v_cvt_pk_bf16_f32 v108, v31, v58
	v_cvt_pk_bf16_f32 v109, v60, v62
	v_cvt_pk_bf16_f32 v110, v64, v49
	v_cvt_pk_bf16_f32 v111, v53, v51
	v_cvt_pk_bf16_f32 v104, v55, v40
	v_cvt_pk_bf16_f32 v105, v45, v42
	v_cvt_pk_bf16_f32 v106, v47, v21
	v_cvt_pk_bf16_f32 v107, v4, v23
	v_cvt_pk_bf16_f32 v100, v57, v59
	v_cvt_pk_bf16_f32 v101, v61, v63
	v_cvt_pk_bf16_f32 v102, v65, v52
	v_cvt_pk_bf16_f32 v103, v66, v54
	v_cvt_pk_bf16_f32 v96, v67, v41
	v_cvt_pk_bf16_f32 v97, v68, v43
	v_cvt_pk_bf16_f32 v98, v69, v24
	v_cvt_pk_bf16_f32 v99, v5, v0
	v_and_b32_e32 v34, 0x78, v33
	v_mul_lo_u32 v0, v32, s0
	v_or_b32_e32 v0, v0, v34
	v_lshlrev_b32_e32 v48, 1, v0
	v_mov_b32_e32 v49, v165
	v_lshl_add_u64 v[166:167], s[2:3], 0, v[48:49]
	v_add_co_u32_e32 v20, vcc, s75, v166
	global_load_dwordx4 v[0:3], v48, s[2:3] offset:2560
	s_nop 0
	v_addc_co_u32_e32 v21, vcc, 0, v167, vcc
	v_add_co_u32_e32 v24, vcc, s76, v166
	global_load_dwordx4 v[4:7], v[20:21], off offset:2560
	s_nop 0
	v_addc_co_u32_e32 v25, vcc, 0, v167, vcc
	global_load_dwordx4 v[8:11], v[24:25], off offset:2560
	v_add_co_u32_e32 v28, vcc, s77, v166
	v_and_b32_e32 v35, 0xfffff0, v32
	s_nop 0
	v_addc_co_u32_e32 v29, vcc, 0, v167, vcc
	global_load_dwordx4 v[12:15], v[28:29], off offset:2560
	global_load_dwordx4 v[16:19], v48, s[2:3] offset:2048
	s_nop 0
	global_load_dwordx4 v[20:23], v[20:21], off offset:2048
	s_nop 0
	global_load_dwordx4 v[24:27], v[24:25], off offset:2048
	s_nop 0
	global_load_dwordx4 v[28:31], v[28:29], off offset:2048
	v_lshlrev_b32_e32 v36, 1, v32
	v_and_or_b32 v35, v36, 8, v35
	v_lshrrev_b32_e32 v35, 1, v35
	v_bfe_u32 v33, v33, 5, 2
	s_and_b32 s0, s29, 0x3fffffc0
	v_lshrrev_b32_e32 v36, 1, v32
	v_or_b32_e32 v33, v35, v33
	v_and_b32_e32 v35, 3, v32
	v_lshlrev_b32_e32 v34, 1, v34
	s_lshl_b32 s0, s0, 2
	v_and_or_b32 v35, v36, 4, v35
	v_and_b32_e32 v36, 48, v34
	s_add_i32 s39, s0, 0
	v_lshl_or_b32 v35, v35, 6, v36
	s_add_i32 s39, s39, 0x20400
	v_lshl_or_b32 v162, v33, 9, v35
	s_add_i32 s1, 0, 0x10000
	v_add_u32_e32 v33, 0x2000, v162
	s_cmp_lg_u32 s1, -1
	v_add_u32_e32 v35, s1, v162
	s_cselect_b32 s0, s1, 0
	s_waitcnt vmcnt(0)
	v_lshlrev_b32_e32 v50, 4, v230
	v_and_b32_e32 v54, 63, v230
	s_mov_b32 s44, 0
	s_mov_b32 s45, s44
	s_mov_b32 s46, s44
	s_mov_b32 s47, s44
	s_mov_b32 s48, s44
	s_mov_b32 s49, s44
	s_mov_b32 s50, s44
	s_mov_b32 s51, s44
	s_mov_b32 s52, s44
	s_mov_b32 s53, s44
	s_mov_b32 s54, s44
	s_mov_b32 s55, s44
	s_mov_b32 s56, s44
	s_mov_b32 s57, s44
	s_mov_b32 s58, s44
	s_mov_b32 s59, s44
	v_cmp_gt_u32_e64 s[2:3], 32, v54
	v_lshl_add_u32 v168, v228, 2, s39
	v_mov_b32_e32 v169, 0
	s_waitcnt vmcnt(7)
	ds_write_b128 v35, v[0:3]
	v_add_u32_e32 v0, s1, v33
	s_add_i32 s1, 0, 0x14000
	v_and_b32_e32 v1, 0x70, v230
	s_waitcnt vmcnt(6)
	ds_write_b128 v0, v[4:7]
	v_add_u32_e32 v0, s1, v162
	s_waitcnt vmcnt(5)
	ds_write_b128 v0, v[8:11]
	v_add_u32_e32 v0, s1, v33
	s_waitcnt vmcnt(4)
	ds_write_b128 v0, v[12:15]
	v_lshlrev_b32_e32 v0, 8, v32
	v_bitop3_b32 v0, v34, v0, v1 bitop3:0xde
	v_lshlrev_b32_e32 v8, 8, v228
	v_and_b32_e32 v9, 0x70, v50
	v_add_u32_e32 v181, 0, v0
	v_bitop3_b32 v0, v164, v8, v9 bitop3:0xde
	v_add_u32_e32 v172, 0, v0
	s_waitcnt vmcnt(3)
	ds_write_b128 v181, v[16:19]
	s_waitcnt vmcnt(2)
	ds_write_b128 v181, v[20:23] offset:8192
	s_waitcnt vmcnt(1)
	ds_write_b128 v181, v[24:27] offset:16384
	s_waitcnt vmcnt(0)
	ds_write_b128 v181, v[28:31] offset:24576
	s_waitcnt lgkmcnt(0)
	s_barrier
; __device__ __forceinline__ void partialSM(f32x16& p0, f32x16& p1, float& m_reg, float& mn, float& alpha) {
;   constexpr float C = SCALE * 1.4426950408889634f;
;   float pmax = p0[0];
; #pragma unroll
;   for (int r = 1; r < 16; ++r) pmax = fmaxf(pmax, p0[r]);
; #pragma unroll
;   for (int r = 0; r < 16; ++r) pmax = fmaxf(pmax, p1[r]);
;   { auto rr = __builtin_amdgcn_permlane32_swap(__float_as_uint(pmax), __float_as_uint(pmax), false, false);
;     pmax = fmaxf(__uint_as_float(rr[0]), __uint_as_float(rr[1])); }
;   if (__builtin_expect(__all(pmax - m_reg <= THR / SCALE), 1)) { mn = m_reg; alpha = 1.f; }
;   else { mn = fmaxf(m_reg, pmax); alpha = __builtin_amdgcn_exp2f((m_reg - mn) * C); m_reg = mn; }
;   float mnC = -mn * C;
; #pragma unroll
;   for (int r = 0; r < 16; ++r) p0[r] = fmaf(p0[r], C, mnC);
; #pragma unroll
;   for (int r = 0; r < 16; ++r) p1[r] = fmaf(p1[r], C, mnC);
; #pragma unroll
;   for (int r = 0; r < 16; ++r) p0[r] = __builtin_amdgcn_exp2f(p0[r]);
; }
; __device__ __forceinline__ void qkt(f32x16& p0, f32x16& p1, const bf16* Ks, const bf16x8* qr, int r32, int hi) {
;   p0 = f32x16{}; p1 = f32x16{};
; #pragma unroll
;   for (int d0 = 0; d0 < 8; ++d0) { int cb = (d0 * 16 + hi * 8) * 2;
;     bf16x8 b0 = *reinterpret_cast<const bf16x8*>((const char*)Ks + KSWZ(r32, cb));
;     bf16x8 b1 = *reinterpret_cast<const bf16x8*>((const char*)Ks + KSWZ(32 + r32, cb));
;     p0 = __builtin_amdgcn_mfma_f32_32x32x16_bf16(b0, qr[d0], p0, 0, 0, 0);
;     p1 = __builtin_amdgcn_mfma_f32_32x32x16_bf16(b1, qr[d0], p1, 0, 0, 0); }
; }
	ds_read_b128 v[0:3], v172
	ds_read_b128 v[4:7], v172 offset:8192
	s_waitcnt lgkmcnt(1)
	v_mfma_f32_32x32x16_bf16 v[32:47], v[0:3], v[124:127], 0
	v_or_b32_e32 v0, 32, v164
	v_bitop3_b32 v0, v0, v8, v9 bitop3:0xde
	v_add_u32_e32 v173, 0, v0
	v_lshlrev_b32_e32 v10, 3, v54
	v_and_b32_e32 v11, 0xc0, v50
	s_waitcnt lgkmcnt(0)
	v_mfma_f32_32x32x16_bf16 v[16:31], v[4:7], v[124:127], 0
	ds_read_b128 v[0:3], v173
	ds_read_b128 v[4:7], v173 offset:8192
	s_waitcnt lgkmcnt(1)
	v_mfma_f32_32x32x16_bf16 v[32:47], v[0:3], v[120:123], v[32:47]
	v_or_b32_e32 v0, 64, v164
	v_bitop3_b32 v0, v0, v8, v9 bitop3:0xde
	v_add_u32_e32 v174, 0, v0
	s_waitcnt lgkmcnt(0)
	v_mfma_f32_32x32x16_bf16 v[16:31], v[4:7], v[120:123], v[16:31]
	ds_read_b128 v[0:3], v174
	ds_read_b128 v[4:7], v174 offset:8192
	s_waitcnt lgkmcnt(1)
	v_mfma_f32_32x32x16_bf16 v[32:47], v[0:3], v[116:119], v[32:47]
	v_or_b32_e32 v0, 0x60, v164
	v_bitop3_b32 v0, v0, v8, v9 bitop3:0xde
	v_add_u32_e32 v175, 0, v0
	s_waitcnt lgkmcnt(0)
	v_mfma_f32_32x32x16_bf16 v[16:31], v[4:7], v[116:119], v[16:31]
	ds_read_b128 v[0:3], v175
	ds_read_b128 v[4:7], v175 offset:8192
	s_waitcnt lgkmcnt(1)
	v_mfma_f32_32x32x16_bf16 v[32:47], v[0:3], v[112:115], v[32:47]
	v_or_b32_e32 v0, 0x80, v164
	v_bitop3_b32 v0, v0, v8, v9 bitop3:0xde
	v_add_u32_e32 v176, 0, v0
	s_waitcnt lgkmcnt(0)
	v_mfma_f32_32x32x16_bf16 v[16:31], v[4:7], v[112:115], v[16:31]
	ds_read_b128 v[0:3], v176
	ds_read_b128 v[4:7], v176 offset:8192
	s_waitcnt lgkmcnt(1)
	v_mfma_f32_32x32x16_bf16 v[32:47], v[0:3], v[108:111], v[32:47]
	v_or_b32_e32 v0, 0xa0, v164
	v_bitop3_b32 v0, v0, v8, v9 bitop3:0xde
	v_add_u32_e32 v177, 0, v0
	ds_read_b128 v[0:3], v177
	s_waitcnt lgkmcnt(1)
	v_mfma_f32_32x32x16_bf16 v[16:31], v[4:7], v[108:111], v[16:31]
	ds_read_b128 v[4:7], v177 offset:8192
	s_waitcnt lgkmcnt(1)
	v_mfma_f32_32x32x16_bf16 v[32:47], v[0:3], v[104:107], v[32:47]
	v_or_b32_e32 v0, 0xc0, v164
	v_bitop3_b32 v0, v0, v8, v9 bitop3:0xde
	v_add_u32_e32 v178, 0, v0
	ds_read_b128 v[0:3], v178
	s_waitcnt lgkmcnt(1)
	v_mfma_f32_32x32x16_bf16 v[16:31], v[4:7], v[104:107], v[16:31]
	v_lshlrev_b32_e32 v5, 1, v230
	v_and_or_b32 v4, v10, 24, v11
	v_and_b32_e32 v5, 32, v5
	v_and_b32_e32 v6, 0x100, v10
	v_or3_b32 v55, v4, v5, v6
	ds_read_b128 v[4:7], v178 offset:8192
	v_add_u32_e32 v182, s0, v55
	s_waitcnt lgkmcnt(1)
	v_mfma_f32_32x32x16_bf16 v[32:47], v[0:3], v[100:103], v[32:47]
	v_or_b32_e32 v0, 0xe0, v164
	v_bitop3_b32 v0, v0, v8, v9 bitop3:0xde
	v_add_u32_e32 v179, 0, v0
	ds_read_b128 v[0:3], v179
	ds_read_b128 v[50:53], v179 offset:8192
	s_waitcnt lgkmcnt(2)
	v_mfma_f32_32x32x16_bf16 v[16:31], v[4:7], v[100:103], v[16:31]
	s_waitcnt lgkmcnt(1)
	v_mfma_f32_32x32x16_bf16 v[32:47], v[0:3], v[96:99], v[32:47]
	v_mov_b64_e32 v[0:1], s[44:45]
	v_mov_b64_e32 v[14:15], s[58:59]
	v_mov_b64_e32 v[2:3], s[46:47]
	v_mov_b64_e32 v[4:5], s[48:49]
	v_mov_b64_e32 v[6:7], s[50:51]
	v_mov_b64_e32 v[8:9], s[52:53]
	v_mov_b64_e32 v[10:11], s[54:55]
	s_waitcnt lgkmcnt(0)
	v_mfma_f32_32x32x16_bf16 v[16:31], v[50:53], v[96:99], v[16:31]
	s_nop 2
	s_add_i32 s1, s0, 0x4000
	v_add_u32_e32 v180, s1, v55
	s_add_i32 s1, s0, 0x8000
	s_add_i32 s0, s0, 0xc000
	v_exp_f32_e32 v64, v32
	v_exp_f32_e32 v65, v33
	v_exp_f32_e32 v66, v34
	v_exp_f32_e32 v67, v35
	v_exp_f32_e32 v68, v36
	v_exp_f32_e32 v69, v37
	v_exp_f32_e32 v70, v38
	v_exp_f32_e32 v71, v39
	v_exp_f32_e32 v72, v40
	v_exp_f32_e32 v73, v41
	v_exp_f32_e32 v74, v42
	v_exp_f32_e32 v75, v43
	v_exp_f32_e32 v76, v44
	v_exp_f32_e32 v77, v45
	v_exp_f32_e32 v78, v46
	v_exp_f32_e32 v79, v47
	v_add_u32_e32 v170, s0, v55
	s_or_b32 s0, s28, s4
	v_exp_f32_e32 v80, v16
	v_exp_f32_e32 v81, v17
	v_exp_f32_e32 v82, v18
	v_exp_f32_e32 v83, v19
	v_exp_f32_e32 v84, v20
	v_exp_f32_e32 v85, v21
	v_exp_f32_e32 v86, v22
	v_exp_f32_e32 v87, v23
	v_exp_f32_e32 v88, v24
	v_exp_f32_e32 v89, v25
	v_exp_f32_e32 v90, v26
	v_exp_f32_e32 v91, v27
	v_exp_f32_e32 v92, v28
	v_exp_f32_e32 v93, v29
	v_exp_f32_e32 v94, v30
	v_exp_f32_e32 v95, v31
	s_add_u32 s0, s69, s0
	v_add_u32_e32 v171, s1, v55
	s_addc_u32 s1, s71, s5
	v_mov_b64_e32 v[12:13], s[56:57]
	v_lshl_add_u64 v[160:161], s[0:1], 0, v[48:49]
	v_mov_b64_e32 v[62:63], v[14:15]
	v_mov_b64_e32 v[46:47], v[14:15]
	v_mov_b64_e32 v[30:31], v[14:15]
	v_mov_b64_e32 v[60:61], v[12:13]
	v_mov_b64_e32 v[58:59], v[10:11]
	v_mov_b64_e32 v[56:57], v[8:9]
	v_mov_b64_e32 v[54:55], v[6:7]
	v_mov_b64_e32 v[52:53], v[4:5]
	v_mov_b64_e32 v[50:51], v[2:3]
	v_mov_b64_e32 v[48:49], v[0:1]
	v_mov_b64_e32 v[44:45], v[12:13]
	v_mov_b64_e32 v[42:43], v[10:11]
	v_mov_b64_e32 v[40:41], v[8:9]
	v_mov_b64_e32 v[38:39], v[6:7]
	v_mov_b64_e32 v[36:37], v[4:5]
	v_mov_b64_e32 v[34:35], v[2:3]
	v_mov_b64_e32 v[32:33], v[0:1]
	v_mov_b64_e32 v[28:29], v[12:13]
	v_mov_b64_e32 v[26:27], v[10:11]
	v_mov_b64_e32 v[24:25], v[8:9]
	v_mov_b64_e32 v[22:23], v[6:7]
	v_mov_b64_e32 v[20:21], v[4:5]
	v_mov_b64_e32 v[18:19], v[2:3]
	v_mov_b64_e32 v[16:17], v[0:1]
.LBB0_486:
	v_add_u32_e32 v180, 0x10000, v162
	v_mov_b32_e32 v216, v160
	v_mov_b32_e32 v217, v161
	v_add_co_u32_e32 v166, vcc, s75, v160
	s_nop 1
	v_addc_co_u32_e32 v167, vcc, 0, v161, vcc
	s_mov_b32 s0, 0x150000
	s_mov_b32 s1, 0
	v_mov_b32_e32 v169, 0
	v_mov_b32_e32 v219, 0
	v_mov_b32_e32 v222, 0
	v_mov_b32_e32 v254, 0
	s_mov_b32 s44, 0
; __device__ __forceinline__ void finishSM(f32x16& p0, f32x16& p1, float alpha, float& l_reg, bf16x8& pa0, bf16x8& pa1, bf16x8& pa2, bf16x8& pa3) {
; #pragma unroll
;   for (int r = 0; r < 16; ++r) p1[r] = __builtin_amdgcn_exp2f(p1[r]);
;   float ps = 0;
; #pragma unroll
;   for (int r = 0; r < 16; ++r) ps += p0[r];
; #pragma unroll
;   for (int r = 0; r < 16; ++r) ps += p1[r];
;   { auto rr = __builtin_amdgcn_permlane32_swap(__float_as_uint(ps), __float_as_uint(ps), false, false);
;     ps = __uint_as_float(rr[0]) + __uint_as_float(rr[1]); }
;   l_reg = l_reg * alpha + ps;
;     ...
;   PK4(p0, 0, pa0); PK4(p0, 8, pa1); PK4(p1, 0, pa2); PK4(p1, 8, pa3);
;     ...
; }
; __device__ __forceinline__ void qkt(f32x16& p0, f32x16& p1, const bf16* Ks, const bf16x8* qr, int r32, int hi) {
;   p0 = f32x16{}; p1 = f32x16{};
; #pragma unroll
;   for (int d0 = 0; d0 < 8; ++d0) { int cb = (d0 * 16 + hi * 8) * 2;
;     bf16x8 b0 = *reinterpret_cast<const bf16x8*>((const char*)Ks + KSWZ(r32, cb));
;     bf16x8 b1 = *reinterpret_cast<const bf16x8*>((const char*)Ks + KSWZ(32 + r32, cb));
;     p0 = __builtin_amdgcn_mfma_f32_32x32x16_bf16(b0, qr[d0], p0, 0, 0, 0);
;     p1 = __builtin_amdgcn_mfma_f32_32x32x16_bf16(b1, qr[d0], p1, 0, 0, 0); }
; }
; __device__ __forceinline__ int v_st(int k, int c) { const int kk = (k & ~0xC) | ((k & 4) << 1) | ((k & 8) >> 1); return ((kk >> 3) * 4 + (c >> 5)) * 512 + ((kk & 7) * 32 + (c & 31)) * 2; }
; __device__ __forceinline__ int v_rd_base(int lane) { return ((lane & 3) << 3) | (((lane >> 2) & 3) << 6) | (((lane >> 4) & 1) << 5) | (((lane >> 5) & 1) << 8); }
; template <int OFF> __device__ __forceinline__ s16x4 tr_read(int vb) {
;   s16x4 r; asm volatile("ds_read_b64_tr_b16 %0, %1 offset:%2" : "=&v"(r) : "v"(vb), "i"(OFF) : "memory"); return r;
; }
; template <int D0> __device__ __forceinline__ void pv_one(f32x16& od, int vb, bf16x8 pa0, bf16x8 pa1, bf16x8 pa2, bf16x8 pa3) {
;   const s16x4 l0 = tr_read<v_rd_off(D0, 0, 0)>(vb), h0 = tr_read<v_rd_off(D0, 0, 1)>(vb), l1 = tr_read<v_rd_off(D0, 1, 0)>(vb), h1 = tr_read<v_rd_off(D0, 1, 1)>(vb);
;   const s16x4 l2 = tr_read<v_rd_off(D0, 2, 0)>(vb), h2 = tr_read<v_rd_off(D0, 2, 1)>(vb), l3 = tr_read<v_rd_off(D0, 3, 0)>(vb), h3 = tr_read<v_rd_off(D0, 3, 1)>(vb);
;   asm volatile("s_waitcnt lgkmcnt(0)" ::: "memory"); SBAR();
;     ...
;   od = __builtin_amdgcn_mfma_f32_32x32x16_bf16(pa0, PK(l0, h0), od, 0, 0, 0);
.Ldense_loop:
	global_load_dwordx4 v[246:249], v[216:217], off
	global_load_dwordx4 v[176:179], v[216:217], off offset:512
	global_load_dwordx4 v[250:253], v[166:167], off
	global_load_dwordx4 v[160:163], v[166:167], off offset:512
	v_lshl_add_u64 v[216:217], v[216:217], 0, s[0:1]
	v_lshl_add_u64 v[166:167], v[166:167], 0, s[0:1]
	ds_read_b128 v[200:203], v172 offset:16384
	ds_read_b128 v[204:207], v172 offset:24576
	ds_read_b128 v[208:211], v173 offset:16384
	ds_read_b128 v[212:215], v173 offset:24576
	ds_read_b128 v[230:233], v174 offset:16384
	ds_read_b128 v[234:237], v174 offset:24576
	ds_read_b128 v[238:241], v175 offset:16384
	ds_read_b128 v[242:245], v175 offset:24576
	s_waitcnt lgkmcnt(7)
	v_mfma_f32_32x32x16_bf16 v[128:143], v[200:203], v[124:127], 0
	ds_read_b128 v[200:203], v172 offset:16512
	v_cvt_pk_bf16_f32 v184, v64, v65
	v_add_f32_e32 v169, v169, v64
	v_add_f32_e32 v219, v219, v65
	s_waitcnt lgkmcnt(7)
	v_mfma_f32_32x32x16_bf16 v[144:159], v[204:207], v[124:127], 0
	ds_read_b128 v[204:207], v172 offset:24704
	v_cvt_pk_bf16_f32 v185, v66, v67
	v_add_f32_e32 v222, v222, v66
	v_add_f32_e32 v254, v254, v67
	s_waitcnt lgkmcnt(7)
	v_mfma_f32_32x32x16_bf16 v[128:143], v[208:211], v[120:123], v[128:143]
	ds_read_b128 v[208:211], v173 offset:16512
	v_cvt_pk_bf16_f32 v186, v68, v69
	v_add_f32_e32 v169, v169, v68
	v_add_f32_e32 v219, v219, v69
	s_waitcnt lgkmcnt(7)
	v_mfma_f32_32x32x16_bf16 v[144:159], v[212:215], v[120:123], v[144:159]
	ds_read_b128 v[212:215], v173 offset:24704
	v_cvt_pk_bf16_f32 v187, v70, v71
	v_add_f32_e32 v222, v222, v70
	v_add_f32_e32 v254, v254, v71
	s_waitcnt lgkmcnt(7)
	v_mfma_f32_32x32x16_bf16 v[128:143], v[230:233], v[116:119], v[128:143]
	ds_read_b128 v[230:233], v174 offset:16512
	v_cvt_pk_bf16_f32 v188, v72, v73
	v_add_f32_e32 v169, v169, v72
	v_add_f32_e32 v219, v219, v73
	v_permlane32_swap_b32_e32 v184, v186
	s_waitcnt lgkmcnt(7)
	v_mfma_f32_32x32x16_bf16 v[144:159], v[234:237], v[116:119], v[144:159]
	ds_read_b128 v[234:237], v174 offset:24704
	v_cvt_pk_bf16_f32 v189, v74, v75
	v_add_f32_e32 v222, v222, v74
	v_add_f32_e32 v254, v254, v75
	v_permlane32_swap_b32_e32 v185, v187
	s_waitcnt lgkmcnt(7)
	v_mfma_f32_32x32x16_bf16 v[128:143], v[238:241], v[112:115], v[128:143]
	ds_read_b128 v[238:241], v175 offset:16512
	v_cvt_pk_bf16_f32 v190, v76, v77
	v_add_f32_e32 v169, v169, v76
	v_add_f32_e32 v219, v219, v77
	s_waitcnt lgkmcnt(7)
	v_mfma_f32_32x32x16_bf16 v[144:159], v[242:245], v[112:115], v[144:159]
	ds_read_b128 v[242:245], v175 offset:24704
	v_cvt_pk_bf16_f32 v191, v78, v79
	v_add_f32_e32 v222, v222, v78
	v_add_f32_e32 v254, v254, v79
	s_waitcnt lgkmcnt(7)
	v_mfma_f32_32x32x16_bf16 v[128:143], v[200:203], v[108:111], v[128:143]
	v_cvt_pk_bf16_f32 v192, v80, v81
	v_add_f32_e32 v169, v169, v80
	v_add_f32_e32 v219, v219, v81
	v_permlane32_swap_b32_e32 v188, v190
	s_waitcnt lgkmcnt(6)
	v_mfma_f32_32x32x16_bf16 v[144:159], v[204:207], v[108:111], v[144:159]
	v_cvt_pk_bf16_f32 v193, v82, v83
	v_add_f32_e32 v222, v222, v82
	v_add_f32_e32 v254, v254, v83
	v_permlane32_swap_b32_e32 v189, v191
	s_waitcnt lgkmcnt(5)
	v_mfma_f32_32x32x16_bf16 v[128:143], v[208:211], v[104:107], v[128:143]
	ds_read_b64_tr_b16 v[200:201], v182 offset:0
	ds_read_b64_tr_b16 v[202:203], v182 offset:2048
	v_cvt_pk_bf16_f32 v194, v84, v85
	v_add_f32_e32 v169, v169, v84
	v_add_f32_e32 v219, v219, v85
	s_waitcnt lgkmcnt(6)
	v_mfma_f32_32x32x16_bf16 v[144:159], v[212:215], v[104:107], v[144:159]
	ds_read_b64_tr_b16 v[204:205], v182 offset:4096
	ds_read_b64_tr_b16 v[206:207], v182 offset:6144
	v_cvt_pk_bf16_f32 v195, v86, v87
	v_add_f32_e32 v222, v222, v86
	v_add_f32_e32 v254, v254, v87
	s_waitcnt lgkmcnt(7)
	v_mfma_f32_32x32x16_bf16 v[128:143], v[230:233], v[100:103], v[128:143]
	ds_read_b64_tr_b16 v[208:209], v182 offset:8192
	ds_read_b64_tr_b16 v[210:211], v182 offset:10240
	v_cvt_pk_bf16_f32 v196, v88, v89
	v_add_f32_e32 v169, v169, v88
	v_add_f32_e32 v219, v219, v89
	v_permlane32_swap_b32_e32 v192, v194
	s_waitcnt lgkmcnt(8)
	v_mfma_f32_32x32x16_bf16 v[144:159], v[234:237], v[100:103], v[144:159]
	ds_read_b64_tr_b16 v[212:213], v182 offset:12288
	ds_read_b64_tr_b16 v[214:215], v182 offset:14336
	v_cvt_pk_bf16_f32 v197, v90, v91
	v_add_f32_e32 v222, v222, v90
	v_add_f32_e32 v254, v254, v91
	v_permlane32_swap_b32_e32 v193, v195
	s_waitcnt lgkmcnt(9)
	v_mfma_f32_32x32x16_bf16 v[128:143], v[238:241], v[96:99], v[128:143]
	ds_read_b64_tr_b16 v[230:231], v182 offset:512
	ds_read_b64_tr_b16 v[232:233], v182 offset:2560
	v_cvt_pk_bf16_f32 v198, v92, v93
	v_add_f32_e32 v169, v169, v92
	v_add_f32_e32 v219, v219, v93
	s_waitcnt lgkmcnt(10)
	v_mfma_f32_32x32x16_bf16 v[144:159], v[242:245], v[96:99], v[144:159]
	ds_read_b64_tr_b16 v[234:235], v182 offset:4608
	ds_read_b64_tr_b16 v[236:237], v182 offset:6656
	v_cvt_pk_bf16_f32 v199, v94, v95
	v_add_f32_e32 v222, v222, v94
	v_add_f32_e32 v254, v254, v95
	v_permlane32_swap_b32_e32 v196, v198
	v_permlane32_swap_b32_e32 v197, v199
	s_waitcnt lgkmcnt(10)
	v_mfma_f32_32x32x16_bf16 v[0:15], v[184:187], v[200:203], v[0:15]
	ds_read_b64_tr_b16 v[238:239], v182 offset:8704
	ds_read_b64_tr_b16 v[240:241], v182 offset:10752
	v_exp_f32_e32 v128, v128
	v_exp_f32_e32 v129, v129
	s_waitcnt lgkmcnt(10)
	v_mfma_f32_32x32x16_bf16 v[0:15], v[188:191], v[204:207], v[0:15]
	ds_read_b64_tr_b16 v[242:243], v182 offset:12800
	ds_read_b64_tr_b16 v[244:245], v182 offset:14848
	v_exp_f32_e32 v130, v130
	v_exp_f32_e32 v131, v131
	s_waitcnt lgkmcnt(10)
	v_mfma_f32_32x32x16_bf16 v[0:15], v[192:195], v[208:211], v[0:15]
	ds_read_b64_tr_b16 v[200:201], v182 offset:1024
	ds_read_b64_tr_b16 v[202:203], v182 offset:3072
	v_exp_f32_e32 v132, v132
	v_exp_f32_e32 v133, v133
	s_waitcnt lgkmcnt(10)
; __device__ __forceinline__ void finishSM(f32x16& p0, f32x16& p1, float alpha, float& l_reg, bf16x8& pa0, bf16x8& pa1, bf16x8& pa2, bf16x8& pa3) {
; #pragma unroll
;   for (int r = 0; r < 16; ++r) p1[r] = __builtin_amdgcn_exp2f(p1[r]);
;   float ps = 0;
; #pragma unroll
;   for (int r = 0; r < 16; ++r) ps += p0[r];
; #pragma unroll
;   for (int r = 0; r < 16; ++r) ps += p1[r];
;   { auto rr = __builtin_amdgcn_permlane32_swap(__float_as_uint(ps), __float_as_uint(ps), false, false);
;     ps = __uint_as_float(rr[0]) + __uint_as_float(rr[1]); }
;   l_reg = l_reg * alpha + ps;
;     ...
;   PK4(p0, 0, pa0); PK4(p0, 8, pa1); PK4(p1, 0, pa2); PK4(p1, 8, pa3);
;     ...
; }
; __device__ __forceinline__ void qkt(f32x16& p0, f32x16& p1, const bf16* Ks, const bf16x8* qr, int r32, int hi) {
;   p0 = f32x16{}; p1 = f32x16{};
; #pragma unroll
;   for (int d0 = 0; d0 < 8; ++d0) { int cb = (d0 * 16 + hi * 8) * 2;
;     bf16x8 b0 = *reinterpret_cast<const bf16x8*>((const char*)Ks + KSWZ(r32, cb));
;     bf16x8 b1 = *reinterpret_cast<const bf16x8*>((const char*)Ks + KSWZ(32 + r32, cb));
;     p0 = __builtin_amdgcn_mfma_f32_32x32x16_bf16(b0, qr[d0], p0, 0, 0, 0);
;     p1 = __builtin_amdgcn_mfma_f32_32x32x16_bf16(b1, qr[d0], p1, 0, 0, 0); }
; }
; __device__ __forceinline__ int v_st(int k, int c) { const int kk = (k & ~0xC) | ((k & 4) << 1) | ((k & 8) >> 1); return ((kk >> 3) * 4 + (c >> 5)) * 512 + ((kk & 7) * 32 + (c & 31)) * 2; }
; __device__ __forceinline__ int v_rd_base(int lane) { return ((lane & 3) << 3) | (((lane >> 2) & 3) << 6) | (((lane >> 4) & 1) << 5) | (((lane >> 5) & 1) << 8); }
; template <int OFF> __device__ __forceinline__ s16x4 tr_read(int vb) {
;   s16x4 r; asm volatile("ds_read_b64_tr_b16 %0, %1 offset:%2" : "=&v"(r) : "v"(vb), "i"(OFF) : "memory"); return r;
; }
; template <int D0> __device__ __forceinline__ void pv_one(f32x16& od, int vb, bf16x8 pa0, bf16x8 pa1, bf16x8 pa2, bf16x8 pa3) {
;   const s16x4 l0 = tr_read<v_rd_off(D0, 0, 0)>(vb), h0 = tr_read<v_rd_off(D0, 0, 1)>(vb), l1 = tr_read<v_rd_off(D0, 1, 0)>(vb), h1 = tr_read<v_rd_off(D0, 1, 1)>(vb);
;   const s16x4 l2 = tr_read<v_rd_off(D0, 2, 0)>(vb), h2 = tr_read<v_rd_off(D0, 2, 1)>(vb), l3 = tr_read<v_rd_off(D0, 3, 0)>(vb), h3 = tr_read<v_rd_off(D0, 3, 1)>(vb);
;   asm volatile("s_waitcnt lgkmcnt(0)" ::: "memory"); SBAR();
;     ...
;   od = __builtin_amdgcn_mfma_f32_32x32x16_bf16(pa0, PK(l0, h0), od, 0, 0, 0);
	v_mfma_f32_32x32x16_bf16 v[0:15], v[196:199], v[212:215], v[0:15]
	ds_read_b64_tr_b16 v[204:205], v182 offset:5120
	ds_read_b64_tr_b16 v[206:207], v182 offset:7168
	v_exp_f32_e32 v134, v134
	v_exp_f32_e32 v135, v135
	s_waitcnt lgkmcnt(10)
	v_mfma_f32_32x32x16_bf16 v[48:63], v[184:187], v[230:233], v[48:63]
	ds_read_b64_tr_b16 v[208:209], v182 offset:9216
	ds_read_b64_tr_b16 v[210:211], v182 offset:11264
	v_exp_f32_e32 v136, v136
	v_exp_f32_e32 v137, v137
	s_waitcnt lgkmcnt(10)
	v_mfma_f32_32x32x16_bf16 v[48:63], v[188:191], v[234:237], v[48:63]
	ds_read_b64_tr_b16 v[212:213], v182 offset:13312
	ds_read_b64_tr_b16 v[214:215], v182 offset:15360
	v_exp_f32_e32 v138, v138
	v_exp_f32_e32 v139, v139
	s_waitcnt lgkmcnt(10)
	v_mfma_f32_32x32x16_bf16 v[48:63], v[192:195], v[238:241], v[48:63]
	ds_read_b64_tr_b16 v[230:231], v182 offset:1536
	ds_read_b64_tr_b16 v[232:233], v182 offset:3584
	v_exp_f32_e32 v140, v140
	v_exp_f32_e32 v141, v141
	s_waitcnt lgkmcnt(10)
	v_mfma_f32_32x32x16_bf16 v[48:63], v[196:199], v[242:245], v[48:63]
	ds_read_b64_tr_b16 v[234:235], v182 offset:5632
	ds_read_b64_tr_b16 v[236:237], v182 offset:7680
	v_exp_f32_e32 v142, v142
	v_exp_f32_e32 v143, v143
	s_waitcnt lgkmcnt(10)
	v_mfma_f32_32x32x16_bf16 v[32:47], v[184:187], v[200:203], v[32:47]
	ds_read_b64_tr_b16 v[238:239], v182 offset:9728
	ds_read_b64_tr_b16 v[240:241], v182 offset:11776
	v_exp_f32_e32 v144, v144
	v_exp_f32_e32 v145, v145
	s_waitcnt lgkmcnt(10)
	v_mfma_f32_32x32x16_bf16 v[32:47], v[188:191], v[204:207], v[32:47]
	ds_read_b64_tr_b16 v[242:243], v182 offset:13824
	ds_read_b64_tr_b16 v[244:245], v182 offset:15872
	v_exp_f32_e32 v146, v146
	v_exp_f32_e32 v147, v147
	s_waitcnt lgkmcnt(10)
	v_mfma_f32_32x32x16_bf16 v[32:47], v[192:195], v[208:211], v[32:47]
	v_exp_f32_e32 v148, v148
	v_exp_f32_e32 v149, v149
	s_waitcnt lgkmcnt(8)
	v_mfma_f32_32x32x16_bf16 v[32:47], v[196:199], v[212:215], v[32:47]
	v_exp_f32_e32 v150, v150
	v_exp_f32_e32 v151, v151
	s_waitcnt vmcnt(0)
	ds_write_b128 v181, v[246:249] offset:32768
	ds_write_b128 v181, v[250:253] offset:40960
	ds_write_b128 v180, v[176:179] offset:32768
	ds_write_b128 v180, v[160:163] offset:40960
	s_waitcnt lgkmcnt(10)
	v_mfma_f32_32x32x16_bf16 v[16:31], v[184:187], v[230:233], v[16:31]
	v_exp_f32_e32 v152, v152
	v_exp_f32_e32 v153, v153
	s_waitcnt lgkmcnt(8)
	v_mfma_f32_32x32x16_bf16 v[16:31], v[188:191], v[234:237], v[16:31]
	v_exp_f32_e32 v154, v154
	v_exp_f32_e32 v155, v155
	s_waitcnt lgkmcnt(6)
	v_mfma_f32_32x32x16_bf16 v[16:31], v[192:195], v[238:241], v[16:31]
	v_exp_f32_e32 v156, v156
	v_exp_f32_e32 v157, v157
	s_waitcnt lgkmcnt(4)
	v_mfma_f32_32x32x16_bf16 v[16:31], v[196:199], v[242:245], v[16:31]
	v_exp_f32_e32 v158, v158
	v_exp_f32_e32 v159, v159
	s_waitcnt lgkmcnt(0)
	s_barrier
	global_load_dwordx4 v[246:249], v[216:217], off
	global_load_dwordx4 v[176:179], v[216:217], off offset:512
	global_load_dwordx4 v[250:253], v[166:167], off
	global_load_dwordx4 v[160:163], v[166:167], off offset:512
	v_lshl_add_u64 v[216:217], v[216:217], 0, s[0:1]
	v_lshl_add_u64 v[166:167], v[166:167], 0, s[0:1]
	ds_read_b128 v[200:203], v172 offset:32768
	ds_read_b128 v[204:207], v172 offset:40960
	ds_read_b128 v[208:211], v173 offset:32768
	ds_read_b128 v[212:215], v173 offset:40960
	ds_read_b128 v[230:233], v174 offset:32768
	ds_read_b128 v[234:237], v174 offset:40960
	ds_read_b128 v[238:241], v175 offset:32768
	ds_read_b128 v[242:245], v175 offset:40960
	s_waitcnt lgkmcnt(7)
	v_mfma_f32_32x32x16_bf16 v[64:79], v[200:203], v[124:127], 0
	ds_read_b128 v[200:203], v172 offset:32896
	v_cvt_pk_bf16_f32 v184, v128, v129
	v_add_f32_e32 v169, v169, v128
	v_add_f32_e32 v219, v219, v129
	s_waitcnt lgkmcnt(7)
	v_mfma_f32_32x32x16_bf16 v[80:95], v[204:207], v[124:127], 0
	ds_read_b128 v[204:207], v172 offset:41088
	v_cvt_pk_bf16_f32 v185, v130, v131
	v_add_f32_e32 v222, v222, v130
	v_add_f32_e32 v254, v254, v131
	s_waitcnt lgkmcnt(7)
	v_mfma_f32_32x32x16_bf16 v[64:79], v[208:211], v[120:123], v[64:79]
	ds_read_b128 v[208:211], v173 offset:32896
	v_cvt_pk_bf16_f32 v186, v132, v133
	v_add_f32_e32 v169, v169, v132
	v_add_f32_e32 v219, v219, v133
	s_waitcnt lgkmcnt(7)
	v_mfma_f32_32x32x16_bf16 v[80:95], v[212:215], v[120:123], v[80:95]
	ds_read_b128 v[212:215], v173 offset:41088
	v_cvt_pk_bf16_f32 v187, v134, v135
	v_add_f32_e32 v222, v222, v134
	v_add_f32_e32 v254, v254, v135
	s_waitcnt lgkmcnt(7)
	v_mfma_f32_32x32x16_bf16 v[64:79], v[230:233], v[116:119], v[64:79]
	ds_read_b128 v[230:233], v174 offset:32896
	v_cvt_pk_bf16_f32 v188, v136, v137
	v_add_f32_e32 v169, v169, v136
	v_add_f32_e32 v219, v219, v137
	v_permlane32_swap_b32_e32 v184, v186
	s_waitcnt lgkmcnt(7)
	v_mfma_f32_32x32x16_bf16 v[80:95], v[234:237], v[116:119], v[80:95]
	ds_read_b128 v[234:237], v174 offset:41088
	v_cvt_pk_bf16_f32 v189, v138, v139
	v_add_f32_e32 v222, v222, v138
	v_add_f32_e32 v254, v254, v139
	v_permlane32_swap_b32_e32 v185, v187
	s_waitcnt lgkmcnt(7)
	v_mfma_f32_32x32x16_bf16 v[64:79], v[238:241], v[112:115], v[64:79]
	ds_read_b128 v[238:241], v175 offset:32896
	v_cvt_pk_bf16_f32 v190, v140, v141
	v_add_f32_e32 v169, v169, v140
	v_add_f32_e32 v219, v219, v141
	s_waitcnt lgkmcnt(7)
	v_mfma_f32_32x32x16_bf16 v[80:95], v[242:245], v[112:115], v[80:95]
	ds_read_b128 v[242:245], v175 offset:41088
	v_cvt_pk_bf16_f32 v191, v142, v143
	v_add_f32_e32 v222, v222, v142
	v_add_f32_e32 v254, v254, v143
	s_waitcnt lgkmcnt(7)
	v_mfma_f32_32x32x16_bf16 v[64:79], v[200:203], v[108:111], v[64:79]
	v_cvt_pk_bf16_f32 v192, v144, v145
	v_add_f32_e32 v169, v169, v144
	v_add_f32_e32 v219, v219, v145
	v_permlane32_swap_b32_e32 v188, v190
	s_waitcnt lgkmcnt(6)
; __device__ __forceinline__ void finishSM(f32x16& p0, f32x16& p1, float alpha, float& l_reg, bf16x8& pa0, bf16x8& pa1, bf16x8& pa2, bf16x8& pa3) {
; #pragma unroll
;   for (int r = 0; r < 16; ++r) p1[r] = __builtin_amdgcn_exp2f(p1[r]);
;   float ps = 0;
; #pragma unroll
;   for (int r = 0; r < 16; ++r) ps += p0[r];
; #pragma unroll
;   for (int r = 0; r < 16; ++r) ps += p1[r];
;   { auto rr = __builtin_amdgcn_permlane32_swap(__float_as_uint(ps), __float_as_uint(ps), false, false);
;     ps = __uint_as_float(rr[0]) + __uint_as_float(rr[1]); }
;   l_reg = l_reg * alpha + ps;
;     ...
;   PK4(p0, 0, pa0); PK4(p0, 8, pa1); PK4(p1, 0, pa2); PK4(p1, 8, pa3);
;     ...
; }
; __device__ __forceinline__ void qkt(f32x16& p0, f32x16& p1, const bf16* Ks, const bf16x8* qr, int r32, int hi) {
;   p0 = f32x16{}; p1 = f32x16{};
; #pragma unroll
;   for (int d0 = 0; d0 < 8; ++d0) { int cb = (d0 * 16 + hi * 8) * 2;
;     bf16x8 b0 = *reinterpret_cast<const bf16x8*>((const char*)Ks + KSWZ(r32, cb));
;     bf16x8 b1 = *reinterpret_cast<const bf16x8*>((const char*)Ks + KSWZ(32 + r32, cb));
;     p0 = __builtin_amdgcn_mfma_f32_32x32x16_bf16(b0, qr[d0], p0, 0, 0, 0);
;     p1 = __builtin_amdgcn_mfma_f32_32x32x16_bf16(b1, qr[d0], p1, 0, 0, 0); }
; }
; __device__ __forceinline__ int v_st(int k, int c) { const int kk = (k & ~0xC) | ((k & 4) << 1) | ((k & 8) >> 1); return ((kk >> 3) * 4 + (c >> 5)) * 512 + ((kk & 7) * 32 + (c & 31)) * 2; }
; __device__ __forceinline__ int v_rd_base(int lane) { return ((lane & 3) << 3) | (((lane >> 2) & 3) << 6) | (((lane >> 4) & 1) << 5) | (((lane >> 5) & 1) << 8); }
; template <int OFF> __device__ __forceinline__ s16x4 tr_read(int vb) {
;   s16x4 r; asm volatile("ds_read_b64_tr_b16 %0, %1 offset:%2" : "=&v"(r) : "v"(vb), "i"(OFF) : "memory"); return r;
; }
; template <int D0> __device__ __forceinline__ void pv_one(f32x16& od, int vb, bf16x8 pa0, bf16x8 pa1, bf16x8 pa2, bf16x8 pa3) {
;   const s16x4 l0 = tr_read<v_rd_off(D0, 0, 0)>(vb), h0 = tr_read<v_rd_off(D0, 0, 1)>(vb), l1 = tr_read<v_rd_off(D0, 1, 0)>(vb), h1 = tr_read<v_rd_off(D0, 1, 1)>(vb);
;   const s16x4 l2 = tr_read<v_rd_off(D0, 2, 0)>(vb), h2 = tr_read<v_rd_off(D0, 2, 1)>(vb), l3 = tr_read<v_rd_off(D0, 3, 0)>(vb), h3 = tr_read<v_rd_off(D0, 3, 1)>(vb);
;   asm volatile("s_waitcnt lgkmcnt(0)" ::: "memory"); SBAR();
;     ...
;   od = __builtin_amdgcn_mfma_f32_32x32x16_bf16(pa0, PK(l0, h0), od, 0, 0, 0);
	v_mfma_f32_32x32x16_bf16 v[80:95], v[204:207], v[108:111], v[80:95]
	v_cvt_pk_bf16_f32 v193, v146, v147
	v_add_f32_e32 v222, v222, v146
	v_add_f32_e32 v254, v254, v147
	v_permlane32_swap_b32_e32 v189, v191
	s_waitcnt lgkmcnt(5)
	v_mfma_f32_32x32x16_bf16 v[64:79], v[208:211], v[104:107], v[64:79]
	ds_read_b64_tr_b16 v[200:201], v182 offset:16384
	ds_read_b64_tr_b16 v[202:203], v182 offset:18432
	v_cvt_pk_bf16_f32 v194, v148, v149
	v_add_f32_e32 v169, v169, v148
	v_add_f32_e32 v219, v219, v149
	s_waitcnt lgkmcnt(6)
	v_mfma_f32_32x32x16_bf16 v[80:95], v[212:215], v[104:107], v[80:95]
	ds_read_b64_tr_b16 v[204:205], v182 offset:20480
	ds_read_b64_tr_b16 v[206:207], v182 offset:22528
	v_cvt_pk_bf16_f32 v195, v150, v151
	v_add_f32_e32 v222, v222, v150
	v_add_f32_e32 v254, v254, v151
	s_waitcnt lgkmcnt(7)
	v_mfma_f32_32x32x16_bf16 v[64:79], v[230:233], v[100:103], v[64:79]
	ds_read_b64_tr_b16 v[208:209], v182 offset:24576
	ds_read_b64_tr_b16 v[210:211], v182 offset:26624
	v_cvt_pk_bf16_f32 v196, v152, v153
	v_add_f32_e32 v169, v169, v152
	v_add_f32_e32 v219, v219, v153
	v_permlane32_swap_b32_e32 v192, v194
	s_waitcnt lgkmcnt(8)
	v_mfma_f32_32x32x16_bf16 v[80:95], v[234:237], v[100:103], v[80:95]
	ds_read_b64_tr_b16 v[212:213], v182 offset:28672
	ds_read_b64_tr_b16 v[214:215], v182 offset:30720
	v_cvt_pk_bf16_f32 v197, v154, v155
	v_add_f32_e32 v222, v222, v154
	v_add_f32_e32 v254, v254, v155
	v_permlane32_swap_b32_e32 v193, v195
	s_waitcnt lgkmcnt(9)
	v_mfma_f32_32x32x16_bf16 v[64:79], v[238:241], v[96:99], v[64:79]
	ds_read_b64_tr_b16 v[230:231], v182 offset:16896
	ds_read_b64_tr_b16 v[232:233], v182 offset:18944
	v_cvt_pk_bf16_f32 v198, v156, v157
	v_add_f32_e32 v169, v169, v156
	v_add_f32_e32 v219, v219, v157
	s_waitcnt lgkmcnt(10)
	v_mfma_f32_32x32x16_bf16 v[80:95], v[242:245], v[96:99], v[80:95]
	ds_read_b64_tr_b16 v[234:235], v182 offset:20992
	ds_read_b64_tr_b16 v[236:237], v182 offset:23040
	v_cvt_pk_bf16_f32 v199, v158, v159
	v_add_f32_e32 v222, v222, v158
	v_add_f32_e32 v254, v254, v159
	v_permlane32_swap_b32_e32 v196, v198
	v_permlane32_swap_b32_e32 v197, v199
	s_waitcnt lgkmcnt(10)
	v_mfma_f32_32x32x16_bf16 v[0:15], v[184:187], v[200:203], v[0:15]
	ds_read_b64_tr_b16 v[238:239], v182 offset:25088
	ds_read_b64_tr_b16 v[240:241], v182 offset:27136
	v_exp_f32_e32 v64, v64
	v_exp_f32_e32 v65, v65
	s_waitcnt lgkmcnt(10)
	v_mfma_f32_32x32x16_bf16 v[0:15], v[188:191], v[204:207], v[0:15]
	ds_read_b64_tr_b16 v[242:243], v182 offset:29184
	ds_read_b64_tr_b16 v[244:245], v182 offset:31232
	v_exp_f32_e32 v66, v66
	v_exp_f32_e32 v67, v67
	s_waitcnt lgkmcnt(10)
	v_mfma_f32_32x32x16_bf16 v[0:15], v[192:195], v[208:211], v[0:15]
	ds_read_b64_tr_b16 v[200:201], v182 offset:17408
	ds_read_b64_tr_b16 v[202:203], v182 offset:19456
	v_exp_f32_e32 v68, v68
	v_exp_f32_e32 v69, v69
	s_waitcnt lgkmcnt(10)
	v_mfma_f32_32x32x16_bf16 v[0:15], v[196:199], v[212:215], v[0:15]
	ds_read_b64_tr_b16 v[204:205], v182 offset:21504
	ds_read_b64_tr_b16 v[206:207], v182 offset:23552
	v_exp_f32_e32 v70, v70
	v_exp_f32_e32 v71, v71
	s_waitcnt lgkmcnt(10)
	v_mfma_f32_32x32x16_bf16 v[48:63], v[184:187], v[230:233], v[48:63]
	ds_read_b64_tr_b16 v[208:209], v182 offset:25600
	ds_read_b64_tr_b16 v[210:211], v182 offset:27648
	v_exp_f32_e32 v72, v72
	v_exp_f32_e32 v73, v73
	s_waitcnt lgkmcnt(10)
	v_mfma_f32_32x32x16_bf16 v[48:63], v[188:191], v[234:237], v[48:63]
	ds_read_b64_tr_b16 v[212:213], v182 offset:29696
	ds_read_b64_tr_b16 v[214:215], v182 offset:31744
	v_exp_f32_e32 v74, v74
	v_exp_f32_e32 v75, v75
	s_waitcnt lgkmcnt(10)
	v_mfma_f32_32x32x16_bf16 v[48:63], v[192:195], v[238:241], v[48:63]
	ds_read_b64_tr_b16 v[230:231], v182 offset:17920
	ds_read_b64_tr_b16 v[232:233], v182 offset:19968
	v_exp_f32_e32 v76, v76
	v_exp_f32_e32 v77, v77
	s_waitcnt lgkmcnt(10)
	v_mfma_f32_32x32x16_bf16 v[48:63], v[196:199], v[242:245], v[48:63]
	ds_read_b64_tr_b16 v[234:235], v182 offset:22016
	ds_read_b64_tr_b16 v[236:237], v182 offset:24064
	v_exp_f32_e32 v78, v78
	v_exp_f32_e32 v79, v79
	s_waitcnt lgkmcnt(10)
	v_mfma_f32_32x32x16_bf16 v[32:47], v[184:187], v[200:203], v[32:47]
	ds_read_b64_tr_b16 v[238:239], v182 offset:26112
	ds_read_b64_tr_b16 v[240:241], v182 offset:28160
	v_exp_f32_e32 v80, v80
	v_exp_f32_e32 v81, v81
	s_waitcnt lgkmcnt(10)
	v_mfma_f32_32x32x16_bf16 v[32:47], v[188:191], v[204:207], v[32:47]
	ds_read_b64_tr_b16 v[242:243], v182 offset:30208
	ds_read_b64_tr_b16 v[244:245], v182 offset:32256
	v_exp_f32_e32 v82, v82
	v_exp_f32_e32 v83, v83
	s_waitcnt lgkmcnt(10)
	v_mfma_f32_32x32x16_bf16 v[32:47], v[192:195], v[208:211], v[32:47]
	v_exp_f32_e32 v84, v84
	v_exp_f32_e32 v85, v85
	s_waitcnt lgkmcnt(8)
	v_mfma_f32_32x32x16_bf16 v[32:47], v[196:199], v[212:215], v[32:47]
	v_exp_f32_e32 v86, v86
	v_exp_f32_e32 v87, v87
	s_waitcnt vmcnt(0)
	ds_write_b128 v181, v[246:249] offset:49152
	ds_write_b128 v181, v[250:253] offset:57344
	ds_write_b128 v180, v[176:179] offset:49152
	ds_write_b128 v180, v[160:163] offset:57344
	s_waitcnt lgkmcnt(10)
	v_mfma_f32_32x32x16_bf16 v[16:31], v[184:187], v[230:233], v[16:31]
	v_exp_f32_e32 v88, v88
	v_exp_f32_e32 v89, v89
	s_waitcnt lgkmcnt(8)
	v_mfma_f32_32x32x16_bf16 v[16:31], v[188:191], v[234:237], v[16:31]
	v_exp_f32_e32 v90, v90
	v_exp_f32_e32 v91, v91
	s_waitcnt lgkmcnt(6)
	v_mfma_f32_32x32x16_bf16 v[16:31], v[192:195], v[238:241], v[16:31]
	v_exp_f32_e32 v92, v92
	v_exp_f32_e32 v93, v93
	s_waitcnt lgkmcnt(4)
	v_mfma_f32_32x32x16_bf16 v[16:31], v[196:199], v[242:245], v[16:31]
	v_exp_f32_e32 v94, v94
	v_exp_f32_e32 v95, v95
	s_waitcnt lgkmcnt(0)
	s_barrier
; __device__ __forceinline__ void finishSM(f32x16& p0, f32x16& p1, float alpha, float& l_reg, bf16x8& pa0, bf16x8& pa1, bf16x8& pa2, bf16x8& pa3) {
; #pragma unroll
;   for (int r = 0; r < 16; ++r) p1[r] = __builtin_amdgcn_exp2f(p1[r]);
;   float ps = 0;
; #pragma unroll
;   for (int r = 0; r < 16; ++r) ps += p0[r];
; #pragma unroll
;   for (int r = 0; r < 16; ++r) ps += p1[r];
;   { auto rr = __builtin_amdgcn_permlane32_swap(__float_as_uint(ps), __float_as_uint(ps), false, false);
;     ps = __uint_as_float(rr[0]) + __uint_as_float(rr[1]); }
;   l_reg = l_reg * alpha + ps;
;     ...
;   PK4(p0, 0, pa0); PK4(p0, 8, pa1); PK4(p1, 0, pa2); PK4(p1, 8, pa3);
;     ...
; }
; __device__ __forceinline__ void qkt(f32x16& p0, f32x16& p1, const bf16* Ks, const bf16x8* qr, int r32, int hi) {
;   p0 = f32x16{}; p1 = f32x16{};
; #pragma unroll
;   for (int d0 = 0; d0 < 8; ++d0) { int cb = (d0 * 16 + hi * 8) * 2;
;     bf16x8 b0 = *reinterpret_cast<const bf16x8*>((const char*)Ks + KSWZ(r32, cb));
;     bf16x8 b1 = *reinterpret_cast<const bf16x8*>((const char*)Ks + KSWZ(32 + r32, cb));
;     p0 = __builtin_amdgcn_mfma_f32_32x32x16_bf16(b0, qr[d0], p0, 0, 0, 0);
;     p1 = __builtin_amdgcn_mfma_f32_32x32x16_bf16(b1, qr[d0], p1, 0, 0, 0); }
; }
; __device__ __forceinline__ int v_st(int k, int c) { const int kk = (k & ~0xC) | ((k & 4) << 1) | ((k & 8) >> 1); return ((kk >> 3) * 4 + (c >> 5)) * 512 + ((kk & 7) * 32 + (c & 31)) * 2; }
; __device__ __forceinline__ int v_rd_base(int lane) { return ((lane & 3) << 3) | (((lane >> 2) & 3) << 6) | (((lane >> 4) & 1) << 5) | (((lane >> 5) & 1) << 8); }
; template <int OFF> __device__ __forceinline__ s16x4 tr_read(int vb) {
;   s16x4 r; asm volatile("ds_read_b64_tr_b16 %0, %1 offset:%2" : "=&v"(r) : "v"(vb), "i"(OFF) : "memory"); return r;
; }
; template <int D0> __device__ __forceinline__ void pv_one(f32x16& od, int vb, bf16x8 pa0, bf16x8 pa1, bf16x8 pa2, bf16x8 pa3) {
;   const s16x4 l0 = tr_read<v_rd_off(D0, 0, 0)>(vb), h0 = tr_read<v_rd_off(D0, 0, 1)>(vb), l1 = tr_read<v_rd_off(D0, 1, 0)>(vb), h1 = tr_read<v_rd_off(D0, 1, 1)>(vb);
;   const s16x4 l2 = tr_read<v_rd_off(D0, 2, 0)>(vb), h2 = tr_read<v_rd_off(D0, 2, 1)>(vb), l3 = tr_read<v_rd_off(D0, 3, 0)>(vb), h3 = tr_read<v_rd_off(D0, 3, 1)>(vb);
;   asm volatile("s_waitcnt lgkmcnt(0)" ::: "memory"); SBAR();
;     ...
;   od = __builtin_amdgcn_mfma_f32_32x32x16_bf16(pa0, PK(l0, h0), od, 0, 0, 0);
	global_load_dwordx4 v[246:249], v[216:217], off
	global_load_dwordx4 v[176:179], v[216:217], off offset:512
	global_load_dwordx4 v[250:253], v[166:167], off
	global_load_dwordx4 v[160:163], v[166:167], off offset:512
	v_lshl_add_u64 v[216:217], v[216:217], 0, s[0:1]
	v_lshl_add_u64 v[166:167], v[166:167], 0, s[0:1]
	ds_read_b128 v[200:203], v172 offset:49152
	ds_read_b128 v[204:207], v172 offset:57344
	ds_read_b128 v[208:211], v173 offset:49152
	ds_read_b128 v[212:215], v173 offset:57344
	ds_read_b128 v[230:233], v174 offset:49152
	ds_read_b128 v[234:237], v174 offset:57344
	ds_read_b128 v[238:241], v175 offset:49152
	ds_read_b128 v[242:245], v175 offset:57344
	s_waitcnt lgkmcnt(7)
	v_mfma_f32_32x32x16_bf16 v[128:143], v[200:203], v[124:127], 0
	ds_read_b128 v[200:203], v172 offset:49280
	v_cvt_pk_bf16_f32 v184, v64, v65
	v_add_f32_e32 v169, v169, v64
	v_add_f32_e32 v219, v219, v65
	s_waitcnt lgkmcnt(7)
	v_mfma_f32_32x32x16_bf16 v[144:159], v[204:207], v[124:127], 0
	ds_read_b128 v[204:207], v172 offset:57472
	v_cvt_pk_bf16_f32 v185, v66, v67
	v_add_f32_e32 v222, v222, v66
	v_add_f32_e32 v254, v254, v67
	s_waitcnt lgkmcnt(7)
	v_mfma_f32_32x32x16_bf16 v[128:143], v[208:211], v[120:123], v[128:143]
	ds_read_b128 v[208:211], v173 offset:49280
	v_cvt_pk_bf16_f32 v186, v68, v69
	v_add_f32_e32 v169, v169, v68
	v_add_f32_e32 v219, v219, v69
	s_waitcnt lgkmcnt(7)
	v_mfma_f32_32x32x16_bf16 v[144:159], v[212:215], v[120:123], v[144:159]
	ds_read_b128 v[212:215], v173 offset:57472
	v_cvt_pk_bf16_f32 v187, v70, v71
	v_add_f32_e32 v222, v222, v70
	v_add_f32_e32 v254, v254, v71
	s_waitcnt lgkmcnt(7)
	v_mfma_f32_32x32x16_bf16 v[128:143], v[230:233], v[116:119], v[128:143]
	ds_read_b128 v[230:233], v174 offset:49280
	v_cvt_pk_bf16_f32 v188, v72, v73
	v_add_f32_e32 v169, v169, v72
	v_add_f32_e32 v219, v219, v73
	v_permlane32_swap_b32_e32 v184, v186
	s_waitcnt lgkmcnt(7)
	v_mfma_f32_32x32x16_bf16 v[144:159], v[234:237], v[116:119], v[144:159]
	ds_read_b128 v[234:237], v174 offset:57472
	v_cvt_pk_bf16_f32 v189, v74, v75
	v_add_f32_e32 v222, v222, v74
	v_add_f32_e32 v254, v254, v75
	v_permlane32_swap_b32_e32 v185, v187
	s_waitcnt lgkmcnt(7)
	v_mfma_f32_32x32x16_bf16 v[128:143], v[238:241], v[112:115], v[128:143]
	ds_read_b128 v[238:241], v175 offset:49280
	v_cvt_pk_bf16_f32 v190, v76, v77
	v_add_f32_e32 v169, v169, v76
	v_add_f32_e32 v219, v219, v77
	s_waitcnt lgkmcnt(7)
	v_mfma_f32_32x32x16_bf16 v[144:159], v[242:245], v[112:115], v[144:159]
	ds_read_b128 v[242:245], v175 offset:57472
	v_cvt_pk_bf16_f32 v191, v78, v79
	v_add_f32_e32 v222, v222, v78
	v_add_f32_e32 v254, v254, v79
	s_waitcnt lgkmcnt(7)
	v_mfma_f32_32x32x16_bf16 v[128:143], v[200:203], v[108:111], v[128:143]
	v_cvt_pk_bf16_f32 v192, v80, v81
	v_add_f32_e32 v169, v169, v80
	v_add_f32_e32 v219, v219, v81
	v_permlane32_swap_b32_e32 v188, v190
	s_waitcnt lgkmcnt(6)
	v_mfma_f32_32x32x16_bf16 v[144:159], v[204:207], v[108:111], v[144:159]
	v_cvt_pk_bf16_f32 v193, v82, v83
	v_add_f32_e32 v222, v222, v82
	v_add_f32_e32 v254, v254, v83
	v_permlane32_swap_b32_e32 v189, v191
	s_waitcnt lgkmcnt(5)
	v_mfma_f32_32x32x16_bf16 v[128:143], v[208:211], v[104:107], v[128:143]
	ds_read_b64_tr_b16 v[200:201], v182 offset:32768
	ds_read_b64_tr_b16 v[202:203], v182 offset:34816
	v_cvt_pk_bf16_f32 v194, v84, v85
	v_add_f32_e32 v169, v169, v84
	v_add_f32_e32 v219, v219, v85
	s_waitcnt lgkmcnt(6)
	v_mfma_f32_32x32x16_bf16 v[144:159], v[212:215], v[104:107], v[144:159]
	ds_read_b64_tr_b16 v[204:205], v182 offset:36864
	ds_read_b64_tr_b16 v[206:207], v182 offset:38912
	v_cvt_pk_bf16_f32 v195, v86, v87
	v_add_f32_e32 v222, v222, v86
	v_add_f32_e32 v254, v254, v87
	s_waitcnt lgkmcnt(7)
	v_mfma_f32_32x32x16_bf16 v[128:143], v[230:233], v[100:103], v[128:143]
	ds_read_b64_tr_b16 v[208:209], v182 offset:40960
	ds_read_b64_tr_b16 v[210:211], v182 offset:43008
	v_cvt_pk_bf16_f32 v196, v88, v89
	v_add_f32_e32 v169, v169, v88
	v_add_f32_e32 v219, v219, v89
	v_permlane32_swap_b32_e32 v192, v194
	s_waitcnt lgkmcnt(8)
	v_mfma_f32_32x32x16_bf16 v[144:159], v[234:237], v[100:103], v[144:159]
	ds_read_b64_tr_b16 v[212:213], v182 offset:45056
	ds_read_b64_tr_b16 v[214:215], v182 offset:47104
	v_cvt_pk_bf16_f32 v197, v90, v91
	v_add_f32_e32 v222, v222, v90
	v_add_f32_e32 v254, v254, v91
	v_permlane32_swap_b32_e32 v193, v195
	s_waitcnt lgkmcnt(9)
	v_mfma_f32_32x32x16_bf16 v[128:143], v[238:241], v[96:99], v[128:143]
	ds_read_b64_tr_b16 v[230:231], v182 offset:33280
	ds_read_b64_tr_b16 v[232:233], v182 offset:35328
	v_cvt_pk_bf16_f32 v198, v92, v93
	v_add_f32_e32 v169, v169, v92
	v_add_f32_e32 v219, v219, v93
	s_waitcnt lgkmcnt(10)
	v_mfma_f32_32x32x16_bf16 v[144:159], v[242:245], v[96:99], v[144:159]
	ds_read_b64_tr_b16 v[234:235], v182 offset:37376
	ds_read_b64_tr_b16 v[236:237], v182 offset:39424
	v_cvt_pk_bf16_f32 v199, v94, v95
	v_add_f32_e32 v222, v222, v94
	v_add_f32_e32 v254, v254, v95
	v_permlane32_swap_b32_e32 v196, v198
	v_permlane32_swap_b32_e32 v197, v199
	s_waitcnt lgkmcnt(10)
	v_mfma_f32_32x32x16_bf16 v[0:15], v[184:187], v[200:203], v[0:15]
	ds_read_b64_tr_b16 v[238:239], v182 offset:41472
	ds_read_b64_tr_b16 v[240:241], v182 offset:43520
	v_exp_f32_e32 v128, v128
	v_exp_f32_e32 v129, v129
	s_waitcnt lgkmcnt(10)
	v_mfma_f32_32x32x16_bf16 v[0:15], v[188:191], v[204:207], v[0:15]
	ds_read_b64_tr_b16 v[242:243], v182 offset:45568
	ds_read_b64_tr_b16 v[244:245], v182 offset:47616
	v_exp_f32_e32 v130, v130
	v_exp_f32_e32 v131, v131
	s_waitcnt lgkmcnt(10)
	v_mfma_f32_32x32x16_bf16 v[0:15], v[192:195], v[208:211], v[0:15]
	ds_read_b64_tr_b16 v[200:201], v182 offset:33792
	ds_read_b64_tr_b16 v[202:203], v182 offset:35840
	v_exp_f32_e32 v132, v132
	v_exp_f32_e32 v133, v133
	s_waitcnt lgkmcnt(10)
; __device__ __forceinline__ void finishSM(f32x16& p0, f32x16& p1, float alpha, float& l_reg, bf16x8& pa0, bf16x8& pa1, bf16x8& pa2, bf16x8& pa3) {
; #pragma unroll
;   for (int r = 0; r < 16; ++r) p1[r] = __builtin_amdgcn_exp2f(p1[r]);
;   float ps = 0;
; #pragma unroll
;   for (int r = 0; r < 16; ++r) ps += p0[r];
; #pragma unroll
;   for (int r = 0; r < 16; ++r) ps += p1[r];
;   { auto rr = __builtin_amdgcn_permlane32_swap(__float_as_uint(ps), __float_as_uint(ps), false, false);
;     ps = __uint_as_float(rr[0]) + __uint_as_float(rr[1]); }
;   l_reg = l_reg * alpha + ps;
;     ...
;   PK4(p0, 0, pa0); PK4(p0, 8, pa1); PK4(p1, 0, pa2); PK4(p1, 8, pa3);
;     ...
; }
; __device__ __forceinline__ void qkt(f32x16& p0, f32x16& p1, const bf16* Ks, const bf16x8* qr, int r32, int hi) {
;   p0 = f32x16{}; p1 = f32x16{};
; #pragma unroll
;   for (int d0 = 0; d0 < 8; ++d0) { int cb = (d0 * 16 + hi * 8) * 2;
;     bf16x8 b0 = *reinterpret_cast<const bf16x8*>((const char*)Ks + KSWZ(r32, cb));
;     bf16x8 b1 = *reinterpret_cast<const bf16x8*>((const char*)Ks + KSWZ(32 + r32, cb));
;     p0 = __builtin_amdgcn_mfma_f32_32x32x16_bf16(b0, qr[d0], p0, 0, 0, 0);
;     p1 = __builtin_amdgcn_mfma_f32_32x32x16_bf16(b1, qr[d0], p1, 0, 0, 0); }
; }
; __device__ __forceinline__ int v_st(int k, int c) { const int kk = (k & ~0xC) | ((k & 4) << 1) | ((k & 8) >> 1); return ((kk >> 3) * 4 + (c >> 5)) * 512 + ((kk & 7) * 32 + (c & 31)) * 2; }
; __device__ __forceinline__ int v_rd_base(int lane) { return ((lane & 3) << 3) | (((lane >> 2) & 3) << 6) | (((lane >> 4) & 1) << 5) | (((lane >> 5) & 1) << 8); }
; template <int OFF> __device__ __forceinline__ s16x4 tr_read(int vb) {
;   s16x4 r; asm volatile("ds_read_b64_tr_b16 %0, %1 offset:%2" : "=&v"(r) : "v"(vb), "i"(OFF) : "memory"); return r;
; }
; template <int D0> __device__ __forceinline__ void pv_one(f32x16& od, int vb, bf16x8 pa0, bf16x8 pa1, bf16x8 pa2, bf16x8 pa3) {
;   const s16x4 l0 = tr_read<v_rd_off(D0, 0, 0)>(vb), h0 = tr_read<v_rd_off(D0, 0, 1)>(vb), l1 = tr_read<v_rd_off(D0, 1, 0)>(vb), h1 = tr_read<v_rd_off(D0, 1, 1)>(vb);
;   const s16x4 l2 = tr_read<v_rd_off(D0, 2, 0)>(vb), h2 = tr_read<v_rd_off(D0, 2, 1)>(vb), l3 = tr_read<v_rd_off(D0, 3, 0)>(vb), h3 = tr_read<v_rd_off(D0, 3, 1)>(vb);
;   asm volatile("s_waitcnt lgkmcnt(0)" ::: "memory"); SBAR();
;     ...
;   od = __builtin_amdgcn_mfma_f32_32x32x16_bf16(pa0, PK(l0, h0), od, 0, 0, 0);
	v_mfma_f32_32x32x16_bf16 v[0:15], v[196:199], v[212:215], v[0:15]
	ds_read_b64_tr_b16 v[204:205], v182 offset:37888
	ds_read_b64_tr_b16 v[206:207], v182 offset:39936
	v_exp_f32_e32 v134, v134
	v_exp_f32_e32 v135, v135
	s_waitcnt lgkmcnt(10)
	v_mfma_f32_32x32x16_bf16 v[48:63], v[184:187], v[230:233], v[48:63]
	ds_read_b64_tr_b16 v[208:209], v182 offset:41984
	ds_read_b64_tr_b16 v[210:211], v182 offset:44032
	v_exp_f32_e32 v136, v136
	v_exp_f32_e32 v137, v137
	s_waitcnt lgkmcnt(10)
	v_mfma_f32_32x32x16_bf16 v[48:63], v[188:191], v[234:237], v[48:63]
	ds_read_b64_tr_b16 v[212:213], v182 offset:46080
	ds_read_b64_tr_b16 v[214:215], v182 offset:48128
	v_exp_f32_e32 v138, v138
	v_exp_f32_e32 v139, v139
	s_waitcnt lgkmcnt(10)
	v_mfma_f32_32x32x16_bf16 v[48:63], v[192:195], v[238:241], v[48:63]
	ds_read_b64_tr_b16 v[230:231], v182 offset:34304
	ds_read_b64_tr_b16 v[232:233], v182 offset:36352
	v_exp_f32_e32 v140, v140
	v_exp_f32_e32 v141, v141
	s_waitcnt lgkmcnt(10)
	v_mfma_f32_32x32x16_bf16 v[48:63], v[196:199], v[242:245], v[48:63]
	ds_read_b64_tr_b16 v[234:235], v182 offset:38400
	ds_read_b64_tr_b16 v[236:237], v182 offset:40448
	v_exp_f32_e32 v142, v142
	v_exp_f32_e32 v143, v143
	s_waitcnt lgkmcnt(10)
	v_mfma_f32_32x32x16_bf16 v[32:47], v[184:187], v[200:203], v[32:47]
	ds_read_b64_tr_b16 v[238:239], v182 offset:42496
	ds_read_b64_tr_b16 v[240:241], v182 offset:44544
	v_exp_f32_e32 v144, v144
	v_exp_f32_e32 v145, v145
	s_waitcnt lgkmcnt(10)
	v_mfma_f32_32x32x16_bf16 v[32:47], v[188:191], v[204:207], v[32:47]
	ds_read_b64_tr_b16 v[242:243], v182 offset:46592
	ds_read_b64_tr_b16 v[244:245], v182 offset:48640
	v_exp_f32_e32 v146, v146
	v_exp_f32_e32 v147, v147
	s_waitcnt lgkmcnt(10)
	v_mfma_f32_32x32x16_bf16 v[32:47], v[192:195], v[208:211], v[32:47]
	v_exp_f32_e32 v148, v148
	v_exp_f32_e32 v149, v149
	s_waitcnt lgkmcnt(8)
	v_mfma_f32_32x32x16_bf16 v[32:47], v[196:199], v[212:215], v[32:47]
	v_exp_f32_e32 v150, v150
	v_exp_f32_e32 v151, v151
	s_waitcnt vmcnt(0)
	ds_write_b128 v181, v[246:249] offset:0
	ds_write_b128 v181, v[250:253] offset:8192
	ds_write_b128 v180, v[176:179] offset:0
	ds_write_b128 v180, v[160:163] offset:8192
	s_waitcnt lgkmcnt(10)
	v_mfma_f32_32x32x16_bf16 v[16:31], v[184:187], v[230:233], v[16:31]
	v_exp_f32_e32 v152, v152
	v_exp_f32_e32 v153, v153
	s_waitcnt lgkmcnt(8)
	v_mfma_f32_32x32x16_bf16 v[16:31], v[188:191], v[234:237], v[16:31]
	v_exp_f32_e32 v154, v154
	v_exp_f32_e32 v155, v155
	s_waitcnt lgkmcnt(6)
	v_mfma_f32_32x32x16_bf16 v[16:31], v[192:195], v[238:241], v[16:31]
	v_exp_f32_e32 v156, v156
	v_exp_f32_e32 v157, v157
	s_waitcnt lgkmcnt(4)
	v_mfma_f32_32x32x16_bf16 v[16:31], v[196:199], v[242:245], v[16:31]
	v_exp_f32_e32 v158, v158
	v_exp_f32_e32 v159, v159
	s_waitcnt lgkmcnt(0)
	s_barrier
	global_load_dwordx4 v[246:249], v[216:217], off
	global_load_dwordx4 v[176:179], v[216:217], off offset:512
	global_load_dwordx4 v[250:253], v[166:167], off
	global_load_dwordx4 v[160:163], v[166:167], off offset:512
	v_lshl_add_u64 v[216:217], v[216:217], 0, s[0:1]
	v_lshl_add_u64 v[166:167], v[166:167], 0, s[0:1]
	ds_read_b128 v[200:203], v172 offset:0
	ds_read_b128 v[204:207], v172 offset:8192
	ds_read_b128 v[208:211], v173 offset:0
	ds_read_b128 v[212:215], v173 offset:8192
	ds_read_b128 v[230:233], v174 offset:0
	ds_read_b128 v[234:237], v174 offset:8192
	ds_read_b128 v[238:241], v175 offset:0
	ds_read_b128 v[242:245], v175 offset:8192
	s_waitcnt lgkmcnt(7)
	v_mfma_f32_32x32x16_bf16 v[64:79], v[200:203], v[124:127], 0
	ds_read_b128 v[200:203], v172 offset:128
	v_cvt_pk_bf16_f32 v184, v128, v129
	v_add_f32_e32 v169, v169, v128
	v_add_f32_e32 v219, v219, v129
	s_waitcnt lgkmcnt(7)
	v_mfma_f32_32x32x16_bf16 v[80:95], v[204:207], v[124:127], 0
	ds_read_b128 v[204:207], v172 offset:8320
	v_cvt_pk_bf16_f32 v185, v130, v131
	v_add_f32_e32 v222, v222, v130
	v_add_f32_e32 v254, v254, v131
	s_waitcnt lgkmcnt(7)
	v_mfma_f32_32x32x16_bf16 v[64:79], v[208:211], v[120:123], v[64:79]
	ds_read_b128 v[208:211], v173 offset:128
	v_cvt_pk_bf16_f32 v186, v132, v133
	v_add_f32_e32 v169, v169, v132
	v_add_f32_e32 v219, v219, v133
	s_waitcnt lgkmcnt(7)
	v_mfma_f32_32x32x16_bf16 v[80:95], v[212:215], v[120:123], v[80:95]
	ds_read_b128 v[212:215], v173 offset:8320
	v_cvt_pk_bf16_f32 v187, v134, v135
	v_add_f32_e32 v222, v222, v134
	v_add_f32_e32 v254, v254, v135
	s_waitcnt lgkmcnt(7)
	v_mfma_f32_32x32x16_bf16 v[64:79], v[230:233], v[116:119], v[64:79]
	ds_read_b128 v[230:233], v174 offset:128
	v_cvt_pk_bf16_f32 v188, v136, v137
	v_add_f32_e32 v169, v169, v136
	v_add_f32_e32 v219, v219, v137
	v_permlane32_swap_b32_e32 v184, v186
	s_waitcnt lgkmcnt(7)
	v_mfma_f32_32x32x16_bf16 v[80:95], v[234:237], v[116:119], v[80:95]
	ds_read_b128 v[234:237], v174 offset:8320
	v_cvt_pk_bf16_f32 v189, v138, v139
	v_add_f32_e32 v222, v222, v138
	v_add_f32_e32 v254, v254, v139
	v_permlane32_swap_b32_e32 v185, v187
	s_waitcnt lgkmcnt(7)
	v_mfma_f32_32x32x16_bf16 v[64:79], v[238:241], v[112:115], v[64:79]
	ds_read_b128 v[238:241], v175 offset:128
	v_cvt_pk_bf16_f32 v190, v140, v141
	v_add_f32_e32 v169, v169, v140
	v_add_f32_e32 v219, v219, v141
	s_waitcnt lgkmcnt(7)
	v_mfma_f32_32x32x16_bf16 v[80:95], v[242:245], v[112:115], v[80:95]
	ds_read_b128 v[242:245], v175 offset:8320
	v_cvt_pk_bf16_f32 v191, v142, v143
	v_add_f32_e32 v222, v222, v142
	v_add_f32_e32 v254, v254, v143
	s_waitcnt lgkmcnt(7)
	v_mfma_f32_32x32x16_bf16 v[64:79], v[200:203], v[108:111], v[64:79]
	v_cvt_pk_bf16_f32 v192, v144, v145
	v_add_f32_e32 v169, v169, v144
	v_add_f32_e32 v219, v219, v145
	v_permlane32_swap_b32_e32 v188, v190
	s_waitcnt lgkmcnt(6)
; __device__ __forceinline__ void finishSM(f32x16& p0, f32x16& p1, float alpha, float& l_reg, bf16x8& pa0, bf16x8& pa1, bf16x8& pa2, bf16x8& pa3) {
; #pragma unroll
;   for (int r = 0; r < 16; ++r) p1[r] = __builtin_amdgcn_exp2f(p1[r]);
;   float ps = 0;
; #pragma unroll
;   for (int r = 0; r < 16; ++r) ps += p0[r];
; #pragma unroll
;   for (int r = 0; r < 16; ++r) ps += p1[r];
;   { auto rr = __builtin_amdgcn_permlane32_swap(__float_as_uint(ps), __float_as_uint(ps), false, false);
;     ps = __uint_as_float(rr[0]) + __uint_as_float(rr[1]); }
;   l_reg = l_reg * alpha + ps;
;     ...
;   PK4(p0, 0, pa0); PK4(p0, 8, pa1); PK4(p1, 0, pa2); PK4(p1, 8, pa3);
;     ...
; }
; __device__ __forceinline__ void qkt(f32x16& p0, f32x16& p1, const bf16* Ks, const bf16x8* qr, int r32, int hi) {
;   p0 = f32x16{}; p1 = f32x16{};
; #pragma unroll
;   for (int d0 = 0; d0 < 8; ++d0) { int cb = (d0 * 16 + hi * 8) * 2;
;     bf16x8 b0 = *reinterpret_cast<const bf16x8*>((const char*)Ks + KSWZ(r32, cb));
;     bf16x8 b1 = *reinterpret_cast<const bf16x8*>((const char*)Ks + KSWZ(32 + r32, cb));
;     p0 = __builtin_amdgcn_mfma_f32_32x32x16_bf16(b0, qr[d0], p0, 0, 0, 0);
;     p1 = __builtin_amdgcn_mfma_f32_32x32x16_bf16(b1, qr[d0], p1, 0, 0, 0); }
; }
; __device__ __forceinline__ int v_st(int k, int c) { const int kk = (k & ~0xC) | ((k & 4) << 1) | ((k & 8) >> 1); return ((kk >> 3) * 4 + (c >> 5)) * 512 + ((kk & 7) * 32 + (c & 31)) * 2; }
; __device__ __forceinline__ int v_rd_base(int lane) { return ((lane & 3) << 3) | (((lane >> 2) & 3) << 6) | (((lane >> 4) & 1) << 5) | (((lane >> 5) & 1) << 8); }
; template <int OFF> __device__ __forceinline__ s16x4 tr_read(int vb) {
;   s16x4 r; asm volatile("ds_read_b64_tr_b16 %0, %1 offset:%2" : "=&v"(r) : "v"(vb), "i"(OFF) : "memory"); return r;
; }
; template <int D0> __device__ __forceinline__ void pv_one(f32x16& od, int vb, bf16x8 pa0, bf16x8 pa1, bf16x8 pa2, bf16x8 pa3) {
;   const s16x4 l0 = tr_read<v_rd_off(D0, 0, 0)>(vb), h0 = tr_read<v_rd_off(D0, 0, 1)>(vb), l1 = tr_read<v_rd_off(D0, 1, 0)>(vb), h1 = tr_read<v_rd_off(D0, 1, 1)>(vb);
;   const s16x4 l2 = tr_read<v_rd_off(D0, 2, 0)>(vb), h2 = tr_read<v_rd_off(D0, 2, 1)>(vb), l3 = tr_read<v_rd_off(D0, 3, 0)>(vb), h3 = tr_read<v_rd_off(D0, 3, 1)>(vb);
;   asm volatile("s_waitcnt lgkmcnt(0)" ::: "memory"); SBAR();
;     ...
;   od = __builtin_amdgcn_mfma_f32_32x32x16_bf16(pa0, PK(l0, h0), od, 0, 0, 0);
	v_mfma_f32_32x32x16_bf16 v[80:95], v[204:207], v[108:111], v[80:95]
	v_cvt_pk_bf16_f32 v193, v146, v147
	v_add_f32_e32 v222, v222, v146
	v_add_f32_e32 v254, v254, v147
	v_permlane32_swap_b32_e32 v189, v191
	s_waitcnt lgkmcnt(5)
	v_mfma_f32_32x32x16_bf16 v[64:79], v[208:211], v[104:107], v[64:79]
	ds_read_b64_tr_b16 v[200:201], v182 offset:49152
	ds_read_b64_tr_b16 v[202:203], v182 offset:51200
	v_cvt_pk_bf16_f32 v194, v148, v149
	v_add_f32_e32 v169, v169, v148
	v_add_f32_e32 v219, v219, v149
	s_waitcnt lgkmcnt(6)
	v_mfma_f32_32x32x16_bf16 v[80:95], v[212:215], v[104:107], v[80:95]
	ds_read_b64_tr_b16 v[204:205], v182 offset:53248
	ds_read_b64_tr_b16 v[206:207], v182 offset:55296
	v_cvt_pk_bf16_f32 v195, v150, v151
	v_add_f32_e32 v222, v222, v150
	v_add_f32_e32 v254, v254, v151
	s_waitcnt lgkmcnt(7)
	v_mfma_f32_32x32x16_bf16 v[64:79], v[230:233], v[100:103], v[64:79]
	ds_read_b64_tr_b16 v[208:209], v182 offset:57344
	ds_read_b64_tr_b16 v[210:211], v182 offset:59392
	v_cvt_pk_bf16_f32 v196, v152, v153
	v_add_f32_e32 v169, v169, v152
	v_add_f32_e32 v219, v219, v153
	v_permlane32_swap_b32_e32 v192, v194
	s_waitcnt lgkmcnt(8)
	v_mfma_f32_32x32x16_bf16 v[80:95], v[234:237], v[100:103], v[80:95]
	ds_read_b64_tr_b16 v[212:213], v182 offset:61440
	ds_read_b64_tr_b16 v[214:215], v182 offset:63488
	v_cvt_pk_bf16_f32 v197, v154, v155
	v_add_f32_e32 v222, v222, v154
	v_add_f32_e32 v254, v254, v155
	v_permlane32_swap_b32_e32 v193, v195
	s_waitcnt lgkmcnt(9)
	v_mfma_f32_32x32x16_bf16 v[64:79], v[238:241], v[96:99], v[64:79]
	ds_read_b64_tr_b16 v[230:231], v182 offset:49664
	ds_read_b64_tr_b16 v[232:233], v182 offset:51712
	v_cvt_pk_bf16_f32 v198, v156, v157
	v_add_f32_e32 v169, v169, v156
	v_add_f32_e32 v219, v219, v157
	s_waitcnt lgkmcnt(10)
	v_mfma_f32_32x32x16_bf16 v[80:95], v[242:245], v[96:99], v[80:95]
	ds_read_b64_tr_b16 v[234:235], v182 offset:53760
	ds_read_b64_tr_b16 v[236:237], v182 offset:55808
	v_cvt_pk_bf16_f32 v199, v158, v159
	v_add_f32_e32 v222, v222, v158
	v_add_f32_e32 v254, v254, v159
	v_permlane32_swap_b32_e32 v196, v198
	v_permlane32_swap_b32_e32 v197, v199
	s_waitcnt lgkmcnt(10)
	v_mfma_f32_32x32x16_bf16 v[0:15], v[184:187], v[200:203], v[0:15]
	ds_read_b64_tr_b16 v[238:239], v182 offset:57856
	ds_read_b64_tr_b16 v[240:241], v182 offset:59904
	v_exp_f32_e32 v64, v64
	v_exp_f32_e32 v65, v65
	s_waitcnt lgkmcnt(10)
	v_mfma_f32_32x32x16_bf16 v[0:15], v[188:191], v[204:207], v[0:15]
	ds_read_b64_tr_b16 v[242:243], v182 offset:61952
	ds_read_b64_tr_b16 v[244:245], v182 offset:64000
	v_exp_f32_e32 v66, v66
	v_exp_f32_e32 v67, v67
	s_waitcnt lgkmcnt(10)
	v_mfma_f32_32x32x16_bf16 v[0:15], v[192:195], v[208:211], v[0:15]
	ds_read_b64_tr_b16 v[200:201], v182 offset:50176
	ds_read_b64_tr_b16 v[202:203], v182 offset:52224
	v_exp_f32_e32 v68, v68
	v_exp_f32_e32 v69, v69
	s_waitcnt lgkmcnt(10)
	v_mfma_f32_32x32x16_bf16 v[0:15], v[196:199], v[212:215], v[0:15]
	ds_read_b64_tr_b16 v[204:205], v182 offset:54272
	ds_read_b64_tr_b16 v[206:207], v182 offset:56320
	v_exp_f32_e32 v70, v70
	v_exp_f32_e32 v71, v71
	s_waitcnt lgkmcnt(10)
	v_mfma_f32_32x32x16_bf16 v[48:63], v[184:187], v[230:233], v[48:63]
	ds_read_b64_tr_b16 v[208:209], v182 offset:58368
	ds_read_b64_tr_b16 v[210:211], v182 offset:60416
	v_exp_f32_e32 v72, v72
	v_exp_f32_e32 v73, v73
	s_waitcnt lgkmcnt(10)
	v_mfma_f32_32x32x16_bf16 v[48:63], v[188:191], v[234:237], v[48:63]
	ds_read_b64_tr_b16 v[212:213], v182 offset:62464
	ds_read_b64_tr_b16 v[214:215], v182 offset:64512
	v_exp_f32_e32 v74, v74
	v_exp_f32_e32 v75, v75
	s_waitcnt lgkmcnt(10)
	v_mfma_f32_32x32x16_bf16 v[48:63], v[192:195], v[238:241], v[48:63]
	ds_read_b64_tr_b16 v[230:231], v182 offset:50688
	ds_read_b64_tr_b16 v[232:233], v182 offset:52736
	v_exp_f32_e32 v76, v76
	v_exp_f32_e32 v77, v77
	s_waitcnt lgkmcnt(10)
	v_mfma_f32_32x32x16_bf16 v[48:63], v[196:199], v[242:245], v[48:63]
	ds_read_b64_tr_b16 v[234:235], v182 offset:54784
	ds_read_b64_tr_b16 v[236:237], v182 offset:56832
	v_exp_f32_e32 v78, v78
	v_exp_f32_e32 v79, v79
	s_waitcnt lgkmcnt(10)
	v_mfma_f32_32x32x16_bf16 v[32:47], v[184:187], v[200:203], v[32:47]
	ds_read_b64_tr_b16 v[238:239], v182 offset:58880
	ds_read_b64_tr_b16 v[240:241], v182 offset:60928
	v_exp_f32_e32 v80, v80
	v_exp_f32_e32 v81, v81
	s_waitcnt lgkmcnt(10)
	v_mfma_f32_32x32x16_bf16 v[32:47], v[188:191], v[204:207], v[32:47]
	ds_read_b64_tr_b16 v[242:243], v182 offset:62976
	ds_read_b64_tr_b16 v[244:245], v182 offset:65024
	v_exp_f32_e32 v82, v82
	v_exp_f32_e32 v83, v83
	s_waitcnt lgkmcnt(10)
	v_mfma_f32_32x32x16_bf16 v[32:47], v[192:195], v[208:211], v[32:47]
	v_exp_f32_e32 v84, v84
	v_exp_f32_e32 v85, v85
	s_waitcnt lgkmcnt(8)
	v_mfma_f32_32x32x16_bf16 v[32:47], v[196:199], v[212:215], v[32:47]
	v_exp_f32_e32 v86, v86
	v_exp_f32_e32 v87, v87
	s_waitcnt vmcnt(0)
	ds_write_b128 v181, v[246:249] offset:16384
	ds_write_b128 v181, v[250:253] offset:24576
	ds_write_b128 v180, v[176:179] offset:16384
	ds_write_b128 v180, v[160:163] offset:24576
	s_waitcnt lgkmcnt(10)
	v_mfma_f32_32x32x16_bf16 v[16:31], v[184:187], v[230:233], v[16:31]
	v_exp_f32_e32 v88, v88
	v_exp_f32_e32 v89, v89
	s_waitcnt lgkmcnt(8)
	v_mfma_f32_32x32x16_bf16 v[16:31], v[188:191], v[234:237], v[16:31]
	v_exp_f32_e32 v90, v90
	v_exp_f32_e32 v91, v91
	s_waitcnt lgkmcnt(6)
	v_mfma_f32_32x32x16_bf16 v[16:31], v[192:195], v[238:241], v[16:31]
	v_exp_f32_e32 v92, v92
	v_exp_f32_e32 v93, v93
	s_waitcnt lgkmcnt(4)
	v_mfma_f32_32x32x16_bf16 v[16:31], v[196:199], v[242:245], v[16:31]
	v_exp_f32_e32 v94, v94
	v_exp_f32_e32 v95, v95
	s_waitcnt lgkmcnt(0)
	s_barrier
	s_add_i32 s44, s44, 1
	s_cmp_lt_u32 s44, 63
	s_cbranch_scc1 .Ldense_loop
; __device__ __forceinline__ void finishSM(f32x16& p0, f32x16& p1, float alpha, float& l_reg, bf16x8& pa0, bf16x8& pa1, bf16x8& pa2, bf16x8& pa3) {
; #pragma unroll
;   for (int r = 0; r < 16; ++r) p1[r] = __builtin_amdgcn_exp2f(p1[r]);
;   float ps = 0;
; #pragma unroll
;   for (int r = 0; r < 16; ++r) ps += p0[r];
; #pragma unroll
;   for (int r = 0; r < 16; ++r) ps += p1[r];
;   { auto rr = __builtin_amdgcn_permlane32_swap(__float_as_uint(ps), __float_as_uint(ps), false, false);
;     ps = __uint_as_float(rr[0]) + __uint_as_float(rr[1]); }
;   l_reg = l_reg * alpha + ps;
;     ...
;   PK4(p0, 0, pa0); PK4(p0, 8, pa1); PK4(p1, 0, pa2); PK4(p1, 8, pa3);
;     ...
; }
; __device__ __forceinline__ void qkt(f32x16& p0, f32x16& p1, const bf16* Ks, const bf16x8* qr, int r32, int hi) {
;   p0 = f32x16{}; p1 = f32x16{};
; #pragma unroll
;   for (int d0 = 0; d0 < 8; ++d0) { int cb = (d0 * 16 + hi * 8) * 2;
;     bf16x8 b0 = *reinterpret_cast<const bf16x8*>((const char*)Ks + KSWZ(r32, cb));
;     bf16x8 b1 = *reinterpret_cast<const bf16x8*>((const char*)Ks + KSWZ(32 + r32, cb));
;     p0 = __builtin_amdgcn_mfma_f32_32x32x16_bf16(b0, qr[d0], p0, 0, 0, 0);
;     p1 = __builtin_amdgcn_mfma_f32_32x32x16_bf16(b1, qr[d0], p1, 0, 0, 0); }
; }
; __device__ __forceinline__ int v_st(int k, int c) { const int kk = (k & ~0xC) | ((k & 4) << 1) | ((k & 8) >> 1); return ((kk >> 3) * 4 + (c >> 5)) * 512 + ((kk & 7) * 32 + (c & 31)) * 2; }
; __device__ __forceinline__ int v_rd_base(int lane) { return ((lane & 3) << 3) | (((lane >> 2) & 3) << 6) | (((lane >> 4) & 1) << 5) | (((lane >> 5) & 1) << 8); }
; template <int OFF> __device__ __forceinline__ s16x4 tr_read(int vb) {
;   s16x4 r; asm volatile("ds_read_b64_tr_b16 %0, %1 offset:%2" : "=&v"(r) : "v"(vb), "i"(OFF) : "memory"); return r;
; }
; template <int D0> __device__ __forceinline__ void pv_one(f32x16& od, int vb, bf16x8 pa0, bf16x8 pa1, bf16x8 pa2, bf16x8 pa3) {
;   const s16x4 l0 = tr_read<v_rd_off(D0, 0, 0)>(vb), h0 = tr_read<v_rd_off(D0, 0, 1)>(vb), l1 = tr_read<v_rd_off(D0, 1, 0)>(vb), h1 = tr_read<v_rd_off(D0, 1, 1)>(vb);
;   const s16x4 l2 = tr_read<v_rd_off(D0, 2, 0)>(vb), h2 = tr_read<v_rd_off(D0, 2, 1)>(vb), l3 = tr_read<v_rd_off(D0, 3, 0)>(vb), h3 = tr_read<v_rd_off(D0, 3, 1)>(vb);
;   asm volatile("s_waitcnt lgkmcnt(0)" ::: "memory"); SBAR();
;     ...
;   od = __builtin_amdgcn_mfma_f32_32x32x16_bf16(pa0, PK(l0, h0), od, 0, 0, 0);
	global_load_dwordx4 v[246:249], v[216:217], off
	global_load_dwordx4 v[176:179], v[216:217], off offset:512
	global_load_dwordx4 v[250:253], v[166:167], off
	global_load_dwordx4 v[160:163], v[166:167], off offset:512
	v_lshl_add_u64 v[216:217], v[216:217], 0, s[0:1]
	v_lshl_add_u64 v[166:167], v[166:167], 0, s[0:1]
	ds_read_b128 v[200:203], v172 offset:16384
	ds_read_b128 v[204:207], v172 offset:24576
	ds_read_b128 v[208:211], v173 offset:16384
	ds_read_b128 v[212:215], v173 offset:24576
	ds_read_b128 v[230:233], v174 offset:16384
	ds_read_b128 v[234:237], v174 offset:24576
	ds_read_b128 v[238:241], v175 offset:16384
	ds_read_b128 v[242:245], v175 offset:24576
	s_waitcnt lgkmcnt(7)
	v_mfma_f32_32x32x16_bf16 v[128:143], v[200:203], v[124:127], 0
	ds_read_b128 v[200:203], v172 offset:16512
	v_cvt_pk_bf16_f32 v184, v64, v65
	v_add_f32_e32 v169, v169, v64
	v_add_f32_e32 v219, v219, v65
	s_waitcnt lgkmcnt(7)
	v_mfma_f32_32x32x16_bf16 v[144:159], v[204:207], v[124:127], 0
	ds_read_b128 v[204:207], v172 offset:24704
	v_cvt_pk_bf16_f32 v185, v66, v67
	v_add_f32_e32 v222, v222, v66
	v_add_f32_e32 v254, v254, v67
	s_waitcnt lgkmcnt(7)
	v_mfma_f32_32x32x16_bf16 v[128:143], v[208:211], v[120:123], v[128:143]
	ds_read_b128 v[208:211], v173 offset:16512
	v_cvt_pk_bf16_f32 v186, v68, v69
	v_add_f32_e32 v169, v169, v68
	v_add_f32_e32 v219, v219, v69
	s_waitcnt lgkmcnt(7)
	v_mfma_f32_32x32x16_bf16 v[144:159], v[212:215], v[120:123], v[144:159]
	ds_read_b128 v[212:215], v173 offset:24704
	v_cvt_pk_bf16_f32 v187, v70, v71
	v_add_f32_e32 v222, v222, v70
	v_add_f32_e32 v254, v254, v71
	s_waitcnt lgkmcnt(7)
	v_mfma_f32_32x32x16_bf16 v[128:143], v[230:233], v[116:119], v[128:143]
	ds_read_b128 v[230:233], v174 offset:16512
	v_cvt_pk_bf16_f32 v188, v72, v73
	v_add_f32_e32 v169, v169, v72
	v_add_f32_e32 v219, v219, v73
	v_permlane32_swap_b32_e32 v184, v186
	s_waitcnt lgkmcnt(7)
	v_mfma_f32_32x32x16_bf16 v[144:159], v[234:237], v[116:119], v[144:159]
	ds_read_b128 v[234:237], v174 offset:24704
	v_cvt_pk_bf16_f32 v189, v74, v75
	v_add_f32_e32 v222, v222, v74
	v_add_f32_e32 v254, v254, v75
	v_permlane32_swap_b32_e32 v185, v187
	s_waitcnt lgkmcnt(7)
	v_mfma_f32_32x32x16_bf16 v[128:143], v[238:241], v[112:115], v[128:143]
	ds_read_b128 v[238:241], v175 offset:16512
	v_cvt_pk_bf16_f32 v190, v76, v77
	v_add_f32_e32 v169, v169, v76
	v_add_f32_e32 v219, v219, v77
	s_waitcnt lgkmcnt(7)
	v_mfma_f32_32x32x16_bf16 v[144:159], v[242:245], v[112:115], v[144:159]
	ds_read_b128 v[242:245], v175 offset:24704
	v_cvt_pk_bf16_f32 v191, v78, v79
	v_add_f32_e32 v222, v222, v78
	v_add_f32_e32 v254, v254, v79
	s_waitcnt lgkmcnt(7)
	v_mfma_f32_32x32x16_bf16 v[128:143], v[200:203], v[108:111], v[128:143]
	v_cvt_pk_bf16_f32 v192, v80, v81
	v_add_f32_e32 v169, v169, v80
	v_add_f32_e32 v219, v219, v81
	v_permlane32_swap_b32_e32 v188, v190
	s_waitcnt lgkmcnt(6)
	v_mfma_f32_32x32x16_bf16 v[144:159], v[204:207], v[108:111], v[144:159]
	v_cvt_pk_bf16_f32 v193, v82, v83
	v_add_f32_e32 v222, v222, v82
	v_add_f32_e32 v254, v254, v83
	v_permlane32_swap_b32_e32 v189, v191
	s_waitcnt lgkmcnt(5)
	v_mfma_f32_32x32x16_bf16 v[128:143], v[208:211], v[104:107], v[128:143]
	ds_read_b64_tr_b16 v[200:201], v182 offset:0
	ds_read_b64_tr_b16 v[202:203], v182 offset:2048
	v_cvt_pk_bf16_f32 v194, v84, v85
	v_add_f32_e32 v169, v169, v84
	v_add_f32_e32 v219, v219, v85
	s_waitcnt lgkmcnt(6)
	v_mfma_f32_32x32x16_bf16 v[144:159], v[212:215], v[104:107], v[144:159]
	ds_read_b64_tr_b16 v[204:205], v182 offset:4096
	ds_read_b64_tr_b16 v[206:207], v182 offset:6144
	v_cvt_pk_bf16_f32 v195, v86, v87
	v_add_f32_e32 v222, v222, v86
	v_add_f32_e32 v254, v254, v87
	s_waitcnt lgkmcnt(7)
	v_mfma_f32_32x32x16_bf16 v[128:143], v[230:233], v[100:103], v[128:143]
	ds_read_b64_tr_b16 v[208:209], v182 offset:8192
	ds_read_b64_tr_b16 v[210:211], v182 offset:10240
	v_cvt_pk_bf16_f32 v196, v88, v89
	v_add_f32_e32 v169, v169, v88
	v_add_f32_e32 v219, v219, v89
	v_permlane32_swap_b32_e32 v192, v194
	s_waitcnt lgkmcnt(8)
	v_mfma_f32_32x32x16_bf16 v[144:159], v[234:237], v[100:103], v[144:159]
	ds_read_b64_tr_b16 v[212:213], v182 offset:12288
	ds_read_b64_tr_b16 v[214:215], v182 offset:14336
	v_cvt_pk_bf16_f32 v197, v90, v91
	v_add_f32_e32 v222, v222, v90
	v_add_f32_e32 v254, v254, v91
	v_permlane32_swap_b32_e32 v193, v195
	s_waitcnt lgkmcnt(9)
	v_mfma_f32_32x32x16_bf16 v[128:143], v[238:241], v[96:99], v[128:143]
	ds_read_b64_tr_b16 v[230:231], v182 offset:512
	ds_read_b64_tr_b16 v[232:233], v182 offset:2560
	v_cvt_pk_bf16_f32 v198, v92, v93
	v_add_f32_e32 v169, v169, v92
	v_add_f32_e32 v219, v219, v93
	s_waitcnt lgkmcnt(10)
	v_mfma_f32_32x32x16_bf16 v[144:159], v[242:245], v[96:99], v[144:159]
	ds_read_b64_tr_b16 v[234:235], v182 offset:4608
	ds_read_b64_tr_b16 v[236:237], v182 offset:6656
	v_cvt_pk_bf16_f32 v199, v94, v95
	v_add_f32_e32 v222, v222, v94
	v_add_f32_e32 v254, v254, v95
	v_permlane32_swap_b32_e32 v196, v198
	v_permlane32_swap_b32_e32 v197, v199
	s_waitcnt lgkmcnt(10)
	v_mfma_f32_32x32x16_bf16 v[0:15], v[184:187], v[200:203], v[0:15]
	ds_read_b64_tr_b16 v[238:239], v182 offset:8704
	ds_read_b64_tr_b16 v[240:241], v182 offset:10752
	v_exp_f32_e32 v128, v128
	v_exp_f32_e32 v129, v129
	s_waitcnt lgkmcnt(10)
	v_mfma_f32_32x32x16_bf16 v[0:15], v[188:191], v[204:207], v[0:15]
	ds_read_b64_tr_b16 v[242:243], v182 offset:12800
	ds_read_b64_tr_b16 v[244:245], v182 offset:14848
	v_exp_f32_e32 v130, v130
	v_exp_f32_e32 v131, v131
	s_waitcnt lgkmcnt(10)
	v_mfma_f32_32x32x16_bf16 v[0:15], v[192:195], v[208:211], v[0:15]
	ds_read_b64_tr_b16 v[200:201], v182 offset:1024
	ds_read_b64_tr_b16 v[202:203], v182 offset:3072
	v_exp_f32_e32 v132, v132
	v_exp_f32_e32 v133, v133
	s_waitcnt lgkmcnt(10)
; __device__ __forceinline__ void finishSM(f32x16& p0, f32x16& p1, float alpha, float& l_reg, bf16x8& pa0, bf16x8& pa1, bf16x8& pa2, bf16x8& pa3) {
; #pragma unroll
;   for (int r = 0; r < 16; ++r) p1[r] = __builtin_amdgcn_exp2f(p1[r]);
;   float ps = 0;
; #pragma unroll
;   for (int r = 0; r < 16; ++r) ps += p0[r];
; #pragma unroll
;   for (int r = 0; r < 16; ++r) ps += p1[r];
;   { auto rr = __builtin_amdgcn_permlane32_swap(__float_as_uint(ps), __float_as_uint(ps), false, false);
;     ps = __uint_as_float(rr[0]) + __uint_as_float(rr[1]); }
;   l_reg = l_reg * alpha + ps;
;     ...
;   PK4(p0, 0, pa0); PK4(p0, 8, pa1); PK4(p1, 0, pa2); PK4(p1, 8, pa3);
;     ...
; }
; __device__ __forceinline__ void qkt(f32x16& p0, f32x16& p1, const bf16* Ks, const bf16x8* qr, int r32, int hi) {
;   p0 = f32x16{}; p1 = f32x16{};
; #pragma unroll
;   for (int d0 = 0; d0 < 8; ++d0) { int cb = (d0 * 16 + hi * 8) * 2;
;     bf16x8 b0 = *reinterpret_cast<const bf16x8*>((const char*)Ks + KSWZ(r32, cb));
;     bf16x8 b1 = *reinterpret_cast<const bf16x8*>((const char*)Ks + KSWZ(32 + r32, cb));
;     p0 = __builtin_amdgcn_mfma_f32_32x32x16_bf16(b0, qr[d0], p0, 0, 0, 0);
;     p1 = __builtin_amdgcn_mfma_f32_32x32x16_bf16(b1, qr[d0], p1, 0, 0, 0); }
; }
; __device__ __forceinline__ int v_st(int k, int c) { const int kk = (k & ~0xC) | ((k & 4) << 1) | ((k & 8) >> 1); return ((kk >> 3) * 4 + (c >> 5)) * 512 + ((kk & 7) * 32 + (c & 31)) * 2; }
; __device__ __forceinline__ int v_rd_base(int lane) { return ((lane & 3) << 3) | (((lane >> 2) & 3) << 6) | (((lane >> 4) & 1) << 5) | (((lane >> 5) & 1) << 8); }
; template <int OFF> __device__ __forceinline__ s16x4 tr_read(int vb) {
;   s16x4 r; asm volatile("ds_read_b64_tr_b16 %0, %1 offset:%2" : "=&v"(r) : "v"(vb), "i"(OFF) : "memory"); return r;
; }
; template <int D0> __device__ __forceinline__ void pv_one(f32x16& od, int vb, bf16x8 pa0, bf16x8 pa1, bf16x8 pa2, bf16x8 pa3) {
;   const s16x4 l0 = tr_read<v_rd_off(D0, 0, 0)>(vb), h0 = tr_read<v_rd_off(D0, 0, 1)>(vb), l1 = tr_read<v_rd_off(D0, 1, 0)>(vb), h1 = tr_read<v_rd_off(D0, 1, 1)>(vb);
;   const s16x4 l2 = tr_read<v_rd_off(D0, 2, 0)>(vb), h2 = tr_read<v_rd_off(D0, 2, 1)>(vb), l3 = tr_read<v_rd_off(D0, 3, 0)>(vb), h3 = tr_read<v_rd_off(D0, 3, 1)>(vb);
;   asm volatile("s_waitcnt lgkmcnt(0)" ::: "memory"); SBAR();
;     ...
;   od = __builtin_amdgcn_mfma_f32_32x32x16_bf16(pa0, PK(l0, h0), od, 0, 0, 0);
	v_mfma_f32_32x32x16_bf16 v[0:15], v[196:199], v[212:215], v[0:15]
	ds_read_b64_tr_b16 v[204:205], v182 offset:5120
	ds_read_b64_tr_b16 v[206:207], v182 offset:7168
	v_exp_f32_e32 v134, v134
	v_exp_f32_e32 v135, v135
	s_waitcnt lgkmcnt(10)
	v_mfma_f32_32x32x16_bf16 v[48:63], v[184:187], v[230:233], v[48:63]
	ds_read_b64_tr_b16 v[208:209], v182 offset:9216
	ds_read_b64_tr_b16 v[210:211], v182 offset:11264
	v_exp_f32_e32 v136, v136
	v_exp_f32_e32 v137, v137
	s_waitcnt lgkmcnt(10)
	v_mfma_f32_32x32x16_bf16 v[48:63], v[188:191], v[234:237], v[48:63]
	ds_read_b64_tr_b16 v[212:213], v182 offset:13312
	ds_read_b64_tr_b16 v[214:215], v182 offset:15360
	v_exp_f32_e32 v138, v138
	v_exp_f32_e32 v139, v139
	s_waitcnt lgkmcnt(10)
	v_mfma_f32_32x32x16_bf16 v[48:63], v[192:195], v[238:241], v[48:63]
	ds_read_b64_tr_b16 v[230:231], v182 offset:1536
	ds_read_b64_tr_b16 v[232:233], v182 offset:3584
	v_exp_f32_e32 v140, v140
	v_exp_f32_e32 v141, v141
	s_waitcnt lgkmcnt(10)
	v_mfma_f32_32x32x16_bf16 v[48:63], v[196:199], v[242:245], v[48:63]
	ds_read_b64_tr_b16 v[234:235], v182 offset:5632
	ds_read_b64_tr_b16 v[236:237], v182 offset:7680
	v_exp_f32_e32 v142, v142
	v_exp_f32_e32 v143, v143
	s_waitcnt lgkmcnt(10)
	v_mfma_f32_32x32x16_bf16 v[32:47], v[184:187], v[200:203], v[32:47]
	ds_read_b64_tr_b16 v[238:239], v182 offset:9728
	ds_read_b64_tr_b16 v[240:241], v182 offset:11776
	v_exp_f32_e32 v144, v144
	v_exp_f32_e32 v145, v145
	s_waitcnt lgkmcnt(10)
	v_mfma_f32_32x32x16_bf16 v[32:47], v[188:191], v[204:207], v[32:47]
	ds_read_b64_tr_b16 v[242:243], v182 offset:13824
	ds_read_b64_tr_b16 v[244:245], v182 offset:15872
	v_exp_f32_e32 v146, v146
	v_exp_f32_e32 v147, v147
	s_waitcnt lgkmcnt(10)
	v_mfma_f32_32x32x16_bf16 v[32:47], v[192:195], v[208:211], v[32:47]
	v_exp_f32_e32 v148, v148
	v_exp_f32_e32 v149, v149
	s_waitcnt lgkmcnt(8)
	v_mfma_f32_32x32x16_bf16 v[32:47], v[196:199], v[212:215], v[32:47]
	v_exp_f32_e32 v150, v150
	v_exp_f32_e32 v151, v151
	s_waitcnt vmcnt(0)
	ds_write_b128 v181, v[246:249] offset:32768
	ds_write_b128 v181, v[250:253] offset:40960
	ds_write_b128 v180, v[176:179] offset:32768
	ds_write_b128 v180, v[160:163] offset:40960
	s_waitcnt lgkmcnt(10)
	v_mfma_f32_32x32x16_bf16 v[16:31], v[184:187], v[230:233], v[16:31]
	v_exp_f32_e32 v152, v152
	v_exp_f32_e32 v153, v153
	s_waitcnt lgkmcnt(8)
	v_mfma_f32_32x32x16_bf16 v[16:31], v[188:191], v[234:237], v[16:31]
	v_exp_f32_e32 v154, v154
	v_exp_f32_e32 v155, v155
	s_waitcnt lgkmcnt(6)
	v_mfma_f32_32x32x16_bf16 v[16:31], v[192:195], v[238:241], v[16:31]
	v_exp_f32_e32 v156, v156
	v_exp_f32_e32 v157, v157
	s_waitcnt lgkmcnt(4)
	v_mfma_f32_32x32x16_bf16 v[16:31], v[196:199], v[242:245], v[16:31]
	v_exp_f32_e32 v158, v158
	v_exp_f32_e32 v159, v159
	s_waitcnt lgkmcnt(0)
	s_barrier
	global_load_dwordx4 v[246:249], v[216:217], off
	global_load_dwordx4 v[176:179], v[216:217], off offset:512
	global_load_dwordx4 v[250:253], v[166:167], off
	global_load_dwordx4 v[160:163], v[166:167], off offset:512
	v_lshl_add_u64 v[216:217], v[216:217], 0, s[0:1]
	v_lshl_add_u64 v[166:167], v[166:167], 0, s[0:1]
	ds_read_b128 v[200:203], v172 offset:32768
	ds_read_b128 v[204:207], v172 offset:40960
	ds_read_b128 v[208:211], v173 offset:32768
	ds_read_b128 v[212:215], v173 offset:40960
	ds_read_b128 v[230:233], v174 offset:32768
	ds_read_b128 v[234:237], v174 offset:40960
	ds_read_b128 v[238:241], v175 offset:32768
	ds_read_b128 v[242:245], v175 offset:40960
	s_waitcnt lgkmcnt(7)
	v_mfma_f32_32x32x16_bf16 v[64:79], v[200:203], v[124:127], 0
	ds_read_b128 v[200:203], v172 offset:32896
	v_cvt_pk_bf16_f32 v184, v128, v129
	v_add_f32_e32 v169, v169, v128
	v_add_f32_e32 v219, v219, v129
	s_waitcnt lgkmcnt(7)
	v_mfma_f32_32x32x16_bf16 v[80:95], v[204:207], v[124:127], 0
	ds_read_b128 v[204:207], v172 offset:41088
	v_cvt_pk_bf16_f32 v185, v130, v131
	v_add_f32_e32 v222, v222, v130
	v_add_f32_e32 v254, v254, v131
	s_waitcnt lgkmcnt(7)
	v_mfma_f32_32x32x16_bf16 v[64:79], v[208:211], v[120:123], v[64:79]
	ds_read_b128 v[208:211], v173 offset:32896
	v_cvt_pk_bf16_f32 v186, v132, v133
	v_add_f32_e32 v169, v169, v132
	v_add_f32_e32 v219, v219, v133
	s_waitcnt lgkmcnt(7)
	v_mfma_f32_32x32x16_bf16 v[80:95], v[212:215], v[120:123], v[80:95]
	ds_read_b128 v[212:215], v173 offset:41088
	v_cvt_pk_bf16_f32 v187, v134, v135
	v_add_f32_e32 v222, v222, v134
	v_add_f32_e32 v254, v254, v135
	s_waitcnt lgkmcnt(7)
	v_mfma_f32_32x32x16_bf16 v[64:79], v[230:233], v[116:119], v[64:79]
	ds_read_b128 v[230:233], v174 offset:32896
	v_cvt_pk_bf16_f32 v188, v136, v137
	v_add_f32_e32 v169, v169, v136
	v_add_f32_e32 v219, v219, v137
	v_permlane32_swap_b32_e32 v184, v186
	s_waitcnt lgkmcnt(7)
	v_mfma_f32_32x32x16_bf16 v[80:95], v[234:237], v[116:119], v[80:95]
	ds_read_b128 v[234:237], v174 offset:41088
	v_cvt_pk_bf16_f32 v189, v138, v139
	v_add_f32_e32 v222, v222, v138
	v_add_f32_e32 v254, v254, v139
	v_permlane32_swap_b32_e32 v185, v187
	s_waitcnt lgkmcnt(7)
	v_mfma_f32_32x32x16_bf16 v[64:79], v[238:241], v[112:115], v[64:79]
	ds_read_b128 v[238:241], v175 offset:32896
	v_cvt_pk_bf16_f32 v190, v140, v141
	v_add_f32_e32 v169, v169, v140
	v_add_f32_e32 v219, v219, v141
	s_waitcnt lgkmcnt(7)
	v_mfma_f32_32x32x16_bf16 v[80:95], v[242:245], v[112:115], v[80:95]
	ds_read_b128 v[242:245], v175 offset:41088
	v_cvt_pk_bf16_f32 v191, v142, v143
	v_add_f32_e32 v222, v222, v142
	v_add_f32_e32 v254, v254, v143
	s_waitcnt lgkmcnt(7)
	v_mfma_f32_32x32x16_bf16 v[64:79], v[200:203], v[108:111], v[64:79]
	v_cvt_pk_bf16_f32 v192, v144, v145
	v_add_f32_e32 v169, v169, v144
	v_add_f32_e32 v219, v219, v145
	v_permlane32_swap_b32_e32 v188, v190
	s_waitcnt lgkmcnt(6)
; __device__ __forceinline__ void finishSM(f32x16& p0, f32x16& p1, float alpha, float& l_reg, bf16x8& pa0, bf16x8& pa1, bf16x8& pa2, bf16x8& pa3) {
; #pragma unroll
;   for (int r = 0; r < 16; ++r) p1[r] = __builtin_amdgcn_exp2f(p1[r]);
;   float ps = 0;
; #pragma unroll
;   for (int r = 0; r < 16; ++r) ps += p0[r];
; #pragma unroll
;   for (int r = 0; r < 16; ++r) ps += p1[r];
;   { auto rr = __builtin_amdgcn_permlane32_swap(__float_as_uint(ps), __float_as_uint(ps), false, false);
;     ps = __uint_as_float(rr[0]) + __uint_as_float(rr[1]); }
;   l_reg = l_reg * alpha + ps;
;     ...
;   PK4(p0, 0, pa0); PK4(p0, 8, pa1); PK4(p1, 0, pa2); PK4(p1, 8, pa3);
;     ...
; }
; __device__ __forceinline__ void qkt(f32x16& p0, f32x16& p1, const bf16* Ks, const bf16x8* qr, int r32, int hi) {
;   p0 = f32x16{}; p1 = f32x16{};
; #pragma unroll
;   for (int d0 = 0; d0 < 8; ++d0) { int cb = (d0 * 16 + hi * 8) * 2;
;     bf16x8 b0 = *reinterpret_cast<const bf16x8*>((const char*)Ks + KSWZ(r32, cb));
;     bf16x8 b1 = *reinterpret_cast<const bf16x8*>((const char*)Ks + KSWZ(32 + r32, cb));
;     p0 = __builtin_amdgcn_mfma_f32_32x32x16_bf16(b0, qr[d0], p0, 0, 0, 0);
;     p1 = __builtin_amdgcn_mfma_f32_32x32x16_bf16(b1, qr[d0], p1, 0, 0, 0); }
; }
; __device__ __forceinline__ int v_st(int k, int c) { const int kk = (k & ~0xC) | ((k & 4) << 1) | ((k & 8) >> 1); return ((kk >> 3) * 4 + (c >> 5)) * 512 + ((kk & 7) * 32 + (c & 31)) * 2; }
; __device__ __forceinline__ int v_rd_base(int lane) { return ((lane & 3) << 3) | (((lane >> 2) & 3) << 6) | (((lane >> 4) & 1) << 5) | (((lane >> 5) & 1) << 8); }
; template <int OFF> __device__ __forceinline__ s16x4 tr_read(int vb) {
;   s16x4 r; asm volatile("ds_read_b64_tr_b16 %0, %1 offset:%2" : "=&v"(r) : "v"(vb), "i"(OFF) : "memory"); return r;
; }
; template <int D0> __device__ __forceinline__ void pv_one(f32x16& od, int vb, bf16x8 pa0, bf16x8 pa1, bf16x8 pa2, bf16x8 pa3) {
;   const s16x4 l0 = tr_read<v_rd_off(D0, 0, 0)>(vb), h0 = tr_read<v_rd_off(D0, 0, 1)>(vb), l1 = tr_read<v_rd_off(D0, 1, 0)>(vb), h1 = tr_read<v_rd_off(D0, 1, 1)>(vb);
;   const s16x4 l2 = tr_read<v_rd_off(D0, 2, 0)>(vb), h2 = tr_read<v_rd_off(D0, 2, 1)>(vb), l3 = tr_read<v_rd_off(D0, 3, 0)>(vb), h3 = tr_read<v_rd_off(D0, 3, 1)>(vb);
;   asm volatile("s_waitcnt lgkmcnt(0)" ::: "memory"); SBAR();
;     ...
;   od = __builtin_amdgcn_mfma_f32_32x32x16_bf16(pa0, PK(l0, h0), od, 0, 0, 0);
	v_mfma_f32_32x32x16_bf16 v[80:95], v[204:207], v[108:111], v[80:95]
	v_cvt_pk_bf16_f32 v193, v146, v147
	v_add_f32_e32 v222, v222, v146
	v_add_f32_e32 v254, v254, v147
	v_permlane32_swap_b32_e32 v189, v191
	s_waitcnt lgkmcnt(5)
	v_mfma_f32_32x32x16_bf16 v[64:79], v[208:211], v[104:107], v[64:79]
	ds_read_b64_tr_b16 v[200:201], v182 offset:16384
	ds_read_b64_tr_b16 v[202:203], v182 offset:18432
	v_cvt_pk_bf16_f32 v194, v148, v149
	v_add_f32_e32 v169, v169, v148
	v_add_f32_e32 v219, v219, v149
	s_waitcnt lgkmcnt(6)
	v_mfma_f32_32x32x16_bf16 v[80:95], v[212:215], v[104:107], v[80:95]
	ds_read_b64_tr_b16 v[204:205], v182 offset:20480
	ds_read_b64_tr_b16 v[206:207], v182 offset:22528
	v_cvt_pk_bf16_f32 v195, v150, v151
	v_add_f32_e32 v222, v222, v150
	v_add_f32_e32 v254, v254, v151
	s_waitcnt lgkmcnt(7)
	v_mfma_f32_32x32x16_bf16 v[64:79], v[230:233], v[100:103], v[64:79]
	ds_read_b64_tr_b16 v[208:209], v182 offset:24576
	ds_read_b64_tr_b16 v[210:211], v182 offset:26624
	v_cvt_pk_bf16_f32 v196, v152, v153
	v_add_f32_e32 v169, v169, v152
	v_add_f32_e32 v219, v219, v153
	v_permlane32_swap_b32_e32 v192, v194
	s_waitcnt lgkmcnt(8)
	v_mfma_f32_32x32x16_bf16 v[80:95], v[234:237], v[100:103], v[80:95]
	ds_read_b64_tr_b16 v[212:213], v182 offset:28672
	ds_read_b64_tr_b16 v[214:215], v182 offset:30720
	v_cvt_pk_bf16_f32 v197, v154, v155
	v_add_f32_e32 v222, v222, v154
	v_add_f32_e32 v254, v254, v155
	v_permlane32_swap_b32_e32 v193, v195
	s_waitcnt lgkmcnt(9)
	v_mfma_f32_32x32x16_bf16 v[64:79], v[238:241], v[96:99], v[64:79]
	ds_read_b64_tr_b16 v[230:231], v182 offset:16896
	ds_read_b64_tr_b16 v[232:233], v182 offset:18944
	v_cvt_pk_bf16_f32 v198, v156, v157
	v_add_f32_e32 v169, v169, v156
	v_add_f32_e32 v219, v219, v157
	s_waitcnt lgkmcnt(10)
	v_mfma_f32_32x32x16_bf16 v[80:95], v[242:245], v[96:99], v[80:95]
	ds_read_b64_tr_b16 v[234:235], v182 offset:20992
	ds_read_b64_tr_b16 v[236:237], v182 offset:23040
	v_cvt_pk_bf16_f32 v199, v158, v159
	v_add_f32_e32 v222, v222, v158
	v_add_f32_e32 v254, v254, v159
	v_permlane32_swap_b32_e32 v196, v198
	v_permlane32_swap_b32_e32 v197, v199
	s_waitcnt lgkmcnt(10)
	v_mfma_f32_32x32x16_bf16 v[0:15], v[184:187], v[200:203], v[0:15]
	ds_read_b64_tr_b16 v[238:239], v182 offset:25088
	ds_read_b64_tr_b16 v[240:241], v182 offset:27136
	v_exp_f32_e32 v64, v64
	v_exp_f32_e32 v65, v65
	s_waitcnt lgkmcnt(10)
	v_mfma_f32_32x32x16_bf16 v[0:15], v[188:191], v[204:207], v[0:15]
	ds_read_b64_tr_b16 v[242:243], v182 offset:29184
	ds_read_b64_tr_b16 v[244:245], v182 offset:31232
	v_exp_f32_e32 v66, v66
	v_exp_f32_e32 v67, v67
	s_waitcnt lgkmcnt(10)
	v_mfma_f32_32x32x16_bf16 v[0:15], v[192:195], v[208:211], v[0:15]
	ds_read_b64_tr_b16 v[200:201], v182 offset:17408
	ds_read_b64_tr_b16 v[202:203], v182 offset:19456
	v_exp_f32_e32 v68, v68
	v_exp_f32_e32 v69, v69
	s_waitcnt lgkmcnt(10)
	v_mfma_f32_32x32x16_bf16 v[0:15], v[196:199], v[212:215], v[0:15]
	ds_read_b64_tr_b16 v[204:205], v182 offset:21504
	ds_read_b64_tr_b16 v[206:207], v182 offset:23552
	v_exp_f32_e32 v70, v70
	v_exp_f32_e32 v71, v71
	s_waitcnt lgkmcnt(10)
	v_mfma_f32_32x32x16_bf16 v[48:63], v[184:187], v[230:233], v[48:63]
	ds_read_b64_tr_b16 v[208:209], v182 offset:25600
	ds_read_b64_tr_b16 v[210:211], v182 offset:27648
	v_exp_f32_e32 v72, v72
	v_exp_f32_e32 v73, v73
	s_waitcnt lgkmcnt(10)
	v_mfma_f32_32x32x16_bf16 v[48:63], v[188:191], v[234:237], v[48:63]
	ds_read_b64_tr_b16 v[212:213], v182 offset:29696
	ds_read_b64_tr_b16 v[214:215], v182 offset:31744
	v_exp_f32_e32 v74, v74
	v_exp_f32_e32 v75, v75
	s_waitcnt lgkmcnt(10)
	v_mfma_f32_32x32x16_bf16 v[48:63], v[192:195], v[238:241], v[48:63]
	ds_read_b64_tr_b16 v[230:231], v182 offset:17920
	ds_read_b64_tr_b16 v[232:233], v182 offset:19968
	v_exp_f32_e32 v76, v76
	v_exp_f32_e32 v77, v77
	s_waitcnt lgkmcnt(10)
	v_mfma_f32_32x32x16_bf16 v[48:63], v[196:199], v[242:245], v[48:63]
	ds_read_b64_tr_b16 v[234:235], v182 offset:22016
	ds_read_b64_tr_b16 v[236:237], v182 offset:24064
	v_exp_f32_e32 v78, v78
	v_exp_f32_e32 v79, v79
	s_waitcnt lgkmcnt(10)
	v_mfma_f32_32x32x16_bf16 v[32:47], v[184:187], v[200:203], v[32:47]
	ds_read_b64_tr_b16 v[238:239], v182 offset:26112
	ds_read_b64_tr_b16 v[240:241], v182 offset:28160
	v_exp_f32_e32 v80, v80
	v_exp_f32_e32 v81, v81
	s_waitcnt lgkmcnt(10)
	v_mfma_f32_32x32x16_bf16 v[32:47], v[188:191], v[204:207], v[32:47]
	ds_read_b64_tr_b16 v[242:243], v182 offset:30208
	ds_read_b64_tr_b16 v[244:245], v182 offset:32256
	v_exp_f32_e32 v82, v82
	v_exp_f32_e32 v83, v83
	s_waitcnt lgkmcnt(10)
	v_mfma_f32_32x32x16_bf16 v[32:47], v[192:195], v[208:211], v[32:47]
	v_exp_f32_e32 v84, v84
	v_exp_f32_e32 v85, v85
	s_waitcnt lgkmcnt(8)
	v_mfma_f32_32x32x16_bf16 v[32:47], v[196:199], v[212:215], v[32:47]
	v_exp_f32_e32 v86, v86
	v_exp_f32_e32 v87, v87
	s_waitcnt vmcnt(0)
	ds_write_b128 v181, v[246:249] offset:49152
	ds_write_b128 v181, v[250:253] offset:57344
	ds_write_b128 v180, v[176:179] offset:49152
	ds_write_b128 v180, v[160:163] offset:57344
	s_waitcnt lgkmcnt(10)
	v_mfma_f32_32x32x16_bf16 v[16:31], v[184:187], v[230:233], v[16:31]
	v_exp_f32_e32 v88, v88
	v_exp_f32_e32 v89, v89
	s_waitcnt lgkmcnt(8)
	v_mfma_f32_32x32x16_bf16 v[16:31], v[188:191], v[234:237], v[16:31]
	v_exp_f32_e32 v90, v90
	v_exp_f32_e32 v91, v91
	s_waitcnt lgkmcnt(6)
	v_mfma_f32_32x32x16_bf16 v[16:31], v[192:195], v[238:241], v[16:31]
	v_exp_f32_e32 v92, v92
	v_exp_f32_e32 v93, v93
	s_waitcnt lgkmcnt(4)
	v_mfma_f32_32x32x16_bf16 v[16:31], v[196:199], v[242:245], v[16:31]
	v_exp_f32_e32 v94, v94
	v_exp_f32_e32 v95, v95
	s_waitcnt lgkmcnt(0)
	s_barrier
; __device__ __forceinline__ void finishSM(f32x16& p0, f32x16& p1, float alpha, float& l_reg, bf16x8& pa0, bf16x8& pa1, bf16x8& pa2, bf16x8& pa3) {
; #pragma unroll
;   for (int r = 0; r < 16; ++r) p1[r] = __builtin_amdgcn_exp2f(p1[r]);
;   float ps = 0;
; #pragma unroll
;   for (int r = 0; r < 16; ++r) ps += p0[r];
; #pragma unroll
;   for (int r = 0; r < 16; ++r) ps += p1[r];
;   { auto rr = __builtin_amdgcn_permlane32_swap(__float_as_uint(ps), __float_as_uint(ps), false, false);
;     ps = __uint_as_float(rr[0]) + __uint_as_float(rr[1]); }
;   l_reg = l_reg * alpha + ps;
;     ...
;   PK4(p0, 0, pa0); PK4(p0, 8, pa1); PK4(p1, 0, pa2); PK4(p1, 8, pa3);
;     ...
; }
; __device__ __forceinline__ void qkt(f32x16& p0, f32x16& p1, const bf16* Ks, const bf16x8* qr, int r32, int hi) {
;   p0 = f32x16{}; p1 = f32x16{};
; #pragma unroll
;   for (int d0 = 0; d0 < 8; ++d0) { int cb = (d0 * 16 + hi * 8) * 2;
;     bf16x8 b0 = *reinterpret_cast<const bf16x8*>((const char*)Ks + KSWZ(r32, cb));
;     bf16x8 b1 = *reinterpret_cast<const bf16x8*>((const char*)Ks + KSWZ(32 + r32, cb));
;     p0 = __builtin_amdgcn_mfma_f32_32x32x16_bf16(b0, qr[d0], p0, 0, 0, 0);
;     p1 = __builtin_amdgcn_mfma_f32_32x32x16_bf16(b1, qr[d0], p1, 0, 0, 0); }
; }
; __device__ __forceinline__ int v_st(int k, int c) { const int kk = (k & ~0xC) | ((k & 4) << 1) | ((k & 8) >> 1); return ((kk >> 3) * 4 + (c >> 5)) * 512 + ((kk & 7) * 32 + (c & 31)) * 2; }
; __device__ __forceinline__ int v_rd_base(int lane) { return ((lane & 3) << 3) | (((lane >> 2) & 3) << 6) | (((lane >> 4) & 1) << 5) | (((lane >> 5) & 1) << 8); }
; template <int OFF> __device__ __forceinline__ s16x4 tr_read(int vb) {
;   s16x4 r; asm volatile("ds_read_b64_tr_b16 %0, %1 offset:%2" : "=&v"(r) : "v"(vb), "i"(OFF) : "memory"); return r;
; }
; template <int D0> __device__ __forceinline__ void pv_one(f32x16& od, int vb, bf16x8 pa0, bf16x8 pa1, bf16x8 pa2, bf16x8 pa3) {
;   const s16x4 l0 = tr_read<v_rd_off(D0, 0, 0)>(vb), h0 = tr_read<v_rd_off(D0, 0, 1)>(vb), l1 = tr_read<v_rd_off(D0, 1, 0)>(vb), h1 = tr_read<v_rd_off(D0, 1, 1)>(vb);
;   const s16x4 l2 = tr_read<v_rd_off(D0, 2, 0)>(vb), h2 = tr_read<v_rd_off(D0, 2, 1)>(vb), l3 = tr_read<v_rd_off(D0, 3, 0)>(vb), h3 = tr_read<v_rd_off(D0, 3, 1)>(vb);
;   asm volatile("s_waitcnt lgkmcnt(0)" ::: "memory"); SBAR();
;     ...
;   od = __builtin_amdgcn_mfma_f32_32x32x16_bf16(pa0, PK(l0, h0), od, 0, 0, 0);
	ds_read_b128 v[200:203], v172 offset:49152
	ds_read_b128 v[204:207], v172 offset:57344
	ds_read_b128 v[208:211], v173 offset:49152
	ds_read_b128 v[212:215], v173 offset:57344
	ds_read_b128 v[230:233], v174 offset:49152
	ds_read_b128 v[234:237], v174 offset:57344
	ds_read_b128 v[238:241], v175 offset:49152
	ds_read_b128 v[242:245], v175 offset:57344
	s_waitcnt lgkmcnt(7)
	v_mfma_f32_32x32x16_bf16 v[128:143], v[200:203], v[124:127], 0
	ds_read_b128 v[200:203], v172 offset:49280
	v_cvt_pk_bf16_f32 v184, v64, v65
	v_add_f32_e32 v169, v169, v64
	v_add_f32_e32 v219, v219, v65
	s_waitcnt lgkmcnt(7)
	v_mfma_f32_32x32x16_bf16 v[144:159], v[204:207], v[124:127], 0
	ds_read_b128 v[204:207], v172 offset:57472
	v_cvt_pk_bf16_f32 v185, v66, v67
	v_add_f32_e32 v222, v222, v66
	v_add_f32_e32 v254, v254, v67
	s_waitcnt lgkmcnt(7)
	v_mfma_f32_32x32x16_bf16 v[128:143], v[208:211], v[120:123], v[128:143]
	ds_read_b128 v[208:211], v173 offset:49280
	v_cvt_pk_bf16_f32 v186, v68, v69
	v_add_f32_e32 v169, v169, v68
	v_add_f32_e32 v219, v219, v69
	s_waitcnt lgkmcnt(7)
	v_mfma_f32_32x32x16_bf16 v[144:159], v[212:215], v[120:123], v[144:159]
	ds_read_b128 v[212:215], v173 offset:57472
	v_cvt_pk_bf16_f32 v187, v70, v71
	v_add_f32_e32 v222, v222, v70
	v_add_f32_e32 v254, v254, v71
	s_waitcnt lgkmcnt(7)
	v_mfma_f32_32x32x16_bf16 v[128:143], v[230:233], v[116:119], v[128:143]
	ds_read_b128 v[230:233], v174 offset:49280
	v_cvt_pk_bf16_f32 v188, v72, v73
	v_add_f32_e32 v169, v169, v72
	v_add_f32_e32 v219, v219, v73
	v_permlane32_swap_b32_e32 v184, v186
	s_waitcnt lgkmcnt(7)
	v_mfma_f32_32x32x16_bf16 v[144:159], v[234:237], v[116:119], v[144:159]
	ds_read_b128 v[234:237], v174 offset:57472
	v_cvt_pk_bf16_f32 v189, v74, v75
	v_add_f32_e32 v222, v222, v74
	v_add_f32_e32 v254, v254, v75
	v_permlane32_swap_b32_e32 v185, v187
	s_waitcnt lgkmcnt(7)
	v_mfma_f32_32x32x16_bf16 v[128:143], v[238:241], v[112:115], v[128:143]
	ds_read_b128 v[238:241], v175 offset:49280
	v_cvt_pk_bf16_f32 v190, v76, v77
	v_add_f32_e32 v169, v169, v76
	v_add_f32_e32 v219, v219, v77
	s_waitcnt lgkmcnt(7)
	v_mfma_f32_32x32x16_bf16 v[144:159], v[242:245], v[112:115], v[144:159]
	ds_read_b128 v[242:245], v175 offset:57472
	v_cvt_pk_bf16_f32 v191, v78, v79
	v_add_f32_e32 v222, v222, v78
	v_add_f32_e32 v254, v254, v79
	s_waitcnt lgkmcnt(7)
	v_mfma_f32_32x32x16_bf16 v[128:143], v[200:203], v[108:111], v[128:143]
	v_cvt_pk_bf16_f32 v192, v80, v81
	v_add_f32_e32 v169, v169, v80
	v_add_f32_e32 v219, v219, v81
	v_permlane32_swap_b32_e32 v188, v190
	s_waitcnt lgkmcnt(6)
	v_mfma_f32_32x32x16_bf16 v[144:159], v[204:207], v[108:111], v[144:159]
	v_cvt_pk_bf16_f32 v193, v82, v83
	v_add_f32_e32 v222, v222, v82
	v_add_f32_e32 v254, v254, v83
	v_permlane32_swap_b32_e32 v189, v191
	s_waitcnt lgkmcnt(5)
	v_mfma_f32_32x32x16_bf16 v[128:143], v[208:211], v[104:107], v[128:143]
	ds_read_b64_tr_b16 v[200:201], v182 offset:32768
	ds_read_b64_tr_b16 v[202:203], v182 offset:34816
	v_cvt_pk_bf16_f32 v194, v84, v85
	v_add_f32_e32 v169, v169, v84
	v_add_f32_e32 v219, v219, v85
	s_waitcnt lgkmcnt(6)
	v_mfma_f32_32x32x16_bf16 v[144:159], v[212:215], v[104:107], v[144:159]
	ds_read_b64_tr_b16 v[204:205], v182 offset:36864
	ds_read_b64_tr_b16 v[206:207], v182 offset:38912
	v_cvt_pk_bf16_f32 v195, v86, v87
	v_add_f32_e32 v222, v222, v86
	v_add_f32_e32 v254, v254, v87
	s_waitcnt lgkmcnt(7)
	v_mfma_f32_32x32x16_bf16 v[128:143], v[230:233], v[100:103], v[128:143]
	ds_read_b64_tr_b16 v[208:209], v182 offset:40960
	ds_read_b64_tr_b16 v[210:211], v182 offset:43008
	v_cvt_pk_bf16_f32 v196, v88, v89
	v_add_f32_e32 v169, v169, v88
	v_add_f32_e32 v219, v219, v89
	v_permlane32_swap_b32_e32 v192, v194
	s_waitcnt lgkmcnt(8)
	v_mfma_f32_32x32x16_bf16 v[144:159], v[234:237], v[100:103], v[144:159]
	ds_read_b64_tr_b16 v[212:213], v182 offset:45056
	ds_read_b64_tr_b16 v[214:215], v182 offset:47104
	v_cvt_pk_bf16_f32 v197, v90, v91
	v_add_f32_e32 v222, v222, v90
	v_add_f32_e32 v254, v254, v91
	v_permlane32_swap_b32_e32 v193, v195
	s_waitcnt lgkmcnt(9)
	v_mfma_f32_32x32x16_bf16 v[128:143], v[238:241], v[96:99], v[128:143]
	ds_read_b64_tr_b16 v[230:231], v182 offset:33280
	ds_read_b64_tr_b16 v[232:233], v182 offset:35328
	v_cvt_pk_bf16_f32 v198, v92, v93
	v_add_f32_e32 v169, v169, v92
	v_add_f32_e32 v219, v219, v93
	s_waitcnt lgkmcnt(10)
	v_mfma_f32_32x32x16_bf16 v[144:159], v[242:245], v[96:99], v[144:159]
	ds_read_b64_tr_b16 v[234:235], v182 offset:37376
	ds_read_b64_tr_b16 v[236:237], v182 offset:39424
	v_cvt_pk_bf16_f32 v199, v94, v95
	v_add_f32_e32 v222, v222, v94
	v_add_f32_e32 v254, v254, v95
	v_permlane32_swap_b32_e32 v196, v198
	v_permlane32_swap_b32_e32 v197, v199
	s_waitcnt lgkmcnt(10)
	v_mfma_f32_32x32x16_bf16 v[0:15], v[184:187], v[200:203], v[0:15]
	ds_read_b64_tr_b16 v[238:239], v182 offset:41472
	ds_read_b64_tr_b16 v[240:241], v182 offset:43520
	v_exp_f32_e32 v128, v128
	v_exp_f32_e32 v129, v129
	s_waitcnt lgkmcnt(10)
	v_mfma_f32_32x32x16_bf16 v[0:15], v[188:191], v[204:207], v[0:15]
	ds_read_b64_tr_b16 v[242:243], v182 offset:45568
	ds_read_b64_tr_b16 v[244:245], v182 offset:47616
	v_exp_f32_e32 v130, v130
	v_exp_f32_e32 v131, v131
	s_waitcnt lgkmcnt(10)
	v_mfma_f32_32x32x16_bf16 v[0:15], v[192:195], v[208:211], v[0:15]
	ds_read_b64_tr_b16 v[200:201], v182 offset:33792
	ds_read_b64_tr_b16 v[202:203], v182 offset:35840
	v_exp_f32_e32 v132, v132
	v_exp_f32_e32 v133, v133
	s_waitcnt lgkmcnt(10)
	v_mfma_f32_32x32x16_bf16 v[0:15], v[196:199], v[212:215], v[0:15]
	ds_read_b64_tr_b16 v[204:205], v182 offset:37888
	ds_read_b64_tr_b16 v[206:207], v182 offset:39936
	v_exp_f32_e32 v134, v134
	v_exp_f32_e32 v135, v135
	s_waitcnt lgkmcnt(10)
; __device__ __forceinline__ void finishSM(f32x16& p0, f32x16& p1, float alpha, float& l_reg, bf16x8& pa0, bf16x8& pa1, bf16x8& pa2, bf16x8& pa3) {
; #pragma unroll
;   for (int r = 0; r < 16; ++r) p1[r] = __builtin_amdgcn_exp2f(p1[r]);
;   float ps = 0;
; #pragma unroll
;   for (int r = 0; r < 16; ++r) ps += p0[r];
; #pragma unroll
;   for (int r = 0; r < 16; ++r) ps += p1[r];
;   { auto rr = __builtin_amdgcn_permlane32_swap(__float_as_uint(ps), __float_as_uint(ps), false, false);
;     ps = __uint_as_float(rr[0]) + __uint_as_float(rr[1]); }
;   l_reg = l_reg * alpha + ps;
;     ...
;   PK4(p0, 0, pa0); PK4(p0, 8, pa1); PK4(p1, 0, pa2); PK4(p1, 8, pa3);
;     ...
; }
; __device__ __forceinline__ void qkt(f32x16& p0, f32x16& p1, const bf16* Ks, const bf16x8* qr, int r32, int hi) {
;   p0 = f32x16{}; p1 = f32x16{};
; #pragma unroll
;   for (int d0 = 0; d0 < 8; ++d0) { int cb = (d0 * 16 + hi * 8) * 2;
;     bf16x8 b0 = *reinterpret_cast<const bf16x8*>((const char*)Ks + KSWZ(r32, cb));
;     bf16x8 b1 = *reinterpret_cast<const bf16x8*>((const char*)Ks + KSWZ(32 + r32, cb));
;     p0 = __builtin_amdgcn_mfma_f32_32x32x16_bf16(b0, qr[d0], p0, 0, 0, 0);
;     p1 = __builtin_amdgcn_mfma_f32_32x32x16_bf16(b1, qr[d0], p1, 0, 0, 0); }
; }
; __device__ __forceinline__ int v_st(int k, int c) { const int kk = (k & ~0xC) | ((k & 4) << 1) | ((k & 8) >> 1); return ((kk >> 3) * 4 + (c >> 5)) * 512 + ((kk & 7) * 32 + (c & 31)) * 2; }
; __device__ __forceinline__ int v_rd_base(int lane) { return ((lane & 3) << 3) | (((lane >> 2) & 3) << 6) | (((lane >> 4) & 1) << 5) | (((lane >> 5) & 1) << 8); }
; template <int OFF> __device__ __forceinline__ s16x4 tr_read(int vb) {
;   s16x4 r; asm volatile("ds_read_b64_tr_b16 %0, %1 offset:%2" : "=&v"(r) : "v"(vb), "i"(OFF) : "memory"); return r;
; }
; template <int D0> __device__ __forceinline__ void pv_one(f32x16& od, int vb, bf16x8 pa0, bf16x8 pa1, bf16x8 pa2, bf16x8 pa3) {
;   const s16x4 l0 = tr_read<v_rd_off(D0, 0, 0)>(vb), h0 = tr_read<v_rd_off(D0, 0, 1)>(vb), l1 = tr_read<v_rd_off(D0, 1, 0)>(vb), h1 = tr_read<v_rd_off(D0, 1, 1)>(vb);
;   const s16x4 l2 = tr_read<v_rd_off(D0, 2, 0)>(vb), h2 = tr_read<v_rd_off(D0, 2, 1)>(vb), l3 = tr_read<v_rd_off(D0, 3, 0)>(vb), h3 = tr_read<v_rd_off(D0, 3, 1)>(vb);
;   asm volatile("s_waitcnt lgkmcnt(0)" ::: "memory"); SBAR();
;     ...
;   od = __builtin_amdgcn_mfma_f32_32x32x16_bf16(pa0, PK(l0, h0), od, 0, 0, 0);
	v_mfma_f32_32x32x16_bf16 v[48:63], v[184:187], v[230:233], v[48:63]
	ds_read_b64_tr_b16 v[208:209], v182 offset:41984
	ds_read_b64_tr_b16 v[210:211], v182 offset:44032
	v_exp_f32_e32 v136, v136
	v_exp_f32_e32 v137, v137
	s_waitcnt lgkmcnt(10)
	v_mfma_f32_32x32x16_bf16 v[48:63], v[188:191], v[234:237], v[48:63]
	ds_read_b64_tr_b16 v[212:213], v182 offset:46080
	ds_read_b64_tr_b16 v[214:215], v182 offset:48128
	v_exp_f32_e32 v138, v138
	v_exp_f32_e32 v139, v139
	s_waitcnt lgkmcnt(10)
	v_mfma_f32_32x32x16_bf16 v[48:63], v[192:195], v[238:241], v[48:63]
	ds_read_b64_tr_b16 v[230:231], v182 offset:34304
	ds_read_b64_tr_b16 v[232:233], v182 offset:36352
	v_exp_f32_e32 v140, v140
	v_exp_f32_e32 v141, v141
	s_waitcnt lgkmcnt(10)
	v_mfma_f32_32x32x16_bf16 v[48:63], v[196:199], v[242:245], v[48:63]
	ds_read_b64_tr_b16 v[234:235], v182 offset:38400
	ds_read_b64_tr_b16 v[236:237], v182 offset:40448
	v_exp_f32_e32 v142, v142
	v_exp_f32_e32 v143, v143
	s_waitcnt lgkmcnt(10)
	v_mfma_f32_32x32x16_bf16 v[32:47], v[184:187], v[200:203], v[32:47]
	ds_read_b64_tr_b16 v[238:239], v182 offset:42496
	ds_read_b64_tr_b16 v[240:241], v182 offset:44544
	v_exp_f32_e32 v144, v144
	v_exp_f32_e32 v145, v145
	s_waitcnt lgkmcnt(10)
	v_mfma_f32_32x32x16_bf16 v[32:47], v[188:191], v[204:207], v[32:47]
	ds_read_b64_tr_b16 v[242:243], v182 offset:46592
	ds_read_b64_tr_b16 v[244:245], v182 offset:48640
	v_exp_f32_e32 v146, v146
	v_exp_f32_e32 v147, v147
	s_waitcnt lgkmcnt(10)
	v_mfma_f32_32x32x16_bf16 v[32:47], v[192:195], v[208:211], v[32:47]
	v_exp_f32_e32 v148, v148
	v_exp_f32_e32 v149, v149
	s_waitcnt lgkmcnt(8)
	v_mfma_f32_32x32x16_bf16 v[32:47], v[196:199], v[212:215], v[32:47]
	v_exp_f32_e32 v150, v150
	v_exp_f32_e32 v151, v151
	s_waitcnt lgkmcnt(6)
	v_mfma_f32_32x32x16_bf16 v[16:31], v[184:187], v[230:233], v[16:31]
	v_exp_f32_e32 v152, v152
	v_exp_f32_e32 v153, v153
	s_waitcnt lgkmcnt(4)
	v_mfma_f32_32x32x16_bf16 v[16:31], v[188:191], v[234:237], v[16:31]
	v_exp_f32_e32 v154, v154
	v_exp_f32_e32 v155, v155
	s_waitcnt lgkmcnt(2)
	v_mfma_f32_32x32x16_bf16 v[16:31], v[192:195], v[238:241], v[16:31]
	v_exp_f32_e32 v156, v156
	v_exp_f32_e32 v157, v157
	s_waitcnt lgkmcnt(0)
	v_mfma_f32_32x32x16_bf16 v[16:31], v[196:199], v[242:245], v[16:31]
	v_exp_f32_e32 v158, v158
	v_exp_f32_e32 v159, v159
	s_waitcnt lgkmcnt(0)
	s_barrier
; #define SBAR() __builtin_amdgcn_sched_barrier(0)
; #define RESC(a) do { if (__any((a) < 1.f)) { if (hi == 0) al_l[r32] = (a); asm volatile("s_waitcnt lgkmcnt(0)" ::: "memory"); \
;     _Pragma("unroll") for (int d = 0; d < 4; ++d) _Pragma("unroll") for (int r = 0; r < 16; ++r) o[d][r] *= al_l[crow(r, hi)]; } } while (0)
;     ...
;   { SBAR(); qkt(pB0, pB1, KSUB(1, 1), qr, r32, hi);
;     finishSM(pA0, pA1, alA, l_reg, pa0, pa1, pa2, pa3); SBAR();
;     pv_d0(o, VSUB(1, 0), pa0, pa1, pa2, pa3); partialSM(pB0, pB1, m_reg, mnB, alB);
;     RESC(alB);
;     finishSM(pB0, pB1, alB, l_reg, pa0, pa1, pa2, pa3); SBAR();
;     pv_d0(o, VSUB(1, 1), pa0, pa1, pa2, pa3); }
;     ...
;   }
;   if (hi == 0) li_l[r32] = l_reg; asm volatile("s_waitcnt lgkmcnt(0)" ::: "memory");
	v_cvt_pk_bf16_f32 v184, v128, v129
	v_add_f32_e32 v169, v169, v128
	v_add_f32_e32 v219, v219, v129
	v_cvt_pk_bf16_f32 v185, v130, v131
	v_add_f32_e32 v222, v222, v130
	v_add_f32_e32 v254, v254, v131
	v_cvt_pk_bf16_f32 v186, v132, v133
	v_add_f32_e32 v169, v169, v132
	v_add_f32_e32 v219, v219, v133
	v_cvt_pk_bf16_f32 v187, v134, v135
	v_add_f32_e32 v222, v222, v134
	v_add_f32_e32 v254, v254, v135
	v_cvt_pk_bf16_f32 v188, v136, v137
	v_add_f32_e32 v169, v169, v136
	v_add_f32_e32 v219, v219, v137
	v_permlane32_swap_b32_e32 v184, v186
	v_cvt_pk_bf16_f32 v189, v138, v139
	v_add_f32_e32 v222, v222, v138
	v_add_f32_e32 v254, v254, v139
	v_permlane32_swap_b32_e32 v185, v187
	v_cvt_pk_bf16_f32 v190, v140, v141
	v_add_f32_e32 v169, v169, v140
	v_add_f32_e32 v219, v219, v141
	v_cvt_pk_bf16_f32 v191, v142, v143
	v_add_f32_e32 v222, v222, v142
	v_add_f32_e32 v254, v254, v143
	v_cvt_pk_bf16_f32 v192, v144, v145
	v_add_f32_e32 v169, v169, v144
	v_add_f32_e32 v219, v219, v145
	v_permlane32_swap_b32_e32 v188, v190
	v_cvt_pk_bf16_f32 v193, v146, v147
	v_add_f32_e32 v222, v222, v146
	v_add_f32_e32 v254, v254, v147
	v_permlane32_swap_b32_e32 v189, v191
	ds_read_b64_tr_b16 v[200:201], v182 offset:49152
	ds_read_b64_tr_b16 v[202:203], v182 offset:51200
	v_cvt_pk_bf16_f32 v194, v148, v149
	v_add_f32_e32 v169, v169, v148
	v_add_f32_e32 v219, v219, v149
	ds_read_b64_tr_b16 v[204:205], v182 offset:53248
	ds_read_b64_tr_b16 v[206:207], v182 offset:55296
	v_cvt_pk_bf16_f32 v195, v150, v151
	v_add_f32_e32 v222, v222, v150
	v_add_f32_e32 v254, v254, v151
	ds_read_b64_tr_b16 v[208:209], v182 offset:57344
	ds_read_b64_tr_b16 v[210:211], v182 offset:59392
	v_cvt_pk_bf16_f32 v196, v152, v153
	v_add_f32_e32 v169, v169, v152
	v_add_f32_e32 v219, v219, v153
	v_permlane32_swap_b32_e32 v192, v194
	ds_read_b64_tr_b16 v[212:213], v182 offset:61440
	ds_read_b64_tr_b16 v[214:215], v182 offset:63488
	v_cvt_pk_bf16_f32 v197, v154, v155
	v_add_f32_e32 v222, v222, v154
	v_add_f32_e32 v254, v254, v155
	v_permlane32_swap_b32_e32 v193, v195
	ds_read_b64_tr_b16 v[230:231], v182 offset:49664
	ds_read_b64_tr_b16 v[232:233], v182 offset:51712
	v_cvt_pk_bf16_f32 v198, v156, v157
	v_add_f32_e32 v169, v169, v156
	v_add_f32_e32 v219, v219, v157
	ds_read_b64_tr_b16 v[234:235], v182 offset:53760
	ds_read_b64_tr_b16 v[236:237], v182 offset:55808
	v_cvt_pk_bf16_f32 v199, v158, v159
	v_add_f32_e32 v222, v222, v158
	v_add_f32_e32 v254, v254, v159
	v_permlane32_swap_b32_e32 v196, v198
	v_permlane32_swap_b32_e32 v197, v199
	s_waitcnt lgkmcnt(10)
	v_mfma_f32_32x32x16_bf16 v[0:15], v[184:187], v[200:203], v[0:15]
	ds_read_b64_tr_b16 v[238:239], v182 offset:57856
	ds_read_b64_tr_b16 v[240:241], v182 offset:59904
	s_waitcnt lgkmcnt(10)
	v_mfma_f32_32x32x16_bf16 v[0:15], v[188:191], v[204:207], v[0:15]
	ds_read_b64_tr_b16 v[242:243], v182 offset:61952
	ds_read_b64_tr_b16 v[244:245], v182 offset:64000
	s_waitcnt lgkmcnt(10)
	v_mfma_f32_32x32x16_bf16 v[0:15], v[192:195], v[208:211], v[0:15]
	ds_read_b64_tr_b16 v[200:201], v182 offset:50176
	ds_read_b64_tr_b16 v[202:203], v182 offset:52224
	s_waitcnt lgkmcnt(10)
	v_mfma_f32_32x32x16_bf16 v[0:15], v[196:199], v[212:215], v[0:15]
	ds_read_b64_tr_b16 v[204:205], v182 offset:54272
	ds_read_b64_tr_b16 v[206:207], v182 offset:56320
	s_waitcnt lgkmcnt(10)
	v_mfma_f32_32x32x16_bf16 v[48:63], v[184:187], v[230:233], v[48:63]
	ds_read_b64_tr_b16 v[208:209], v182 offset:58368
	ds_read_b64_tr_b16 v[210:211], v182 offset:60416
	s_waitcnt lgkmcnt(10)
	v_mfma_f32_32x32x16_bf16 v[48:63], v[188:191], v[234:237], v[48:63]
	ds_read_b64_tr_b16 v[212:213], v182 offset:62464
	ds_read_b64_tr_b16 v[214:215], v182 offset:64512
	s_waitcnt lgkmcnt(10)
	v_mfma_f32_32x32x16_bf16 v[48:63], v[192:195], v[238:241], v[48:63]
	ds_read_b64_tr_b16 v[230:231], v182 offset:50688
	ds_read_b64_tr_b16 v[232:233], v182 offset:52736
	s_waitcnt lgkmcnt(10)
	v_mfma_f32_32x32x16_bf16 v[48:63], v[196:199], v[242:245], v[48:63]
	ds_read_b64_tr_b16 v[234:235], v182 offset:54784
	ds_read_b64_tr_b16 v[236:237], v182 offset:56832
	s_waitcnt lgkmcnt(10)
	v_mfma_f32_32x32x16_bf16 v[32:47], v[184:187], v[200:203], v[32:47]
	ds_read_b64_tr_b16 v[238:239], v182 offset:58880
	ds_read_b64_tr_b16 v[240:241], v182 offset:60928
	s_waitcnt lgkmcnt(10)
	v_mfma_f32_32x32x16_bf16 v[32:47], v[188:191], v[204:207], v[32:47]
	ds_read_b64_tr_b16 v[242:243], v182 offset:62976
	ds_read_b64_tr_b16 v[244:245], v182 offset:65024
	s_waitcnt lgkmcnt(10)
	v_mfma_f32_32x32x16_bf16 v[32:47], v[192:195], v[208:211], v[32:47]
	s_waitcnt lgkmcnt(8)
	v_mfma_f32_32x32x16_bf16 v[32:47], v[196:199], v[212:215], v[32:47]
	s_waitcnt lgkmcnt(6)
	v_mfma_f32_32x32x16_bf16 v[16:31], v[184:187], v[230:233], v[16:31]
	s_waitcnt lgkmcnt(4)
	v_mfma_f32_32x32x16_bf16 v[16:31], v[188:191], v[234:237], v[16:31]
	s_waitcnt lgkmcnt(2)
	v_mfma_f32_32x32x16_bf16 v[16:31], v[192:195], v[238:241], v[16:31]
	s_waitcnt lgkmcnt(0)
	v_mfma_f32_32x32x16_bf16 v[16:31], v[196:199], v[242:245], v[16:31]
	s_waitcnt lgkmcnt(0)
	s_barrier
	v_add_f32_e32 v169, v169, v219
	v_add_f32_e32 v222, v222, v254
	v_add_f32_e32 v169, v169, v222
	v_mov_b32_e32 v219, v169
	s_nop 1
	v_permlane32_swap_b32_e32 v169, v219
	v_add_f32_e32 v64, v169, v219
	s_and_saveexec_b64 s[0:1], s[2:3]
	ds_write_b32 v168, v64
	s_branch .LBB0_477

;     ...
;   if (hi == 0) li_l[r32] = l_reg; asm volatile("s_waitcnt lgkmcnt(0)" ::: "memory");
;   if constexpr (MODE == 1) { if (hi == 0) lse_out[(long)(wid * QBLK + r32) * lse_stride] = m_reg * SCALE + __logf(l_reg); }
.LBB0_534:
	s_and_saveexec_b64 s[4:5], s[2:3]
	ds_write_b32 v203, v216
	s_or_b64 exec, exec, s[4:5]
	s_waitcnt lgkmcnt(0)
	s_and_saveexec_b64 s[4:5], s[2:3]
	s_cbranch_execz .LBB0_504
	s_ashr_i32 s1, s0, 31
	s_lshl_b64 s[0:1], s[0:1], 15
	s_or_b32 s0, s0, s45
	s_and_b64 s[2:3], s[20:21], exec
	s_cselect_b32 s28, 2, 4
	s_and_b64 s[2:3], s[38:39], exec
	s_mov_b32 s45, s15
	s_cselect_b32 s2, 0, s28
	s_lshl_b64 s[2:3], s[44:45], s2
	s_add_u32 s0, s0, s2
	s_mov_b32 s2, 0x800000
	v_cmp_gt_f32_e32 vcc, s2, v216
	s_addc_u32 s1, s1, s3
	s_lshl_b64 s[0:1], s[0:1], 5
	v_cndmask_b32_e64 v64, 0, 32, vcc
	v_ldexp_f32 v64, v216, v64
	v_log_f32_e32 v64, v64
	s_add_u32 s0, s66, s0
	s_addc_u32 s1, s67, s1
	s_lshl_b32 s2, s56, 2
	s_add_u32 s2, s0, s2
	v_mul_f32_e32 v65, 0x3f317217, v64
	s_mov_b32 s0, 0x3f317217
	v_fma_f32 v65, v64, s0, -v65
	v_fmac_f32_e32 v65, 0x3377d1cf, v64
	s_mov_b32 s0, 0x7f800000
	s_addc_u32 s3, s1, 0
	v_fmac_f32_e32 v65, 0x3f317217, v64
	v_cmp_lt_f32_e64 s[0:1], |v64|, s0
	s_nop 1
	v_cndmask_b32_e64 v64, v64, v65, s[0:1]
	s_and_b64 s[0:1], s[20:21], exec
	s_cselect_b32 s20, 5, 7
	s_and_b64 s[0:1], s[38:39], exec
	v_cndmask_b32_e32 v65, 0, v224, vcc
	s_cselect_b32 s0, 3, s20
	v_sub_f32_e32 v66, v64, v65
	v_lshlrev_b64 v[64:65], s0, v[160:161]
	v_fmac_f32_e32 v66, 0x3db504f3, v201
	v_lshl_add_u64 v[64:65], v[64:65], 2, s[2:3]
	global_store_dword v[64:65], v66, off
	s_branch .LBB0_504
.LBB0_552:
	v_readlane_b32 s92, v255, 0
	v_readlane_b32 s93, v255, 1
